# V pass residual loads and final stores marked nt (streamed once, kept out of the L2 the gather sweep lives in)
# speedup vs baseline: 1.0033x; 1.0033x over previous
; DI void peer_item_v(const Params& p, int item) {
;     ...
; #pragma unroll 1
;   for (int ti = 0; ti < 8; ++ti) {
;     const size_t tok = (size_t)item * 32 + wave * 8 + ti;
;     const int e_lo = EG[tok * 128 + lane], e_hi = EG[tok * 128 + 64 + lane];
;     const int a_lo = __float_as_int(AG[tok * 128 + lane]), a_hi = __float_as_int(AG[tok * 128 + 64 + lane]);
;     float out[16];
; #pragma unroll
;     for (int i = 0; i < 16; ++i) out[i] = 0.f;
;     u32x4 vqa[8], vqb[8];
;     ...
;     V_ISSUE(vqa, 0)
; #pragma unroll 1
;     for (int g = 0; g < 16; g += 2) {
;       V_ISSUE(vqb, g + 1)
;       V_CONSUME(vqa, g)
;       if (g + 2 < 16) V_ISSUE(vqa, g + 2)
;       V_CONSUME(vqb, g + 1)
;     }
;     ...
;     float* orow = p.out + tok * 1024 + lane * 4;
;     float4 y[4];
;     float ss = 0.f;
; #pragma unroll
;     for (int i = 0; i < 4; ++i) {
;       y[i] = *(const float4*)(orow + 256 * i);
.Lvq_item:
	s_lshl_b32 s14, s10, 5
	s_add_u32 s14, s14, s56
	s_lshl_b32 s13, s14, 9
	s_add_u32 s58, s2, s13
	s_addc_u32 s59, s3, 0
	s_add_u32 s60, s4, s13
	s_addc_u32 s61, s5, 0
	v_lshrrev_b32_e32 v250, 3, v249
	v_and_b32_e32 v251, 7, v249
	v_lshlrev_b32_e32 v250, 6, v250
	v_lshl_add_u32 v250, v251, 2, v250
	global_load_dword v128, v250, s[58:59] offset:0
	global_load_dword v129, v250, s[58:59] offset:32
	global_load_dword v130, v250, s[60:61] offset:0
	global_load_dword v131, v250, s[60:61] offset:32
	global_load_dword v132, v250, s[58:59] offset:512
	global_load_dword v133, v250, s[58:59] offset:544
	global_load_dword v134, v250, s[60:61] offset:512
	global_load_dword v135, v250, s[60:61] offset:544
	global_load_dword v136, v250, s[58:59] offset:1024
	global_load_dword v137, v250, s[58:59] offset:1056
	global_load_dword v138, v250, s[60:61] offset:1024
	global_load_dword v139, v250, s[60:61] offset:1056
	global_load_dword v140, v250, s[58:59] offset:1536
	global_load_dword v141, v250, s[58:59] offset:1568
	global_load_dword v142, v250, s[60:61] offset:1536
	global_load_dword v143, v250, s[60:61] offset:1568
	global_load_dword v144, v250, s[58:59] offset:2048
	global_load_dword v145, v250, s[58:59] offset:2080
	global_load_dword v146, v250, s[60:61] offset:2048
	global_load_dword v147, v250, s[60:61] offset:2080
	global_load_dword v148, v250, s[58:59] offset:2560
	global_load_dword v149, v250, s[58:59] offset:2592
	global_load_dword v150, v250, s[60:61] offset:2560
	global_load_dword v151, v250, s[60:61] offset:2592
	global_load_dword v152, v250, s[58:59] offset:3072
	global_load_dword v153, v250, s[58:59] offset:3104
	global_load_dword v154, v250, s[60:61] offset:3072
	global_load_dword v155, v250, s[60:61] offset:3104
	global_load_dword v156, v250, s[58:59] offset:3584
	global_load_dword v157, v250, s[58:59] offset:3616
	global_load_dword v158, v250, s[60:61] offset:3584
	global_load_dword v159, v250, s[60:61] offset:3616
	v_add_u32_e32 v160, s57, v241
	v_mov_b32_e32 v161, 0
	v_mov_b32_e32 v162, 1
	v_lshrrev_b32_e32 v163, 3, v249
	v_and_b32_e32 v164, 7, v249
	v_lshlrev_b32_e32 v163, 6, v163
	v_lshl_add_u32 v163, v164, 2, v163
	v_add_u32_e32 v163, s57, v163
	v_add_u32_e32 v164, 32, v163
	v_subrev_u32_e32 v165, 1, v249
	v_subrev_u32_e32 v166, 2, v249
	v_subrev_u32_e32 v167, 4, v249
	v_subrev_u32_e32 v168, 8, v249
	v_subrev_u32_e32 v169, 16, v249
	v_subrev_u32_e32 v170, 32, v249
	v_lshlrev_b32_e32 v165, 2, v165
	v_lshlrev_b32_e32 v166, 2, v166
	v_lshlrev_b32_e32 v167, 2, v167
	v_lshlrev_b32_e32 v168, 2, v168
	v_lshlrev_b32_e32 v169, 2, v169
	v_lshlrev_b32_e32 v170, 2, v170
	v_mov_b32_e32 v0, 0
	v_mov_b32_e32 v1, 0
	v_mov_b32_e32 v2, 0
	v_mov_b32_e32 v3, 0
	v_mov_b32_e32 v4, 0
	v_mov_b32_e32 v5, 0
	v_mov_b32_e32 v6, 0
	v_mov_b32_e32 v7, 0
	v_mov_b32_e32 v8, 0
	v_mov_b32_e32 v9, 0
	v_mov_b32_e32 v10, 0
	v_mov_b32_e32 v11, 0
	v_mov_b32_e32 v12, 0
	v_mov_b32_e32 v13, 0
	v_mov_b32_e32 v14, 0
	v_mov_b32_e32 v15, 0
	v_mov_b32_e32 v16, 0
	v_mov_b32_e32 v17, 0
	v_mov_b32_e32 v18, 0
	v_mov_b32_e32 v19, 0
	v_mov_b32_e32 v20, 0
	v_mov_b32_e32 v21, 0
	v_mov_b32_e32 v22, 0
	v_mov_b32_e32 v23, 0
	v_mov_b32_e32 v24, 0
	v_mov_b32_e32 v25, 0
	v_mov_b32_e32 v26, 0
	v_mov_b32_e32 v27, 0
	v_mov_b32_e32 v28, 0
	v_mov_b32_e32 v29, 0
	v_mov_b32_e32 v30, 0
	v_mov_b32_e32 v31, 0
	v_mov_b32_e32 v32, 0
	v_mov_b32_e32 v33, 0
	v_mov_b32_e32 v34, 0
	v_mov_b32_e32 v35, 0
	v_mov_b32_e32 v36, 0
	v_mov_b32_e32 v37, 0
	v_mov_b32_e32 v38, 0
	v_mov_b32_e32 v39, 0
	v_mov_b32_e32 v40, 0
	v_mov_b32_e32 v41, 0
	v_mov_b32_e32 v42, 0
	v_mov_b32_e32 v43, 0
	v_mov_b32_e32 v44, 0
	v_mov_b32_e32 v45, 0
	v_mov_b32_e32 v46, 0
	v_mov_b32_e32 v47, 0
	v_mov_b32_e32 v48, 0
	v_mov_b32_e32 v49, 0
	v_mov_b32_e32 v50, 0
	v_mov_b32_e32 v51, 0
	v_mov_b32_e32 v52, 0
	v_mov_b32_e32 v53, 0
	v_mov_b32_e32 v54, 0
	v_mov_b32_e32 v55, 0
	v_mov_b32_e32 v56, 0
	v_mov_b32_e32 v57, 0
	v_mov_b32_e32 v58, 0
	v_mov_b32_e32 v59, 0
	v_mov_b32_e32 v60, 0
	v_mov_b32_e32 v61, 0
	v_mov_b32_e32 v62, 0
	v_mov_b32_e32 v63, 0
	s_waitcnt vmcnt(0)
	v_lshlrev_b32_e32 v128, 10, v128
	v_lshlrev_b32_e32 v129, 10, v129
	v_lshlrev_b32_e32 v132, 10, v132
	v_lshlrev_b32_e32 v133, 10, v133
	v_lshlrev_b32_e32 v136, 10, v136
	v_lshlrev_b32_e32 v137, 10, v137
	v_lshlrev_b32_e32 v140, 10, v140
	v_lshlrev_b32_e32 v141, 10, v141
	v_lshlrev_b32_e32 v144, 10, v144
	v_lshlrev_b32_e32 v145, 10, v145
	v_lshlrev_b32_e32 v148, 10, v148
	v_lshlrev_b32_e32 v149, 10, v149
	v_lshlrev_b32_e32 v152, 10, v152
	v_lshlrev_b32_e32 v153, 10, v153
	v_lshlrev_b32_e32 v156, 10, v156
	v_lshlrev_b32_e32 v157, 10, v157
	s_lshl_b32 s15, s14, 12
	s_add_u32 s62, s6, s15
	s_addc_u32 s63, s7, 0
	s_add_u32 s32, s62, 0
	s_addc_u32 s33, s63, 0
	s_add_u32 s34, s62, 4096
	s_addc_u32 s35, s63, 0
	s_add_u32 s36, s62, 8192
	s_addc_u32 s37, s63, 0
	s_add_u32 s38, s62, 12288
	s_addc_u32 s39, s63, 0
	global_load_dwordx4 v[64:67], v240, s[32:33] nt
	global_load_dwordx4 v[68:71], v240, s[32:33] offset:1024 nt
	global_load_dwordx4 v[72:75], v240, s[32:33] offset:2048 nt
	global_load_dwordx4 v[76:79], v240, s[32:33] offset:3072 nt
	global_load_dwordx4 v[80:83], v240, s[34:35] nt
	global_load_dwordx4 v[84:87], v240, s[34:35] offset:1024 nt
	global_load_dwordx4 v[88:91], v240, s[34:35] offset:2048 nt
	global_load_dwordx4 v[92:95], v240, s[34:35] offset:3072 nt
	global_load_dwordx4 v[96:99], v240, s[36:37] nt
	global_load_dwordx4 v[100:103], v240, s[36:37] offset:1024 nt
	global_load_dwordx4 v[104:107], v240, s[36:37] offset:2048 nt
	global_load_dwordx4 v[108:111], v240, s[36:37] offset:3072 nt
	global_load_dwordx4 v[112:115], v240, s[38:39] nt
	global_load_dwordx4 v[116:119], v240, s[38:39] offset:1024 nt
	global_load_dwordx4 v[120:123], v240, s[38:39] offset:2048 nt
	global_load_dwordx4 v[124:127], v240, s[38:39] offset:3072 nt
	s_mov_b32 s72, 0
	s_mov_b32 s73, 1
	s_mov_b32 s74, 2
	s_mov_b32 s75, 3
	s_mov_b32 s76, 4
	s_mov_b32 s77, 5
	s_mov_b32 s78, 6
	s_mov_b32 s79, 7
	s_nop 0
	v_readlane_b32 s48, v128, s72
	v_readlane_b32 s49, v128, s73
	v_readlane_b32 s50, v128, s74
	v_readlane_b32 s51, v128, s75
	v_readlane_b32 s52, v128, s76
	v_readlane_b32 s53, v128, s77
	v_readlane_b32 s54, v128, s78
	v_readlane_b32 s55, v128, s79
	s_add_u32 s32, s0, s48
	s_addc_u32 s33, s1, 0
	s_add_u32 s34, s0, s49
	s_addc_u32 s35, s1, 0
	s_add_u32 s36, s0, s50
	s_addc_u32 s37, s1, 0
	s_add_u32 s38, s0, s51
	s_addc_u32 s39, s1, 0
	s_add_u32 s40, s0, s52
	s_addc_u32 s41, s1, 0
	s_add_u32 s42, s0, s53
	s_addc_u32 s43, s1, 0
	s_add_u32 s44, s0, s54
	s_addc_u32 s45, s1, 0
	s_add_u32 s46, s0, s55
	s_addc_u32 s47, s1, 0
	global_load_dwordx4 v[160:163], v240, s[32:33]
	global_load_dwordx4 v[164:167], v240, s[34:35]
	global_load_dwordx4 v[168:171], v240, s[36:37]
	global_load_dwordx4 v[172:175], v240, s[38:39]
	global_load_dwordx4 v[176:179], v240, s[40:41]
	global_load_dwordx4 v[180:183], v240, s[42:43]
	global_load_dwordx4 v[184:187], v240, s[44:45]
	global_load_dwordx4 v[188:191], v240, s[46:47]
	s_mov_b32 s12, 0
.Lvq_kA:
	v_readlane_b32 s16, v130, s72
	v_readlane_b32 s18, v130, s73
	v_readlane_b32 s20, v130, s74
	v_readlane_b32 s22, v130, s75
	v_readlane_b32 s24, v130, s76
	v_readlane_b32 s26, v130, s77
	v_readlane_b32 s28, v130, s78
	v_readlane_b32 s30, v130, s79
	v_readlane_b32 s48, v132, s72
	v_readlane_b32 s49, v132, s73
	v_readlane_b32 s50, v132, s74
	v_readlane_b32 s51, v132, s75
	v_readlane_b32 s52, v132, s76
	v_readlane_b32 s53, v132, s77
	v_readlane_b32 s54, v132, s78
	v_readlane_b32 s55, v132, s79
	s_add_u32 s32, s0, s48
	s_addc_u32 s33, s1, 0
	s_add_u32 s34, s0, s49
	s_addc_u32 s35, s1, 0
	s_add_u32 s36, s0, s50
	s_addc_u32 s37, s1, 0
	s_add_u32 s38, s0, s51
	s_addc_u32 s39, s1, 0
	s_add_u32 s40, s0, s52
	s_addc_u32 s41, s1, 0
	s_add_u32 s42, s0, s53
	s_addc_u32 s43, s1, 0
	s_add_u32 s44, s0, s54
	s_addc_u32 s45, s1, 0
	s_add_u32 s46, s0, s55
	s_addc_u32 s47, s1, 0
	global_load_dwordx4 v[192:195], v240, s[32:33]
	global_load_dwordx4 v[196:199], v240, s[34:35]
	global_load_dwordx4 v[200:203], v240, s[36:37]
	global_load_dwordx4 v[204:207], v240, s[38:39]
	global_load_dwordx4 v[208:211], v240, s[40:41]
	global_load_dwordx4 v[212:215], v240, s[42:43]
	global_load_dwordx4 v[216:219], v240, s[44:45]
	global_load_dwordx4 v[220:223], v240, s[46:47]
	s_waitcnt vmcnt(8)
	v_cvt_pk_f32_fp8_e32 v[224:225], v160
	v_cvt_pk_f32_fp8_sdwa v[226:227], v160 src0_sel:WORD_1
	v_cvt_pk_f32_fp8_e32 v[228:229], v161
	v_cvt_pk_f32_fp8_sdwa v[230:231], v161 src0_sel:WORD_1
	v_cvt_pk_f32_fp8_e32 v[232:233], v162
	v_cvt_pk_f32_fp8_sdwa v[234:235], v162 src0_sel:WORD_1
	v_cvt_pk_f32_fp8_e32 v[236:237], v163
	v_cvt_pk_f32_fp8_sdwa v[238:239], v163 src0_sel:WORD_1
	v_pk_fma_f32 v[0:1], v[224:225], s[16:17], v[0:1] op_sel_hi:[1,0,1]
	v_pk_fma_f32 v[2:3], v[226:227], s[16:17], v[2:3] op_sel_hi:[1,0,1]
	v_pk_fma_f32 v[4:5], v[228:229], s[16:17], v[4:5] op_sel_hi:[1,0,1]
	v_pk_fma_f32 v[6:7], v[230:231], s[16:17], v[6:7] op_sel_hi:[1,0,1]
	v_pk_fma_f32 v[8:9], v[232:233], s[16:17], v[8:9] op_sel_hi:[1,0,1]
	v_pk_fma_f32 v[10:11], v[234:235], s[16:17], v[10:11] op_sel_hi:[1,0,1]
	v_pk_fma_f32 v[12:13], v[236:237], s[16:17], v[12:13] op_sel_hi:[1,0,1]
	v_pk_fma_f32 v[14:15], v[238:239], s[16:17], v[14:15] op_sel_hi:[1,0,1]
	v_cvt_pk_f32_fp8_e32 v[224:225], v164
	v_cvt_pk_f32_fp8_sdwa v[226:227], v164 src0_sel:WORD_1
	v_cvt_pk_f32_fp8_e32 v[228:229], v165
	v_cvt_pk_f32_fp8_sdwa v[230:231], v165 src0_sel:WORD_1
	v_cvt_pk_f32_fp8_e32 v[232:233], v166
	v_cvt_pk_f32_fp8_sdwa v[234:235], v166 src0_sel:WORD_1
	v_cvt_pk_f32_fp8_e32 v[236:237], v167
	v_cvt_pk_f32_fp8_sdwa v[238:239], v167 src0_sel:WORD_1
	v_pk_fma_f32 v[0:1], v[224:225], s[18:19], v[0:1] op_sel_hi:[1,0,1]
	v_pk_fma_f32 v[2:3], v[226:227], s[18:19], v[2:3] op_sel_hi:[1,0,1]
	v_pk_fma_f32 v[4:5], v[228:229], s[18:19], v[4:5] op_sel_hi:[1,0,1]
	v_pk_fma_f32 v[6:7], v[230:231], s[18:19], v[6:7] op_sel_hi:[1,0,1]
	v_pk_fma_f32 v[8:9], v[232:233], s[18:19], v[8:9] op_sel_hi:[1,0,1]
	v_pk_fma_f32 v[10:11], v[234:235], s[18:19], v[10:11] op_sel_hi:[1,0,1]
	v_pk_fma_f32 v[12:13], v[236:237], s[18:19], v[12:13] op_sel_hi:[1,0,1]
	v_pk_fma_f32 v[14:15], v[238:239], s[18:19], v[14:15] op_sel_hi:[1,0,1]
	v_cvt_pk_f32_fp8_e32 v[224:225], v168
	v_cvt_pk_f32_fp8_sdwa v[226:227], v168 src0_sel:WORD_1
	v_cvt_pk_f32_fp8_e32 v[228:229], v169
	v_cvt_pk_f32_fp8_sdwa v[230:231], v169 src0_sel:WORD_1
	v_cvt_pk_f32_fp8_e32 v[232:233], v170
	v_cvt_pk_f32_fp8_sdwa v[234:235], v170 src0_sel:WORD_1
	v_cvt_pk_f32_fp8_e32 v[236:237], v171
	v_cvt_pk_f32_fp8_sdwa v[238:239], v171 src0_sel:WORD_1
	v_pk_fma_f32 v[0:1], v[224:225], s[20:21], v[0:1] op_sel_hi:[1,0,1]
	v_pk_fma_f32 v[2:3], v[226:227], s[20:21], v[2:3] op_sel_hi:[1,0,1]
	v_pk_fma_f32 v[4:5], v[228:229], s[20:21], v[4:5] op_sel_hi:[1,0,1]
	v_pk_fma_f32 v[6:7], v[230:231], s[20:21], v[6:7] op_sel_hi:[1,0,1]
	v_pk_fma_f32 v[8:9], v[232:233], s[20:21], v[8:9] op_sel_hi:[1,0,1]
	v_pk_fma_f32 v[10:11], v[234:235], s[20:21], v[10:11] op_sel_hi:[1,0,1]
	v_pk_fma_f32 v[12:13], v[236:237], s[20:21], v[12:13] op_sel_hi:[1,0,1]
	v_pk_fma_f32 v[14:15], v[238:239], s[20:21], v[14:15] op_sel_hi:[1,0,1]
	v_cvt_pk_f32_fp8_e32 v[224:225], v172
	v_cvt_pk_f32_fp8_sdwa v[226:227], v172 src0_sel:WORD_1
	v_cvt_pk_f32_fp8_e32 v[228:229], v173
	v_cvt_pk_f32_fp8_sdwa v[230:231], v173 src0_sel:WORD_1
	v_cvt_pk_f32_fp8_e32 v[232:233], v174
	v_cvt_pk_f32_fp8_sdwa v[234:235], v174 src0_sel:WORD_1
	v_cvt_pk_f32_fp8_e32 v[236:237], v175
	v_cvt_pk_f32_fp8_sdwa v[238:239], v175 src0_sel:WORD_1
	v_pk_fma_f32 v[0:1], v[224:225], s[22:23], v[0:1] op_sel_hi:[1,0,1]
	v_pk_fma_f32 v[2:3], v[226:227], s[22:23], v[2:3] op_sel_hi:[1,0,1]
	v_pk_fma_f32 v[4:5], v[228:229], s[22:23], v[4:5] op_sel_hi:[1,0,1]
	v_pk_fma_f32 v[6:7], v[230:231], s[22:23], v[6:7] op_sel_hi:[1,0,1]
	v_pk_fma_f32 v[8:9], v[232:233], s[22:23], v[8:9] op_sel_hi:[1,0,1]
	v_pk_fma_f32 v[10:11], v[234:235], s[22:23], v[10:11] op_sel_hi:[1,0,1]
	v_pk_fma_f32 v[12:13], v[236:237], s[22:23], v[12:13] op_sel_hi:[1,0,1]
	v_pk_fma_f32 v[14:15], v[238:239], s[22:23], v[14:15] op_sel_hi:[1,0,1]
	v_cvt_pk_f32_fp8_e32 v[224:225], v176
	v_cvt_pk_f32_fp8_sdwa v[226:227], v176 src0_sel:WORD_1
	v_cvt_pk_f32_fp8_e32 v[228:229], v177
	v_cvt_pk_f32_fp8_sdwa v[230:231], v177 src0_sel:WORD_1
	v_cvt_pk_f32_fp8_e32 v[232:233], v178
	v_cvt_pk_f32_fp8_sdwa v[234:235], v178 src0_sel:WORD_1
	v_cvt_pk_f32_fp8_e32 v[236:237], v179
	v_cvt_pk_f32_fp8_sdwa v[238:239], v179 src0_sel:WORD_1
	v_pk_fma_f32 v[0:1], v[224:225], s[24:25], v[0:1] op_sel_hi:[1,0,1]
	v_pk_fma_f32 v[2:3], v[226:227], s[24:25], v[2:3] op_sel_hi:[1,0,1]
	v_pk_fma_f32 v[4:5], v[228:229], s[24:25], v[4:5] op_sel_hi:[1,0,1]
	v_pk_fma_f32 v[6:7], v[230:231], s[24:25], v[6:7] op_sel_hi:[1,0,1]
	v_pk_fma_f32 v[8:9], v[232:233], s[24:25], v[8:9] op_sel_hi:[1,0,1]
	v_pk_fma_f32 v[10:11], v[234:235], s[24:25], v[10:11] op_sel_hi:[1,0,1]
	v_pk_fma_f32 v[12:13], v[236:237], s[24:25], v[12:13] op_sel_hi:[1,0,1]
	v_pk_fma_f32 v[14:15], v[238:239], s[24:25], v[14:15] op_sel_hi:[1,0,1]
	v_cvt_pk_f32_fp8_e32 v[224:225], v180
	v_cvt_pk_f32_fp8_sdwa v[226:227], v180 src0_sel:WORD_1
	v_cvt_pk_f32_fp8_e32 v[228:229], v181
	v_cvt_pk_f32_fp8_sdwa v[230:231], v181 src0_sel:WORD_1
	v_cvt_pk_f32_fp8_e32 v[232:233], v182
	v_cvt_pk_f32_fp8_sdwa v[234:235], v182 src0_sel:WORD_1
	v_cvt_pk_f32_fp8_e32 v[236:237], v183
	v_cvt_pk_f32_fp8_sdwa v[238:239], v183 src0_sel:WORD_1
	v_pk_fma_f32 v[0:1], v[224:225], s[26:27], v[0:1] op_sel_hi:[1,0,1]
	v_pk_fma_f32 v[2:3], v[226:227], s[26:27], v[2:3] op_sel_hi:[1,0,1]
	v_pk_fma_f32 v[4:5], v[228:229], s[26:27], v[4:5] op_sel_hi:[1,0,1]
	v_pk_fma_f32 v[6:7], v[230:231], s[26:27], v[6:7] op_sel_hi:[1,0,1]
	v_pk_fma_f32 v[8:9], v[232:233], s[26:27], v[8:9] op_sel_hi:[1,0,1]
	v_pk_fma_f32 v[10:11], v[234:235], s[26:27], v[10:11] op_sel_hi:[1,0,1]
	v_pk_fma_f32 v[12:13], v[236:237], s[26:27], v[12:13] op_sel_hi:[1,0,1]
	v_pk_fma_f32 v[14:15], v[238:239], s[26:27], v[14:15] op_sel_hi:[1,0,1]
	v_cvt_pk_f32_fp8_e32 v[224:225], v184
	v_cvt_pk_f32_fp8_sdwa v[226:227], v184 src0_sel:WORD_1
	v_cvt_pk_f32_fp8_e32 v[228:229], v185
	v_cvt_pk_f32_fp8_sdwa v[230:231], v185 src0_sel:WORD_1
	v_cvt_pk_f32_fp8_e32 v[232:233], v186
	v_cvt_pk_f32_fp8_sdwa v[234:235], v186 src0_sel:WORD_1
	v_cvt_pk_f32_fp8_e32 v[236:237], v187
	v_cvt_pk_f32_fp8_sdwa v[238:239], v187 src0_sel:WORD_1
	v_pk_fma_f32 v[0:1], v[224:225], s[28:29], v[0:1] op_sel_hi:[1,0,1]
	v_pk_fma_f32 v[2:3], v[226:227], s[28:29], v[2:3] op_sel_hi:[1,0,1]
	v_pk_fma_f32 v[4:5], v[228:229], s[28:29], v[4:5] op_sel_hi:[1,0,1]
	v_pk_fma_f32 v[6:7], v[230:231], s[28:29], v[6:7] op_sel_hi:[1,0,1]
	v_pk_fma_f32 v[8:9], v[232:233], s[28:29], v[8:9] op_sel_hi:[1,0,1]
	v_pk_fma_f32 v[10:11], v[234:235], s[28:29], v[10:11] op_sel_hi:[1,0,1]
	v_pk_fma_f32 v[12:13], v[236:237], s[28:29], v[12:13] op_sel_hi:[1,0,1]
	v_pk_fma_f32 v[14:15], v[238:239], s[28:29], v[14:15] op_sel_hi:[1,0,1]
	v_cvt_pk_f32_fp8_e32 v[224:225], v188
	v_cvt_pk_f32_fp8_sdwa v[226:227], v188 src0_sel:WORD_1
	v_cvt_pk_f32_fp8_e32 v[228:229], v189
	v_cvt_pk_f32_fp8_sdwa v[230:231], v189 src0_sel:WORD_1
	v_cvt_pk_f32_fp8_e32 v[232:233], v190
	v_cvt_pk_f32_fp8_sdwa v[234:235], v190 src0_sel:WORD_1
	v_cvt_pk_f32_fp8_e32 v[236:237], v191
	v_cvt_pk_f32_fp8_sdwa v[238:239], v191 src0_sel:WORD_1
	v_pk_fma_f32 v[0:1], v[224:225], s[30:31], v[0:1] op_sel_hi:[1,0,1]
	v_pk_fma_f32 v[2:3], v[226:227], s[30:31], v[2:3] op_sel_hi:[1,0,1]
	v_pk_fma_f32 v[4:5], v[228:229], s[30:31], v[4:5] op_sel_hi:[1,0,1]
	v_pk_fma_f32 v[6:7], v[230:231], s[30:31], v[6:7] op_sel_hi:[1,0,1]
	v_pk_fma_f32 v[8:9], v[232:233], s[30:31], v[8:9] op_sel_hi:[1,0,1]
	v_pk_fma_f32 v[10:11], v[234:235], s[30:31], v[10:11] op_sel_hi:[1,0,1]
	v_pk_fma_f32 v[12:13], v[236:237], s[30:31], v[12:13] op_sel_hi:[1,0,1]
	v_pk_fma_f32 v[14:15], v[238:239], s[30:31], v[14:15] op_sel_hi:[1,0,1]
	v_readlane_b32 s16, v134, s72
	v_readlane_b32 s18, v134, s73
	v_readlane_b32 s20, v134, s74
	v_readlane_b32 s22, v134, s75
	v_readlane_b32 s24, v134, s76
	v_readlane_b32 s26, v134, s77
	v_readlane_b32 s28, v134, s78
	v_readlane_b32 s30, v134, s79
	v_readlane_b32 s48, v136, s72
	v_readlane_b32 s49, v136, s73
	v_readlane_b32 s50, v136, s74
	v_readlane_b32 s51, v136, s75
	v_readlane_b32 s52, v136, s76
	v_readlane_b32 s53, v136, s77
	v_readlane_b32 s54, v136, s78
	v_readlane_b32 s55, v136, s79
	s_add_u32 s32, s0, s48
	s_addc_u32 s33, s1, 0
	s_add_u32 s34, s0, s49
	s_addc_u32 s35, s1, 0
	s_add_u32 s36, s0, s50
	s_addc_u32 s37, s1, 0
	s_add_u32 s38, s0, s51
	s_addc_u32 s39, s1, 0
	s_add_u32 s40, s0, s52
	s_addc_u32 s41, s1, 0
	s_add_u32 s42, s0, s53
	s_addc_u32 s43, s1, 0
	s_add_u32 s44, s0, s54
	s_addc_u32 s45, s1, 0
	s_add_u32 s46, s0, s55
	s_addc_u32 s47, s1, 0
	global_load_dwordx4 v[160:163], v240, s[32:33]
	global_load_dwordx4 v[164:167], v240, s[34:35]
	global_load_dwordx4 v[168:171], v240, s[36:37]
	global_load_dwordx4 v[172:175], v240, s[38:39]
	global_load_dwordx4 v[176:179], v240, s[40:41]
	global_load_dwordx4 v[180:183], v240, s[42:43]
	global_load_dwordx4 v[184:187], v240, s[44:45]
	global_load_dwordx4 v[188:191], v240, s[46:47]
	s_waitcnt vmcnt(8)
	v_cvt_pk_f32_fp8_e32 v[224:225], v192
	v_cvt_pk_f32_fp8_sdwa v[226:227], v192 src0_sel:WORD_1
	v_cvt_pk_f32_fp8_e32 v[228:229], v193
	v_cvt_pk_f32_fp8_sdwa v[230:231], v193 src0_sel:WORD_1
	v_cvt_pk_f32_fp8_e32 v[232:233], v194
	v_cvt_pk_f32_fp8_sdwa v[234:235], v194 src0_sel:WORD_1
	v_cvt_pk_f32_fp8_e32 v[236:237], v195
	v_cvt_pk_f32_fp8_sdwa v[238:239], v195 src0_sel:WORD_1
	v_pk_fma_f32 v[16:17], v[224:225], s[16:17], v[16:17] op_sel_hi:[1,0,1]
	v_pk_fma_f32 v[18:19], v[226:227], s[16:17], v[18:19] op_sel_hi:[1,0,1]
	v_pk_fma_f32 v[20:21], v[228:229], s[16:17], v[20:21] op_sel_hi:[1,0,1]
	v_pk_fma_f32 v[22:23], v[230:231], s[16:17], v[22:23] op_sel_hi:[1,0,1]
	v_pk_fma_f32 v[24:25], v[232:233], s[16:17], v[24:25] op_sel_hi:[1,0,1]
	v_pk_fma_f32 v[26:27], v[234:235], s[16:17], v[26:27] op_sel_hi:[1,0,1]
	v_pk_fma_f32 v[28:29], v[236:237], s[16:17], v[28:29] op_sel_hi:[1,0,1]
	v_pk_fma_f32 v[30:31], v[238:239], s[16:17], v[30:31] op_sel_hi:[1,0,1]
	v_cvt_pk_f32_fp8_e32 v[224:225], v196
	v_cvt_pk_f32_fp8_sdwa v[226:227], v196 src0_sel:WORD_1
	v_cvt_pk_f32_fp8_e32 v[228:229], v197
	v_cvt_pk_f32_fp8_sdwa v[230:231], v197 src0_sel:WORD_1
	v_cvt_pk_f32_fp8_e32 v[232:233], v198
	v_cvt_pk_f32_fp8_sdwa v[234:235], v198 src0_sel:WORD_1
	v_cvt_pk_f32_fp8_e32 v[236:237], v199
	v_cvt_pk_f32_fp8_sdwa v[238:239], v199 src0_sel:WORD_1
	v_pk_fma_f32 v[16:17], v[224:225], s[18:19], v[16:17] op_sel_hi:[1,0,1]
	v_pk_fma_f32 v[18:19], v[226:227], s[18:19], v[18:19] op_sel_hi:[1,0,1]
	v_pk_fma_f32 v[20:21], v[228:229], s[18:19], v[20:21] op_sel_hi:[1,0,1]
	v_pk_fma_f32 v[22:23], v[230:231], s[18:19], v[22:23] op_sel_hi:[1,0,1]
	v_pk_fma_f32 v[24:25], v[232:233], s[18:19], v[24:25] op_sel_hi:[1,0,1]
	v_pk_fma_f32 v[26:27], v[234:235], s[18:19], v[26:27] op_sel_hi:[1,0,1]
	v_pk_fma_f32 v[28:29], v[236:237], s[18:19], v[28:29] op_sel_hi:[1,0,1]
	v_pk_fma_f32 v[30:31], v[238:239], s[18:19], v[30:31] op_sel_hi:[1,0,1]
	v_cvt_pk_f32_fp8_e32 v[224:225], v200
	v_cvt_pk_f32_fp8_sdwa v[226:227], v200 src0_sel:WORD_1
	v_cvt_pk_f32_fp8_e32 v[228:229], v201
	v_cvt_pk_f32_fp8_sdwa v[230:231], v201 src0_sel:WORD_1
	v_cvt_pk_f32_fp8_e32 v[232:233], v202
	v_cvt_pk_f32_fp8_sdwa v[234:235], v202 src0_sel:WORD_1
	v_cvt_pk_f32_fp8_e32 v[236:237], v203
	v_cvt_pk_f32_fp8_sdwa v[238:239], v203 src0_sel:WORD_1
	v_pk_fma_f32 v[16:17], v[224:225], s[20:21], v[16:17] op_sel_hi:[1,0,1]
	v_pk_fma_f32 v[18:19], v[226:227], s[20:21], v[18:19] op_sel_hi:[1,0,1]
	v_pk_fma_f32 v[20:21], v[228:229], s[20:21], v[20:21] op_sel_hi:[1,0,1]
	v_pk_fma_f32 v[22:23], v[230:231], s[20:21], v[22:23] op_sel_hi:[1,0,1]
	v_pk_fma_f32 v[24:25], v[232:233], s[20:21], v[24:25] op_sel_hi:[1,0,1]
	v_pk_fma_f32 v[26:27], v[234:235], s[20:21], v[26:27] op_sel_hi:[1,0,1]
	v_pk_fma_f32 v[28:29], v[236:237], s[20:21], v[28:29] op_sel_hi:[1,0,1]
	v_pk_fma_f32 v[30:31], v[238:239], s[20:21], v[30:31] op_sel_hi:[1,0,1]
	v_cvt_pk_f32_fp8_e32 v[224:225], v204
	v_cvt_pk_f32_fp8_sdwa v[226:227], v204 src0_sel:WORD_1
	v_cvt_pk_f32_fp8_e32 v[228:229], v205
	v_cvt_pk_f32_fp8_sdwa v[230:231], v205 src0_sel:WORD_1
	v_cvt_pk_f32_fp8_e32 v[232:233], v206
	v_cvt_pk_f32_fp8_sdwa v[234:235], v206 src0_sel:WORD_1
	v_cvt_pk_f32_fp8_e32 v[236:237], v207
	v_cvt_pk_f32_fp8_sdwa v[238:239], v207 src0_sel:WORD_1
	v_pk_fma_f32 v[16:17], v[224:225], s[22:23], v[16:17] op_sel_hi:[1,0,1]
	v_pk_fma_f32 v[18:19], v[226:227], s[22:23], v[18:19] op_sel_hi:[1,0,1]
	v_pk_fma_f32 v[20:21], v[228:229], s[22:23], v[20:21] op_sel_hi:[1,0,1]
	v_pk_fma_f32 v[22:23], v[230:231], s[22:23], v[22:23] op_sel_hi:[1,0,1]
	v_pk_fma_f32 v[24:25], v[232:233], s[22:23], v[24:25] op_sel_hi:[1,0,1]
	v_pk_fma_f32 v[26:27], v[234:235], s[22:23], v[26:27] op_sel_hi:[1,0,1]
	v_pk_fma_f32 v[28:29], v[236:237], s[22:23], v[28:29] op_sel_hi:[1,0,1]
	v_pk_fma_f32 v[30:31], v[238:239], s[22:23], v[30:31] op_sel_hi:[1,0,1]
	v_cvt_pk_f32_fp8_e32 v[224:225], v208
	v_cvt_pk_f32_fp8_sdwa v[226:227], v208 src0_sel:WORD_1
	v_cvt_pk_f32_fp8_e32 v[228:229], v209
	v_cvt_pk_f32_fp8_sdwa v[230:231], v209 src0_sel:WORD_1
	v_cvt_pk_f32_fp8_e32 v[232:233], v210
	v_cvt_pk_f32_fp8_sdwa v[234:235], v210 src0_sel:WORD_1
	v_cvt_pk_f32_fp8_e32 v[236:237], v211
	v_cvt_pk_f32_fp8_sdwa v[238:239], v211 src0_sel:WORD_1
	v_pk_fma_f32 v[16:17], v[224:225], s[24:25], v[16:17] op_sel_hi:[1,0,1]
	v_pk_fma_f32 v[18:19], v[226:227], s[24:25], v[18:19] op_sel_hi:[1,0,1]
	v_pk_fma_f32 v[20:21], v[228:229], s[24:25], v[20:21] op_sel_hi:[1,0,1]
	v_pk_fma_f32 v[22:23], v[230:231], s[24:25], v[22:23] op_sel_hi:[1,0,1]
	v_pk_fma_f32 v[24:25], v[232:233], s[24:25], v[24:25] op_sel_hi:[1,0,1]
	v_pk_fma_f32 v[26:27], v[234:235], s[24:25], v[26:27] op_sel_hi:[1,0,1]
	v_pk_fma_f32 v[28:29], v[236:237], s[24:25], v[28:29] op_sel_hi:[1,0,1]
	v_pk_fma_f32 v[30:31], v[238:239], s[24:25], v[30:31] op_sel_hi:[1,0,1]
	v_cvt_pk_f32_fp8_e32 v[224:225], v212
	v_cvt_pk_f32_fp8_sdwa v[226:227], v212 src0_sel:WORD_1
	v_cvt_pk_f32_fp8_e32 v[228:229], v213
	v_cvt_pk_f32_fp8_sdwa v[230:231], v213 src0_sel:WORD_1
	v_cvt_pk_f32_fp8_e32 v[232:233], v214
	v_cvt_pk_f32_fp8_sdwa v[234:235], v214 src0_sel:WORD_1
	v_cvt_pk_f32_fp8_e32 v[236:237], v215
	v_cvt_pk_f32_fp8_sdwa v[238:239], v215 src0_sel:WORD_1
	v_pk_fma_f32 v[16:17], v[224:225], s[26:27], v[16:17] op_sel_hi:[1,0,1]
	v_pk_fma_f32 v[18:19], v[226:227], s[26:27], v[18:19] op_sel_hi:[1,0,1]
	v_pk_fma_f32 v[20:21], v[228:229], s[26:27], v[20:21] op_sel_hi:[1,0,1]
	v_pk_fma_f32 v[22:23], v[230:231], s[26:27], v[22:23] op_sel_hi:[1,0,1]
	v_pk_fma_f32 v[24:25], v[232:233], s[26:27], v[24:25] op_sel_hi:[1,0,1]
	v_pk_fma_f32 v[26:27], v[234:235], s[26:27], v[26:27] op_sel_hi:[1,0,1]
	v_pk_fma_f32 v[28:29], v[236:237], s[26:27], v[28:29] op_sel_hi:[1,0,1]
	v_pk_fma_f32 v[30:31], v[238:239], s[26:27], v[30:31] op_sel_hi:[1,0,1]
	v_cvt_pk_f32_fp8_e32 v[224:225], v216
	v_cvt_pk_f32_fp8_sdwa v[226:227], v216 src0_sel:WORD_1
	v_cvt_pk_f32_fp8_e32 v[228:229], v217
	v_cvt_pk_f32_fp8_sdwa v[230:231], v217 src0_sel:WORD_1
	v_cvt_pk_f32_fp8_e32 v[232:233], v218
	v_cvt_pk_f32_fp8_sdwa v[234:235], v218 src0_sel:WORD_1
	v_cvt_pk_f32_fp8_e32 v[236:237], v219
	v_cvt_pk_f32_fp8_sdwa v[238:239], v219 src0_sel:WORD_1
	v_pk_fma_f32 v[16:17], v[224:225], s[28:29], v[16:17] op_sel_hi:[1,0,1]
	v_pk_fma_f32 v[18:19], v[226:227], s[28:29], v[18:19] op_sel_hi:[1,0,1]
	v_pk_fma_f32 v[20:21], v[228:229], s[28:29], v[20:21] op_sel_hi:[1,0,1]
	v_pk_fma_f32 v[22:23], v[230:231], s[28:29], v[22:23] op_sel_hi:[1,0,1]
	v_pk_fma_f32 v[24:25], v[232:233], s[28:29], v[24:25] op_sel_hi:[1,0,1]
	v_pk_fma_f32 v[26:27], v[234:235], s[28:29], v[26:27] op_sel_hi:[1,0,1]
	v_pk_fma_f32 v[28:29], v[236:237], s[28:29], v[28:29] op_sel_hi:[1,0,1]
	v_pk_fma_f32 v[30:31], v[238:239], s[28:29], v[30:31] op_sel_hi:[1,0,1]
	v_cvt_pk_f32_fp8_e32 v[224:225], v220
	v_cvt_pk_f32_fp8_sdwa v[226:227], v220 src0_sel:WORD_1
	v_cvt_pk_f32_fp8_e32 v[228:229], v221
	v_cvt_pk_f32_fp8_sdwa v[230:231], v221 src0_sel:WORD_1
	v_cvt_pk_f32_fp8_e32 v[232:233], v222
	v_cvt_pk_f32_fp8_sdwa v[234:235], v222 src0_sel:WORD_1
	v_cvt_pk_f32_fp8_e32 v[236:237], v223
	v_cvt_pk_f32_fp8_sdwa v[238:239], v223 src0_sel:WORD_1
	v_pk_fma_f32 v[16:17], v[224:225], s[30:31], v[16:17] op_sel_hi:[1,0,1]
	v_pk_fma_f32 v[18:19], v[226:227], s[30:31], v[18:19] op_sel_hi:[1,0,1]
	v_pk_fma_f32 v[20:21], v[228:229], s[30:31], v[20:21] op_sel_hi:[1,0,1]
	v_pk_fma_f32 v[22:23], v[230:231], s[30:31], v[22:23] op_sel_hi:[1,0,1]
	v_pk_fma_f32 v[24:25], v[232:233], s[30:31], v[24:25] op_sel_hi:[1,0,1]
	v_pk_fma_f32 v[26:27], v[234:235], s[30:31], v[26:27] op_sel_hi:[1,0,1]
	v_pk_fma_f32 v[28:29], v[236:237], s[30:31], v[28:29] op_sel_hi:[1,0,1]
	v_pk_fma_f32 v[30:31], v[238:239], s[30:31], v[30:31] op_sel_hi:[1,0,1]
	v_readlane_b32 s16, v138, s72
	v_readlane_b32 s18, v138, s73
	v_readlane_b32 s20, v138, s74
	v_readlane_b32 s22, v138, s75
	v_readlane_b32 s24, v138, s76
	v_readlane_b32 s26, v138, s77
	v_readlane_b32 s28, v138, s78
	v_readlane_b32 s30, v138, s79
	v_readlane_b32 s48, v140, s72
	v_readlane_b32 s49, v140, s73
	v_readlane_b32 s50, v140, s74
	v_readlane_b32 s51, v140, s75
	v_readlane_b32 s52, v140, s76
	v_readlane_b32 s53, v140, s77
	v_readlane_b32 s54, v140, s78
	v_readlane_b32 s55, v140, s79
	s_add_u32 s32, s0, s48
	s_addc_u32 s33, s1, 0
	s_add_u32 s34, s0, s49
	s_addc_u32 s35, s1, 0
	s_add_u32 s36, s0, s50
	s_addc_u32 s37, s1, 0
	s_add_u32 s38, s0, s51
	s_addc_u32 s39, s1, 0
	s_add_u32 s40, s0, s52
	s_addc_u32 s41, s1, 0
	s_add_u32 s42, s0, s53
	s_addc_u32 s43, s1, 0
	s_add_u32 s44, s0, s54
	s_addc_u32 s45, s1, 0
	s_add_u32 s46, s0, s55
	s_addc_u32 s47, s1, 0
	global_load_dwordx4 v[192:195], v240, s[32:33]
	global_load_dwordx4 v[196:199], v240, s[34:35]
	global_load_dwordx4 v[200:203], v240, s[36:37]
	global_load_dwordx4 v[204:207], v240, s[38:39]
	global_load_dwordx4 v[208:211], v240, s[40:41]
	global_load_dwordx4 v[212:215], v240, s[42:43]
	global_load_dwordx4 v[216:219], v240, s[44:45]
	global_load_dwordx4 v[220:223], v240, s[46:47]
	s_waitcnt vmcnt(8)
	v_cvt_pk_f32_fp8_e32 v[224:225], v160
	v_cvt_pk_f32_fp8_sdwa v[226:227], v160 src0_sel:WORD_1
	v_cvt_pk_f32_fp8_e32 v[228:229], v161
	v_cvt_pk_f32_fp8_sdwa v[230:231], v161 src0_sel:WORD_1
	v_cvt_pk_f32_fp8_e32 v[232:233], v162
	v_cvt_pk_f32_fp8_sdwa v[234:235], v162 src0_sel:WORD_1
	v_cvt_pk_f32_fp8_e32 v[236:237], v163
	v_cvt_pk_f32_fp8_sdwa v[238:239], v163 src0_sel:WORD_1
	v_pk_fma_f32 v[32:33], v[224:225], s[16:17], v[32:33] op_sel_hi:[1,0,1]
	v_pk_fma_f32 v[34:35], v[226:227], s[16:17], v[34:35] op_sel_hi:[1,0,1]
	v_pk_fma_f32 v[36:37], v[228:229], s[16:17], v[36:37] op_sel_hi:[1,0,1]
	v_pk_fma_f32 v[38:39], v[230:231], s[16:17], v[38:39] op_sel_hi:[1,0,1]
	v_pk_fma_f32 v[40:41], v[232:233], s[16:17], v[40:41] op_sel_hi:[1,0,1]
	v_pk_fma_f32 v[42:43], v[234:235], s[16:17], v[42:43] op_sel_hi:[1,0,1]
	v_pk_fma_f32 v[44:45], v[236:237], s[16:17], v[44:45] op_sel_hi:[1,0,1]
	v_pk_fma_f32 v[46:47], v[238:239], s[16:17], v[46:47] op_sel_hi:[1,0,1]
	v_cvt_pk_f32_fp8_e32 v[224:225], v164
	v_cvt_pk_f32_fp8_sdwa v[226:227], v164 src0_sel:WORD_1
	v_cvt_pk_f32_fp8_e32 v[228:229], v165
	v_cvt_pk_f32_fp8_sdwa v[230:231], v165 src0_sel:WORD_1
	v_cvt_pk_f32_fp8_e32 v[232:233], v166
	v_cvt_pk_f32_fp8_sdwa v[234:235], v166 src0_sel:WORD_1
	v_cvt_pk_f32_fp8_e32 v[236:237], v167
	v_cvt_pk_f32_fp8_sdwa v[238:239], v167 src0_sel:WORD_1
	v_pk_fma_f32 v[32:33], v[224:225], s[18:19], v[32:33] op_sel_hi:[1,0,1]
	v_pk_fma_f32 v[34:35], v[226:227], s[18:19], v[34:35] op_sel_hi:[1,0,1]
	v_pk_fma_f32 v[36:37], v[228:229], s[18:19], v[36:37] op_sel_hi:[1,0,1]
	v_pk_fma_f32 v[38:39], v[230:231], s[18:19], v[38:39] op_sel_hi:[1,0,1]
	v_pk_fma_f32 v[40:41], v[232:233], s[18:19], v[40:41] op_sel_hi:[1,0,1]
	v_pk_fma_f32 v[42:43], v[234:235], s[18:19], v[42:43] op_sel_hi:[1,0,1]
	v_pk_fma_f32 v[44:45], v[236:237], s[18:19], v[44:45] op_sel_hi:[1,0,1]
	v_pk_fma_f32 v[46:47], v[238:239], s[18:19], v[46:47] op_sel_hi:[1,0,1]
	v_cvt_pk_f32_fp8_e32 v[224:225], v168
	v_cvt_pk_f32_fp8_sdwa v[226:227], v168 src0_sel:WORD_1
	v_cvt_pk_f32_fp8_e32 v[228:229], v169
	v_cvt_pk_f32_fp8_sdwa v[230:231], v169 src0_sel:WORD_1
	v_cvt_pk_f32_fp8_e32 v[232:233], v170
	v_cvt_pk_f32_fp8_sdwa v[234:235], v170 src0_sel:WORD_1
	v_cvt_pk_f32_fp8_e32 v[236:237], v171
	v_cvt_pk_f32_fp8_sdwa v[238:239], v171 src0_sel:WORD_1
	v_pk_fma_f32 v[32:33], v[224:225], s[20:21], v[32:33] op_sel_hi:[1,0,1]
	v_pk_fma_f32 v[34:35], v[226:227], s[20:21], v[34:35] op_sel_hi:[1,0,1]
	v_pk_fma_f32 v[36:37], v[228:229], s[20:21], v[36:37] op_sel_hi:[1,0,1]
	v_pk_fma_f32 v[38:39], v[230:231], s[20:21], v[38:39] op_sel_hi:[1,0,1]
	v_pk_fma_f32 v[40:41], v[232:233], s[20:21], v[40:41] op_sel_hi:[1,0,1]
	v_pk_fma_f32 v[42:43], v[234:235], s[20:21], v[42:43] op_sel_hi:[1,0,1]
	v_pk_fma_f32 v[44:45], v[236:237], s[20:21], v[44:45] op_sel_hi:[1,0,1]
	v_pk_fma_f32 v[46:47], v[238:239], s[20:21], v[46:47] op_sel_hi:[1,0,1]
	v_cvt_pk_f32_fp8_e32 v[224:225], v172
	v_cvt_pk_f32_fp8_sdwa v[226:227], v172 src0_sel:WORD_1
	v_cvt_pk_f32_fp8_e32 v[228:229], v173
	v_cvt_pk_f32_fp8_sdwa v[230:231], v173 src0_sel:WORD_1
	v_cvt_pk_f32_fp8_e32 v[232:233], v174
	v_cvt_pk_f32_fp8_sdwa v[234:235], v174 src0_sel:WORD_1
	v_cvt_pk_f32_fp8_e32 v[236:237], v175
	v_cvt_pk_f32_fp8_sdwa v[238:239], v175 src0_sel:WORD_1
	v_pk_fma_f32 v[32:33], v[224:225], s[22:23], v[32:33] op_sel_hi:[1,0,1]
	v_pk_fma_f32 v[34:35], v[226:227], s[22:23], v[34:35] op_sel_hi:[1,0,1]
	v_pk_fma_f32 v[36:37], v[228:229], s[22:23], v[36:37] op_sel_hi:[1,0,1]
	v_pk_fma_f32 v[38:39], v[230:231], s[22:23], v[38:39] op_sel_hi:[1,0,1]
	v_pk_fma_f32 v[40:41], v[232:233], s[22:23], v[40:41] op_sel_hi:[1,0,1]
	v_pk_fma_f32 v[42:43], v[234:235], s[22:23], v[42:43] op_sel_hi:[1,0,1]
	v_pk_fma_f32 v[44:45], v[236:237], s[22:23], v[44:45] op_sel_hi:[1,0,1]
	v_pk_fma_f32 v[46:47], v[238:239], s[22:23], v[46:47] op_sel_hi:[1,0,1]
	v_cvt_pk_f32_fp8_e32 v[224:225], v176
	v_cvt_pk_f32_fp8_sdwa v[226:227], v176 src0_sel:WORD_1
	v_cvt_pk_f32_fp8_e32 v[228:229], v177
	v_cvt_pk_f32_fp8_sdwa v[230:231], v177 src0_sel:WORD_1
	v_cvt_pk_f32_fp8_e32 v[232:233], v178
	v_cvt_pk_f32_fp8_sdwa v[234:235], v178 src0_sel:WORD_1
	v_cvt_pk_f32_fp8_e32 v[236:237], v179
	v_cvt_pk_f32_fp8_sdwa v[238:239], v179 src0_sel:WORD_1
	v_pk_fma_f32 v[32:33], v[224:225], s[24:25], v[32:33] op_sel_hi:[1,0,1]
	v_pk_fma_f32 v[34:35], v[226:227], s[24:25], v[34:35] op_sel_hi:[1,0,1]
	v_pk_fma_f32 v[36:37], v[228:229], s[24:25], v[36:37] op_sel_hi:[1,0,1]
	v_pk_fma_f32 v[38:39], v[230:231], s[24:25], v[38:39] op_sel_hi:[1,0,1]
	v_pk_fma_f32 v[40:41], v[232:233], s[24:25], v[40:41] op_sel_hi:[1,0,1]
	v_pk_fma_f32 v[42:43], v[234:235], s[24:25], v[42:43] op_sel_hi:[1,0,1]
	v_pk_fma_f32 v[44:45], v[236:237], s[24:25], v[44:45] op_sel_hi:[1,0,1]
	v_pk_fma_f32 v[46:47], v[238:239], s[24:25], v[46:47] op_sel_hi:[1,0,1]
	v_cvt_pk_f32_fp8_e32 v[224:225], v180
	v_cvt_pk_f32_fp8_sdwa v[226:227], v180 src0_sel:WORD_1
	v_cvt_pk_f32_fp8_e32 v[228:229], v181
	v_cvt_pk_f32_fp8_sdwa v[230:231], v181 src0_sel:WORD_1
	v_cvt_pk_f32_fp8_e32 v[232:233], v182
	v_cvt_pk_f32_fp8_sdwa v[234:235], v182 src0_sel:WORD_1
	v_cvt_pk_f32_fp8_e32 v[236:237], v183
	v_cvt_pk_f32_fp8_sdwa v[238:239], v183 src0_sel:WORD_1
	v_pk_fma_f32 v[32:33], v[224:225], s[26:27], v[32:33] op_sel_hi:[1,0,1]
	v_pk_fma_f32 v[34:35], v[226:227], s[26:27], v[34:35] op_sel_hi:[1,0,1]
	v_pk_fma_f32 v[36:37], v[228:229], s[26:27], v[36:37] op_sel_hi:[1,0,1]
	v_pk_fma_f32 v[38:39], v[230:231], s[26:27], v[38:39] op_sel_hi:[1,0,1]
	v_pk_fma_f32 v[40:41], v[232:233], s[26:27], v[40:41] op_sel_hi:[1,0,1]
	v_pk_fma_f32 v[42:43], v[234:235], s[26:27], v[42:43] op_sel_hi:[1,0,1]
	v_pk_fma_f32 v[44:45], v[236:237], s[26:27], v[44:45] op_sel_hi:[1,0,1]
	v_pk_fma_f32 v[46:47], v[238:239], s[26:27], v[46:47] op_sel_hi:[1,0,1]
	v_cvt_pk_f32_fp8_e32 v[224:225], v184
	v_cvt_pk_f32_fp8_sdwa v[226:227], v184 src0_sel:WORD_1
	v_cvt_pk_f32_fp8_e32 v[228:229], v185
	v_cvt_pk_f32_fp8_sdwa v[230:231], v185 src0_sel:WORD_1
	v_cvt_pk_f32_fp8_e32 v[232:233], v186
	v_cvt_pk_f32_fp8_sdwa v[234:235], v186 src0_sel:WORD_1
	v_cvt_pk_f32_fp8_e32 v[236:237], v187
	v_cvt_pk_f32_fp8_sdwa v[238:239], v187 src0_sel:WORD_1
	v_pk_fma_f32 v[32:33], v[224:225], s[28:29], v[32:33] op_sel_hi:[1,0,1]
	v_pk_fma_f32 v[34:35], v[226:227], s[28:29], v[34:35] op_sel_hi:[1,0,1]
	v_pk_fma_f32 v[36:37], v[228:229], s[28:29], v[36:37] op_sel_hi:[1,0,1]
	v_pk_fma_f32 v[38:39], v[230:231], s[28:29], v[38:39] op_sel_hi:[1,0,1]
	v_pk_fma_f32 v[40:41], v[232:233], s[28:29], v[40:41] op_sel_hi:[1,0,1]
	v_pk_fma_f32 v[42:43], v[234:235], s[28:29], v[42:43] op_sel_hi:[1,0,1]
	v_pk_fma_f32 v[44:45], v[236:237], s[28:29], v[44:45] op_sel_hi:[1,0,1]
	v_pk_fma_f32 v[46:47], v[238:239], s[28:29], v[46:47] op_sel_hi:[1,0,1]
	v_cvt_pk_f32_fp8_e32 v[224:225], v188
	v_cvt_pk_f32_fp8_sdwa v[226:227], v188 src0_sel:WORD_1
	v_cvt_pk_f32_fp8_e32 v[228:229], v189
	v_cvt_pk_f32_fp8_sdwa v[230:231], v189 src0_sel:WORD_1
	v_cvt_pk_f32_fp8_e32 v[232:233], v190
	v_cvt_pk_f32_fp8_sdwa v[234:235], v190 src0_sel:WORD_1
	v_cvt_pk_f32_fp8_e32 v[236:237], v191
	v_cvt_pk_f32_fp8_sdwa v[238:239], v191 src0_sel:WORD_1
	v_pk_fma_f32 v[32:33], v[224:225], s[30:31], v[32:33] op_sel_hi:[1,0,1]
	v_pk_fma_f32 v[34:35], v[226:227], s[30:31], v[34:35] op_sel_hi:[1,0,1]
	v_pk_fma_f32 v[36:37], v[228:229], s[30:31], v[36:37] op_sel_hi:[1,0,1]
	v_pk_fma_f32 v[38:39], v[230:231], s[30:31], v[38:39] op_sel_hi:[1,0,1]
	v_pk_fma_f32 v[40:41], v[232:233], s[30:31], v[40:41] op_sel_hi:[1,0,1]
	v_pk_fma_f32 v[42:43], v[234:235], s[30:31], v[42:43] op_sel_hi:[1,0,1]
	v_pk_fma_f32 v[44:45], v[236:237], s[30:31], v[44:45] op_sel_hi:[1,0,1]
	v_pk_fma_f32 v[46:47], v[238:239], s[30:31], v[46:47] op_sel_hi:[1,0,1]
	v_readlane_b32 s16, v142, s72
	v_readlane_b32 s18, v142, s73
	v_readlane_b32 s20, v142, s74
	v_readlane_b32 s22, v142, s75
	v_readlane_b32 s24, v142, s76
	v_readlane_b32 s26, v142, s77
	v_readlane_b32 s28, v142, s78
	v_readlane_b32 s30, v142, s79
	v_readlane_b32 s48, v129, s72
	v_readlane_b32 s49, v129, s73
	v_readlane_b32 s50, v129, s74
	v_readlane_b32 s51, v129, s75
	v_readlane_b32 s52, v129, s76
	v_readlane_b32 s53, v129, s77
	v_readlane_b32 s54, v129, s78
	v_readlane_b32 s55, v129, s79
	s_add_u32 s32, s0, s48
	s_addc_u32 s33, s1, 0
	s_add_u32 s34, s0, s49
	s_addc_u32 s35, s1, 0
	s_add_u32 s36, s0, s50
	s_addc_u32 s37, s1, 0
	s_add_u32 s38, s0, s51
	s_addc_u32 s39, s1, 0
	s_add_u32 s40, s0, s52
	s_addc_u32 s41, s1, 0
	s_add_u32 s42, s0, s53
	s_addc_u32 s43, s1, 0
	s_add_u32 s44, s0, s54
	s_addc_u32 s45, s1, 0
	s_add_u32 s46, s0, s55
	s_addc_u32 s47, s1, 0
	global_load_dwordx4 v[160:163], v240, s[32:33]
	global_load_dwordx4 v[164:167], v240, s[34:35]
	global_load_dwordx4 v[168:171], v240, s[36:37]
	global_load_dwordx4 v[172:175], v240, s[38:39]
	global_load_dwordx4 v[176:179], v240, s[40:41]
	global_load_dwordx4 v[180:183], v240, s[42:43]
	global_load_dwordx4 v[184:187], v240, s[44:45]
	global_load_dwordx4 v[188:191], v240, s[46:47]
	s_waitcnt vmcnt(8)
	v_cvt_pk_f32_fp8_e32 v[224:225], v192
	v_cvt_pk_f32_fp8_sdwa v[226:227], v192 src0_sel:WORD_1
	v_cvt_pk_f32_fp8_e32 v[228:229], v193
	v_cvt_pk_f32_fp8_sdwa v[230:231], v193 src0_sel:WORD_1
	v_cvt_pk_f32_fp8_e32 v[232:233], v194
	v_cvt_pk_f32_fp8_sdwa v[234:235], v194 src0_sel:WORD_1
	v_cvt_pk_f32_fp8_e32 v[236:237], v195
	v_cvt_pk_f32_fp8_sdwa v[238:239], v195 src0_sel:WORD_1
	v_pk_fma_f32 v[48:49], v[224:225], s[16:17], v[48:49] op_sel_hi:[1,0,1]
	v_pk_fma_f32 v[50:51], v[226:227], s[16:17], v[50:51] op_sel_hi:[1,0,1]
	v_pk_fma_f32 v[52:53], v[228:229], s[16:17], v[52:53] op_sel_hi:[1,0,1]
	v_pk_fma_f32 v[54:55], v[230:231], s[16:17], v[54:55] op_sel_hi:[1,0,1]
	v_pk_fma_f32 v[56:57], v[232:233], s[16:17], v[56:57] op_sel_hi:[1,0,1]
	v_pk_fma_f32 v[58:59], v[234:235], s[16:17], v[58:59] op_sel_hi:[1,0,1]
	v_pk_fma_f32 v[60:61], v[236:237], s[16:17], v[60:61] op_sel_hi:[1,0,1]
	v_pk_fma_f32 v[62:63], v[238:239], s[16:17], v[62:63] op_sel_hi:[1,0,1]
	v_cvt_pk_f32_fp8_e32 v[224:225], v196
	v_cvt_pk_f32_fp8_sdwa v[226:227], v196 src0_sel:WORD_1
	v_cvt_pk_f32_fp8_e32 v[228:229], v197
	v_cvt_pk_f32_fp8_sdwa v[230:231], v197 src0_sel:WORD_1
	v_cvt_pk_f32_fp8_e32 v[232:233], v198
	v_cvt_pk_f32_fp8_sdwa v[234:235], v198 src0_sel:WORD_1
	v_cvt_pk_f32_fp8_e32 v[236:237], v199
	v_cvt_pk_f32_fp8_sdwa v[238:239], v199 src0_sel:WORD_1
	v_pk_fma_f32 v[48:49], v[224:225], s[18:19], v[48:49] op_sel_hi:[1,0,1]
	v_pk_fma_f32 v[50:51], v[226:227], s[18:19], v[50:51] op_sel_hi:[1,0,1]
	v_pk_fma_f32 v[52:53], v[228:229], s[18:19], v[52:53] op_sel_hi:[1,0,1]
	v_pk_fma_f32 v[54:55], v[230:231], s[18:19], v[54:55] op_sel_hi:[1,0,1]
	v_pk_fma_f32 v[56:57], v[232:233], s[18:19], v[56:57] op_sel_hi:[1,0,1]
	v_pk_fma_f32 v[58:59], v[234:235], s[18:19], v[58:59] op_sel_hi:[1,0,1]
	v_pk_fma_f32 v[60:61], v[236:237], s[18:19], v[60:61] op_sel_hi:[1,0,1]
	v_pk_fma_f32 v[62:63], v[238:239], s[18:19], v[62:63] op_sel_hi:[1,0,1]
	v_cvt_pk_f32_fp8_e32 v[224:225], v200
	v_cvt_pk_f32_fp8_sdwa v[226:227], v200 src0_sel:WORD_1
	v_cvt_pk_f32_fp8_e32 v[228:229], v201
	v_cvt_pk_f32_fp8_sdwa v[230:231], v201 src0_sel:WORD_1
	v_cvt_pk_f32_fp8_e32 v[232:233], v202
	v_cvt_pk_f32_fp8_sdwa v[234:235], v202 src0_sel:WORD_1
	v_cvt_pk_f32_fp8_e32 v[236:237], v203
	v_cvt_pk_f32_fp8_sdwa v[238:239], v203 src0_sel:WORD_1
	v_pk_fma_f32 v[48:49], v[224:225], s[20:21], v[48:49] op_sel_hi:[1,0,1]
	v_pk_fma_f32 v[50:51], v[226:227], s[20:21], v[50:51] op_sel_hi:[1,0,1]
	v_pk_fma_f32 v[52:53], v[228:229], s[20:21], v[52:53] op_sel_hi:[1,0,1]
	v_pk_fma_f32 v[54:55], v[230:231], s[20:21], v[54:55] op_sel_hi:[1,0,1]
	v_pk_fma_f32 v[56:57], v[232:233], s[20:21], v[56:57] op_sel_hi:[1,0,1]
	v_pk_fma_f32 v[58:59], v[234:235], s[20:21], v[58:59] op_sel_hi:[1,0,1]
	v_pk_fma_f32 v[60:61], v[236:237], s[20:21], v[60:61] op_sel_hi:[1,0,1]
	v_pk_fma_f32 v[62:63], v[238:239], s[20:21], v[62:63] op_sel_hi:[1,0,1]
	v_cvt_pk_f32_fp8_e32 v[224:225], v204
	v_cvt_pk_f32_fp8_sdwa v[226:227], v204 src0_sel:WORD_1
	v_cvt_pk_f32_fp8_e32 v[228:229], v205
	v_cvt_pk_f32_fp8_sdwa v[230:231], v205 src0_sel:WORD_1
	v_cvt_pk_f32_fp8_e32 v[232:233], v206
	v_cvt_pk_f32_fp8_sdwa v[234:235], v206 src0_sel:WORD_1
	v_cvt_pk_f32_fp8_e32 v[236:237], v207
	v_cvt_pk_f32_fp8_sdwa v[238:239], v207 src0_sel:WORD_1
	v_pk_fma_f32 v[48:49], v[224:225], s[22:23], v[48:49] op_sel_hi:[1,0,1]
	v_pk_fma_f32 v[50:51], v[226:227], s[22:23], v[50:51] op_sel_hi:[1,0,1]
	v_pk_fma_f32 v[52:53], v[228:229], s[22:23], v[52:53] op_sel_hi:[1,0,1]
	v_pk_fma_f32 v[54:55], v[230:231], s[22:23], v[54:55] op_sel_hi:[1,0,1]
	v_pk_fma_f32 v[56:57], v[232:233], s[22:23], v[56:57] op_sel_hi:[1,0,1]
	v_pk_fma_f32 v[58:59], v[234:235], s[22:23], v[58:59] op_sel_hi:[1,0,1]
	v_pk_fma_f32 v[60:61], v[236:237], s[22:23], v[60:61] op_sel_hi:[1,0,1]
	v_pk_fma_f32 v[62:63], v[238:239], s[22:23], v[62:63] op_sel_hi:[1,0,1]
	v_cvt_pk_f32_fp8_e32 v[224:225], v208
	v_cvt_pk_f32_fp8_sdwa v[226:227], v208 src0_sel:WORD_1
	v_cvt_pk_f32_fp8_e32 v[228:229], v209
	v_cvt_pk_f32_fp8_sdwa v[230:231], v209 src0_sel:WORD_1
	v_cvt_pk_f32_fp8_e32 v[232:233], v210
	v_cvt_pk_f32_fp8_sdwa v[234:235], v210 src0_sel:WORD_1
	v_cvt_pk_f32_fp8_e32 v[236:237], v211
	v_cvt_pk_f32_fp8_sdwa v[238:239], v211 src0_sel:WORD_1
	v_pk_fma_f32 v[48:49], v[224:225], s[24:25], v[48:49] op_sel_hi:[1,0,1]
	v_pk_fma_f32 v[50:51], v[226:227], s[24:25], v[50:51] op_sel_hi:[1,0,1]
	v_pk_fma_f32 v[52:53], v[228:229], s[24:25], v[52:53] op_sel_hi:[1,0,1]
	v_pk_fma_f32 v[54:55], v[230:231], s[24:25], v[54:55] op_sel_hi:[1,0,1]
	v_pk_fma_f32 v[56:57], v[232:233], s[24:25], v[56:57] op_sel_hi:[1,0,1]
	v_pk_fma_f32 v[58:59], v[234:235], s[24:25], v[58:59] op_sel_hi:[1,0,1]
	v_pk_fma_f32 v[60:61], v[236:237], s[24:25], v[60:61] op_sel_hi:[1,0,1]
	v_pk_fma_f32 v[62:63], v[238:239], s[24:25], v[62:63] op_sel_hi:[1,0,1]
	v_cvt_pk_f32_fp8_e32 v[224:225], v212
	v_cvt_pk_f32_fp8_sdwa v[226:227], v212 src0_sel:WORD_1
	v_cvt_pk_f32_fp8_e32 v[228:229], v213
	v_cvt_pk_f32_fp8_sdwa v[230:231], v213 src0_sel:WORD_1
	v_cvt_pk_f32_fp8_e32 v[232:233], v214
	v_cvt_pk_f32_fp8_sdwa v[234:235], v214 src0_sel:WORD_1
	v_cvt_pk_f32_fp8_e32 v[236:237], v215
	v_cvt_pk_f32_fp8_sdwa v[238:239], v215 src0_sel:WORD_1
	v_pk_fma_f32 v[48:49], v[224:225], s[26:27], v[48:49] op_sel_hi:[1,0,1]
	v_pk_fma_f32 v[50:51], v[226:227], s[26:27], v[50:51] op_sel_hi:[1,0,1]
	v_pk_fma_f32 v[52:53], v[228:229], s[26:27], v[52:53] op_sel_hi:[1,0,1]
	v_pk_fma_f32 v[54:55], v[230:231], s[26:27], v[54:55] op_sel_hi:[1,0,1]
	v_pk_fma_f32 v[56:57], v[232:233], s[26:27], v[56:57] op_sel_hi:[1,0,1]
	v_pk_fma_f32 v[58:59], v[234:235], s[26:27], v[58:59] op_sel_hi:[1,0,1]
	v_pk_fma_f32 v[60:61], v[236:237], s[26:27], v[60:61] op_sel_hi:[1,0,1]
	v_pk_fma_f32 v[62:63], v[238:239], s[26:27], v[62:63] op_sel_hi:[1,0,1]
	v_cvt_pk_f32_fp8_e32 v[224:225], v216
	v_cvt_pk_f32_fp8_sdwa v[226:227], v216 src0_sel:WORD_1
	v_cvt_pk_f32_fp8_e32 v[228:229], v217
	v_cvt_pk_f32_fp8_sdwa v[230:231], v217 src0_sel:WORD_1
	v_cvt_pk_f32_fp8_e32 v[232:233], v218
	v_cvt_pk_f32_fp8_sdwa v[234:235], v218 src0_sel:WORD_1
	v_cvt_pk_f32_fp8_e32 v[236:237], v219
	v_cvt_pk_f32_fp8_sdwa v[238:239], v219 src0_sel:WORD_1
	v_pk_fma_f32 v[48:49], v[224:225], s[28:29], v[48:49] op_sel_hi:[1,0,1]
	v_pk_fma_f32 v[50:51], v[226:227], s[28:29], v[50:51] op_sel_hi:[1,0,1]
	v_pk_fma_f32 v[52:53], v[228:229], s[28:29], v[52:53] op_sel_hi:[1,0,1]
	v_pk_fma_f32 v[54:55], v[230:231], s[28:29], v[54:55] op_sel_hi:[1,0,1]
	v_pk_fma_f32 v[56:57], v[232:233], s[28:29], v[56:57] op_sel_hi:[1,0,1]
	v_pk_fma_f32 v[58:59], v[234:235], s[28:29], v[58:59] op_sel_hi:[1,0,1]
	v_pk_fma_f32 v[60:61], v[236:237], s[28:29], v[60:61] op_sel_hi:[1,0,1]
	v_pk_fma_f32 v[62:63], v[238:239], s[28:29], v[62:63] op_sel_hi:[1,0,1]
	v_cvt_pk_f32_fp8_e32 v[224:225], v220
	v_cvt_pk_f32_fp8_sdwa v[226:227], v220 src0_sel:WORD_1
	v_cvt_pk_f32_fp8_e32 v[228:229], v221
	v_cvt_pk_f32_fp8_sdwa v[230:231], v221 src0_sel:WORD_1
	v_cvt_pk_f32_fp8_e32 v[232:233], v222
	v_cvt_pk_f32_fp8_sdwa v[234:235], v222 src0_sel:WORD_1
	v_cvt_pk_f32_fp8_e32 v[236:237], v223
	v_cvt_pk_f32_fp8_sdwa v[238:239], v223 src0_sel:WORD_1
	v_pk_fma_f32 v[48:49], v[224:225], s[30:31], v[48:49] op_sel_hi:[1,0,1]
	v_pk_fma_f32 v[50:51], v[226:227], s[30:31], v[50:51] op_sel_hi:[1,0,1]
	v_pk_fma_f32 v[52:53], v[228:229], s[30:31], v[52:53] op_sel_hi:[1,0,1]
	v_pk_fma_f32 v[54:55], v[230:231], s[30:31], v[54:55] op_sel_hi:[1,0,1]
	v_pk_fma_f32 v[56:57], v[232:233], s[30:31], v[56:57] op_sel_hi:[1,0,1]
	v_pk_fma_f32 v[58:59], v[234:235], s[30:31], v[58:59] op_sel_hi:[1,0,1]
	v_pk_fma_f32 v[60:61], v[236:237], s[30:31], v[60:61] op_sel_hi:[1,0,1]
	v_pk_fma_f32 v[62:63], v[238:239], s[30:31], v[62:63] op_sel_hi:[1,0,1]
	v_readlane_b32 s16, v131, s72
	v_readlane_b32 s18, v131, s73
	v_readlane_b32 s20, v131, s74
	v_readlane_b32 s22, v131, s75
	v_readlane_b32 s24, v131, s76
	v_readlane_b32 s26, v131, s77
	v_readlane_b32 s28, v131, s78
	v_readlane_b32 s30, v131, s79
	v_readlane_b32 s48, v133, s72
	v_readlane_b32 s49, v133, s73
	v_readlane_b32 s50, v133, s74
	v_readlane_b32 s51, v133, s75
	v_readlane_b32 s52, v133, s76
	v_readlane_b32 s53, v133, s77
	v_readlane_b32 s54, v133, s78
	v_readlane_b32 s55, v133, s79
	s_add_u32 s32, s0, s48
	s_addc_u32 s33, s1, 0
	s_add_u32 s34, s0, s49
	s_addc_u32 s35, s1, 0
	s_add_u32 s36, s0, s50
	s_addc_u32 s37, s1, 0
	s_add_u32 s38, s0, s51
	s_addc_u32 s39, s1, 0
	s_add_u32 s40, s0, s52
	s_addc_u32 s41, s1, 0
	s_add_u32 s42, s0, s53
	s_addc_u32 s43, s1, 0
	s_add_u32 s44, s0, s54
	s_addc_u32 s45, s1, 0
	s_add_u32 s46, s0, s55
	s_addc_u32 s47, s1, 0
	global_load_dwordx4 v[192:195], v240, s[32:33]
	global_load_dwordx4 v[196:199], v240, s[34:35]
	global_load_dwordx4 v[200:203], v240, s[36:37]
	global_load_dwordx4 v[204:207], v240, s[38:39]
	global_load_dwordx4 v[208:211], v240, s[40:41]
	global_load_dwordx4 v[212:215], v240, s[42:43]
	global_load_dwordx4 v[216:219], v240, s[44:45]
	global_load_dwordx4 v[220:223], v240, s[46:47]
	s_waitcnt vmcnt(8)
	v_cvt_pk_f32_fp8_e32 v[224:225], v160
	v_cvt_pk_f32_fp8_sdwa v[226:227], v160 src0_sel:WORD_1
	v_cvt_pk_f32_fp8_e32 v[228:229], v161
	v_cvt_pk_f32_fp8_sdwa v[230:231], v161 src0_sel:WORD_1
	v_cvt_pk_f32_fp8_e32 v[232:233], v162
	v_cvt_pk_f32_fp8_sdwa v[234:235], v162 src0_sel:WORD_1
	v_cvt_pk_f32_fp8_e32 v[236:237], v163
	v_cvt_pk_f32_fp8_sdwa v[238:239], v163 src0_sel:WORD_1
	v_pk_fma_f32 v[0:1], v[224:225], s[16:17], v[0:1] op_sel_hi:[1,0,1]
	v_pk_fma_f32 v[2:3], v[226:227], s[16:17], v[2:3] op_sel_hi:[1,0,1]
	v_pk_fma_f32 v[4:5], v[228:229], s[16:17], v[4:5] op_sel_hi:[1,0,1]
	v_pk_fma_f32 v[6:7], v[230:231], s[16:17], v[6:7] op_sel_hi:[1,0,1]
	v_pk_fma_f32 v[8:9], v[232:233], s[16:17], v[8:9] op_sel_hi:[1,0,1]
	v_pk_fma_f32 v[10:11], v[234:235], s[16:17], v[10:11] op_sel_hi:[1,0,1]
	v_pk_fma_f32 v[12:13], v[236:237], s[16:17], v[12:13] op_sel_hi:[1,0,1]
	v_pk_fma_f32 v[14:15], v[238:239], s[16:17], v[14:15] op_sel_hi:[1,0,1]
	v_cvt_pk_f32_fp8_e32 v[224:225], v164
	v_cvt_pk_f32_fp8_sdwa v[226:227], v164 src0_sel:WORD_1
	v_cvt_pk_f32_fp8_e32 v[228:229], v165
	v_cvt_pk_f32_fp8_sdwa v[230:231], v165 src0_sel:WORD_1
	v_cvt_pk_f32_fp8_e32 v[232:233], v166
	v_cvt_pk_f32_fp8_sdwa v[234:235], v166 src0_sel:WORD_1
	v_cvt_pk_f32_fp8_e32 v[236:237], v167
	v_cvt_pk_f32_fp8_sdwa v[238:239], v167 src0_sel:WORD_1
	v_pk_fma_f32 v[0:1], v[224:225], s[18:19], v[0:1] op_sel_hi:[1,0,1]
	v_pk_fma_f32 v[2:3], v[226:227], s[18:19], v[2:3] op_sel_hi:[1,0,1]
	v_pk_fma_f32 v[4:5], v[228:229], s[18:19], v[4:5] op_sel_hi:[1,0,1]
	v_pk_fma_f32 v[6:7], v[230:231], s[18:19], v[6:7] op_sel_hi:[1,0,1]
	v_pk_fma_f32 v[8:9], v[232:233], s[18:19], v[8:9] op_sel_hi:[1,0,1]
	v_pk_fma_f32 v[10:11], v[234:235], s[18:19], v[10:11] op_sel_hi:[1,0,1]
	v_pk_fma_f32 v[12:13], v[236:237], s[18:19], v[12:13] op_sel_hi:[1,0,1]
	v_pk_fma_f32 v[14:15], v[238:239], s[18:19], v[14:15] op_sel_hi:[1,0,1]
	v_cvt_pk_f32_fp8_e32 v[224:225], v168
	v_cvt_pk_f32_fp8_sdwa v[226:227], v168 src0_sel:WORD_1
	v_cvt_pk_f32_fp8_e32 v[228:229], v169
	v_cvt_pk_f32_fp8_sdwa v[230:231], v169 src0_sel:WORD_1
	v_cvt_pk_f32_fp8_e32 v[232:233], v170
	v_cvt_pk_f32_fp8_sdwa v[234:235], v170 src0_sel:WORD_1
	v_cvt_pk_f32_fp8_e32 v[236:237], v171
	v_cvt_pk_f32_fp8_sdwa v[238:239], v171 src0_sel:WORD_1
	v_pk_fma_f32 v[0:1], v[224:225], s[20:21], v[0:1] op_sel_hi:[1,0,1]
	v_pk_fma_f32 v[2:3], v[226:227], s[20:21], v[2:3] op_sel_hi:[1,0,1]
	v_pk_fma_f32 v[4:5], v[228:229], s[20:21], v[4:5] op_sel_hi:[1,0,1]
	v_pk_fma_f32 v[6:7], v[230:231], s[20:21], v[6:7] op_sel_hi:[1,0,1]
	v_pk_fma_f32 v[8:9], v[232:233], s[20:21], v[8:9] op_sel_hi:[1,0,1]
	v_pk_fma_f32 v[10:11], v[234:235], s[20:21], v[10:11] op_sel_hi:[1,0,1]
	v_pk_fma_f32 v[12:13], v[236:237], s[20:21], v[12:13] op_sel_hi:[1,0,1]
	v_pk_fma_f32 v[14:15], v[238:239], s[20:21], v[14:15] op_sel_hi:[1,0,1]
	v_cvt_pk_f32_fp8_e32 v[224:225], v172
	v_cvt_pk_f32_fp8_sdwa v[226:227], v172 src0_sel:WORD_1
	v_cvt_pk_f32_fp8_e32 v[228:229], v173
	v_cvt_pk_f32_fp8_sdwa v[230:231], v173 src0_sel:WORD_1
	v_cvt_pk_f32_fp8_e32 v[232:233], v174
	v_cvt_pk_f32_fp8_sdwa v[234:235], v174 src0_sel:WORD_1
	v_cvt_pk_f32_fp8_e32 v[236:237], v175
	v_cvt_pk_f32_fp8_sdwa v[238:239], v175 src0_sel:WORD_1
	v_pk_fma_f32 v[0:1], v[224:225], s[22:23], v[0:1] op_sel_hi:[1,0,1]
	v_pk_fma_f32 v[2:3], v[226:227], s[22:23], v[2:3] op_sel_hi:[1,0,1]
	v_pk_fma_f32 v[4:5], v[228:229], s[22:23], v[4:5] op_sel_hi:[1,0,1]
	v_pk_fma_f32 v[6:7], v[230:231], s[22:23], v[6:7] op_sel_hi:[1,0,1]
	v_pk_fma_f32 v[8:9], v[232:233], s[22:23], v[8:9] op_sel_hi:[1,0,1]
	v_pk_fma_f32 v[10:11], v[234:235], s[22:23], v[10:11] op_sel_hi:[1,0,1]
	v_pk_fma_f32 v[12:13], v[236:237], s[22:23], v[12:13] op_sel_hi:[1,0,1]
	v_pk_fma_f32 v[14:15], v[238:239], s[22:23], v[14:15] op_sel_hi:[1,0,1]
	v_cvt_pk_f32_fp8_e32 v[224:225], v176
	v_cvt_pk_f32_fp8_sdwa v[226:227], v176 src0_sel:WORD_1
	v_cvt_pk_f32_fp8_e32 v[228:229], v177
	v_cvt_pk_f32_fp8_sdwa v[230:231], v177 src0_sel:WORD_1
	v_cvt_pk_f32_fp8_e32 v[232:233], v178
	v_cvt_pk_f32_fp8_sdwa v[234:235], v178 src0_sel:WORD_1
	v_cvt_pk_f32_fp8_e32 v[236:237], v179
	v_cvt_pk_f32_fp8_sdwa v[238:239], v179 src0_sel:WORD_1
	v_pk_fma_f32 v[0:1], v[224:225], s[24:25], v[0:1] op_sel_hi:[1,0,1]
	v_pk_fma_f32 v[2:3], v[226:227], s[24:25], v[2:3] op_sel_hi:[1,0,1]
	v_pk_fma_f32 v[4:5], v[228:229], s[24:25], v[4:5] op_sel_hi:[1,0,1]
	v_pk_fma_f32 v[6:7], v[230:231], s[24:25], v[6:7] op_sel_hi:[1,0,1]
	v_pk_fma_f32 v[8:9], v[232:233], s[24:25], v[8:9] op_sel_hi:[1,0,1]
	v_pk_fma_f32 v[10:11], v[234:235], s[24:25], v[10:11] op_sel_hi:[1,0,1]
	v_pk_fma_f32 v[12:13], v[236:237], s[24:25], v[12:13] op_sel_hi:[1,0,1]
	v_pk_fma_f32 v[14:15], v[238:239], s[24:25], v[14:15] op_sel_hi:[1,0,1]
	v_cvt_pk_f32_fp8_e32 v[224:225], v180
	v_cvt_pk_f32_fp8_sdwa v[226:227], v180 src0_sel:WORD_1
	v_cvt_pk_f32_fp8_e32 v[228:229], v181
	v_cvt_pk_f32_fp8_sdwa v[230:231], v181 src0_sel:WORD_1
	v_cvt_pk_f32_fp8_e32 v[232:233], v182
	v_cvt_pk_f32_fp8_sdwa v[234:235], v182 src0_sel:WORD_1
	v_cvt_pk_f32_fp8_e32 v[236:237], v183
	v_cvt_pk_f32_fp8_sdwa v[238:239], v183 src0_sel:WORD_1
	v_pk_fma_f32 v[0:1], v[224:225], s[26:27], v[0:1] op_sel_hi:[1,0,1]
	v_pk_fma_f32 v[2:3], v[226:227], s[26:27], v[2:3] op_sel_hi:[1,0,1]
	v_pk_fma_f32 v[4:5], v[228:229], s[26:27], v[4:5] op_sel_hi:[1,0,1]
	v_pk_fma_f32 v[6:7], v[230:231], s[26:27], v[6:7] op_sel_hi:[1,0,1]
	v_pk_fma_f32 v[8:9], v[232:233], s[26:27], v[8:9] op_sel_hi:[1,0,1]
	v_pk_fma_f32 v[10:11], v[234:235], s[26:27], v[10:11] op_sel_hi:[1,0,1]
	v_pk_fma_f32 v[12:13], v[236:237], s[26:27], v[12:13] op_sel_hi:[1,0,1]
	v_pk_fma_f32 v[14:15], v[238:239], s[26:27], v[14:15] op_sel_hi:[1,0,1]
	v_cvt_pk_f32_fp8_e32 v[224:225], v184
	v_cvt_pk_f32_fp8_sdwa v[226:227], v184 src0_sel:WORD_1
	v_cvt_pk_f32_fp8_e32 v[228:229], v185
	v_cvt_pk_f32_fp8_sdwa v[230:231], v185 src0_sel:WORD_1
	v_cvt_pk_f32_fp8_e32 v[232:233], v186
	v_cvt_pk_f32_fp8_sdwa v[234:235], v186 src0_sel:WORD_1
	v_cvt_pk_f32_fp8_e32 v[236:237], v187
	v_cvt_pk_f32_fp8_sdwa v[238:239], v187 src0_sel:WORD_1
	v_pk_fma_f32 v[0:1], v[224:225], s[28:29], v[0:1] op_sel_hi:[1,0,1]
	v_pk_fma_f32 v[2:3], v[226:227], s[28:29], v[2:3] op_sel_hi:[1,0,1]
	v_pk_fma_f32 v[4:5], v[228:229], s[28:29], v[4:5] op_sel_hi:[1,0,1]
	v_pk_fma_f32 v[6:7], v[230:231], s[28:29], v[6:7] op_sel_hi:[1,0,1]
	v_pk_fma_f32 v[8:9], v[232:233], s[28:29], v[8:9] op_sel_hi:[1,0,1]
	v_pk_fma_f32 v[10:11], v[234:235], s[28:29], v[10:11] op_sel_hi:[1,0,1]
	v_pk_fma_f32 v[12:13], v[236:237], s[28:29], v[12:13] op_sel_hi:[1,0,1]
	v_pk_fma_f32 v[14:15], v[238:239], s[28:29], v[14:15] op_sel_hi:[1,0,1]
	v_cvt_pk_f32_fp8_e32 v[224:225], v188
	v_cvt_pk_f32_fp8_sdwa v[226:227], v188 src0_sel:WORD_1
	v_cvt_pk_f32_fp8_e32 v[228:229], v189
	v_cvt_pk_f32_fp8_sdwa v[230:231], v189 src0_sel:WORD_1
	v_cvt_pk_f32_fp8_e32 v[232:233], v190
	v_cvt_pk_f32_fp8_sdwa v[234:235], v190 src0_sel:WORD_1
	v_cvt_pk_f32_fp8_e32 v[236:237], v191
	v_cvt_pk_f32_fp8_sdwa v[238:239], v191 src0_sel:WORD_1
	v_pk_fma_f32 v[0:1], v[224:225], s[30:31], v[0:1] op_sel_hi:[1,0,1]
	v_pk_fma_f32 v[2:3], v[226:227], s[30:31], v[2:3] op_sel_hi:[1,0,1]
	v_pk_fma_f32 v[4:5], v[228:229], s[30:31], v[4:5] op_sel_hi:[1,0,1]
	v_pk_fma_f32 v[6:7], v[230:231], s[30:31], v[6:7] op_sel_hi:[1,0,1]
	v_pk_fma_f32 v[8:9], v[232:233], s[30:31], v[8:9] op_sel_hi:[1,0,1]
	v_pk_fma_f32 v[10:11], v[234:235], s[30:31], v[10:11] op_sel_hi:[1,0,1]
	v_pk_fma_f32 v[12:13], v[236:237], s[30:31], v[12:13] op_sel_hi:[1,0,1]
	v_pk_fma_f32 v[14:15], v[238:239], s[30:31], v[14:15] op_sel_hi:[1,0,1]
	v_readlane_b32 s16, v135, s72
	v_readlane_b32 s18, v135, s73
	v_readlane_b32 s20, v135, s74
	v_readlane_b32 s22, v135, s75
	v_readlane_b32 s24, v135, s76
	v_readlane_b32 s26, v135, s77
	v_readlane_b32 s28, v135, s78
	v_readlane_b32 s30, v135, s79
	v_readlane_b32 s48, v137, s72
	v_readlane_b32 s49, v137, s73
	v_readlane_b32 s50, v137, s74
	v_readlane_b32 s51, v137, s75
	v_readlane_b32 s52, v137, s76
	v_readlane_b32 s53, v137, s77
	v_readlane_b32 s54, v137, s78
	v_readlane_b32 s55, v137, s79
	s_add_u32 s32, s0, s48
	s_addc_u32 s33, s1, 0
	s_add_u32 s34, s0, s49
	s_addc_u32 s35, s1, 0
	s_add_u32 s36, s0, s50
	s_addc_u32 s37, s1, 0
	s_add_u32 s38, s0, s51
	s_addc_u32 s39, s1, 0
	s_add_u32 s40, s0, s52
	s_addc_u32 s41, s1, 0
	s_add_u32 s42, s0, s53
	s_addc_u32 s43, s1, 0
	s_add_u32 s44, s0, s54
	s_addc_u32 s45, s1, 0
	s_add_u32 s46, s0, s55
	s_addc_u32 s47, s1, 0
	global_load_dwordx4 v[160:163], v240, s[32:33]
	global_load_dwordx4 v[164:167], v240, s[34:35]
	global_load_dwordx4 v[168:171], v240, s[36:37]
	global_load_dwordx4 v[172:175], v240, s[38:39]
	global_load_dwordx4 v[176:179], v240, s[40:41]
	global_load_dwordx4 v[180:183], v240, s[42:43]
	global_load_dwordx4 v[184:187], v240, s[44:45]
	global_load_dwordx4 v[188:191], v240, s[46:47]
	s_waitcnt vmcnt(8)
	v_cvt_pk_f32_fp8_e32 v[224:225], v192
	v_cvt_pk_f32_fp8_sdwa v[226:227], v192 src0_sel:WORD_1
	v_cvt_pk_f32_fp8_e32 v[228:229], v193
	v_cvt_pk_f32_fp8_sdwa v[230:231], v193 src0_sel:WORD_1
	v_cvt_pk_f32_fp8_e32 v[232:233], v194
	v_cvt_pk_f32_fp8_sdwa v[234:235], v194 src0_sel:WORD_1
	v_cvt_pk_f32_fp8_e32 v[236:237], v195
	v_cvt_pk_f32_fp8_sdwa v[238:239], v195 src0_sel:WORD_1
	v_pk_fma_f32 v[16:17], v[224:225], s[16:17], v[16:17] op_sel_hi:[1,0,1]
	v_pk_fma_f32 v[18:19], v[226:227], s[16:17], v[18:19] op_sel_hi:[1,0,1]
	v_pk_fma_f32 v[20:21], v[228:229], s[16:17], v[20:21] op_sel_hi:[1,0,1]
	v_pk_fma_f32 v[22:23], v[230:231], s[16:17], v[22:23] op_sel_hi:[1,0,1]
	v_pk_fma_f32 v[24:25], v[232:233], s[16:17], v[24:25] op_sel_hi:[1,0,1]
	v_pk_fma_f32 v[26:27], v[234:235], s[16:17], v[26:27] op_sel_hi:[1,0,1]
	v_pk_fma_f32 v[28:29], v[236:237], s[16:17], v[28:29] op_sel_hi:[1,0,1]
	v_pk_fma_f32 v[30:31], v[238:239], s[16:17], v[30:31] op_sel_hi:[1,0,1]
	v_cvt_pk_f32_fp8_e32 v[224:225], v196
	v_cvt_pk_f32_fp8_sdwa v[226:227], v196 src0_sel:WORD_1
	v_cvt_pk_f32_fp8_e32 v[228:229], v197
	v_cvt_pk_f32_fp8_sdwa v[230:231], v197 src0_sel:WORD_1
	v_cvt_pk_f32_fp8_e32 v[232:233], v198
	v_cvt_pk_f32_fp8_sdwa v[234:235], v198 src0_sel:WORD_1
	v_cvt_pk_f32_fp8_e32 v[236:237], v199
	v_cvt_pk_f32_fp8_sdwa v[238:239], v199 src0_sel:WORD_1
	v_pk_fma_f32 v[16:17], v[224:225], s[18:19], v[16:17] op_sel_hi:[1,0,1]
	v_pk_fma_f32 v[18:19], v[226:227], s[18:19], v[18:19] op_sel_hi:[1,0,1]
	v_pk_fma_f32 v[20:21], v[228:229], s[18:19], v[20:21] op_sel_hi:[1,0,1]
	v_pk_fma_f32 v[22:23], v[230:231], s[18:19], v[22:23] op_sel_hi:[1,0,1]
	v_pk_fma_f32 v[24:25], v[232:233], s[18:19], v[24:25] op_sel_hi:[1,0,1]
	v_pk_fma_f32 v[26:27], v[234:235], s[18:19], v[26:27] op_sel_hi:[1,0,1]
	v_pk_fma_f32 v[28:29], v[236:237], s[18:19], v[28:29] op_sel_hi:[1,0,1]
	v_pk_fma_f32 v[30:31], v[238:239], s[18:19], v[30:31] op_sel_hi:[1,0,1]
	v_cvt_pk_f32_fp8_e32 v[224:225], v200
	v_cvt_pk_f32_fp8_sdwa v[226:227], v200 src0_sel:WORD_1
	v_cvt_pk_f32_fp8_e32 v[228:229], v201
	v_cvt_pk_f32_fp8_sdwa v[230:231], v201 src0_sel:WORD_1
	v_cvt_pk_f32_fp8_e32 v[232:233], v202
	v_cvt_pk_f32_fp8_sdwa v[234:235], v202 src0_sel:WORD_1
	v_cvt_pk_f32_fp8_e32 v[236:237], v203
	v_cvt_pk_f32_fp8_sdwa v[238:239], v203 src0_sel:WORD_1
	v_pk_fma_f32 v[16:17], v[224:225], s[20:21], v[16:17] op_sel_hi:[1,0,1]
	v_pk_fma_f32 v[18:19], v[226:227], s[20:21], v[18:19] op_sel_hi:[1,0,1]
	v_pk_fma_f32 v[20:21], v[228:229], s[20:21], v[20:21] op_sel_hi:[1,0,1]
	v_pk_fma_f32 v[22:23], v[230:231], s[20:21], v[22:23] op_sel_hi:[1,0,1]
	v_pk_fma_f32 v[24:25], v[232:233], s[20:21], v[24:25] op_sel_hi:[1,0,1]
	v_pk_fma_f32 v[26:27], v[234:235], s[20:21], v[26:27] op_sel_hi:[1,0,1]
	v_pk_fma_f32 v[28:29], v[236:237], s[20:21], v[28:29] op_sel_hi:[1,0,1]
	v_pk_fma_f32 v[30:31], v[238:239], s[20:21], v[30:31] op_sel_hi:[1,0,1]
	v_cvt_pk_f32_fp8_e32 v[224:225], v204
	v_cvt_pk_f32_fp8_sdwa v[226:227], v204 src0_sel:WORD_1
	v_cvt_pk_f32_fp8_e32 v[228:229], v205
	v_cvt_pk_f32_fp8_sdwa v[230:231], v205 src0_sel:WORD_1
	v_cvt_pk_f32_fp8_e32 v[232:233], v206
	v_cvt_pk_f32_fp8_sdwa v[234:235], v206 src0_sel:WORD_1
	v_cvt_pk_f32_fp8_e32 v[236:237], v207
	v_cvt_pk_f32_fp8_sdwa v[238:239], v207 src0_sel:WORD_1
	v_pk_fma_f32 v[16:17], v[224:225], s[22:23], v[16:17] op_sel_hi:[1,0,1]
	v_pk_fma_f32 v[18:19], v[226:227], s[22:23], v[18:19] op_sel_hi:[1,0,1]
	v_pk_fma_f32 v[20:21], v[228:229], s[22:23], v[20:21] op_sel_hi:[1,0,1]
	v_pk_fma_f32 v[22:23], v[230:231], s[22:23], v[22:23] op_sel_hi:[1,0,1]
	v_pk_fma_f32 v[24:25], v[232:233], s[22:23], v[24:25] op_sel_hi:[1,0,1]
	v_pk_fma_f32 v[26:27], v[234:235], s[22:23], v[26:27] op_sel_hi:[1,0,1]
	v_pk_fma_f32 v[28:29], v[236:237], s[22:23], v[28:29] op_sel_hi:[1,0,1]
	v_pk_fma_f32 v[30:31], v[238:239], s[22:23], v[30:31] op_sel_hi:[1,0,1]
	v_cvt_pk_f32_fp8_e32 v[224:225], v208
	v_cvt_pk_f32_fp8_sdwa v[226:227], v208 src0_sel:WORD_1
	v_cvt_pk_f32_fp8_e32 v[228:229], v209
	v_cvt_pk_f32_fp8_sdwa v[230:231], v209 src0_sel:WORD_1
	v_cvt_pk_f32_fp8_e32 v[232:233], v210
	v_cvt_pk_f32_fp8_sdwa v[234:235], v210 src0_sel:WORD_1
	v_cvt_pk_f32_fp8_e32 v[236:237], v211
	v_cvt_pk_f32_fp8_sdwa v[238:239], v211 src0_sel:WORD_1
	v_pk_fma_f32 v[16:17], v[224:225], s[24:25], v[16:17] op_sel_hi:[1,0,1]
	v_pk_fma_f32 v[18:19], v[226:227], s[24:25], v[18:19] op_sel_hi:[1,0,1]
	v_pk_fma_f32 v[20:21], v[228:229], s[24:25], v[20:21] op_sel_hi:[1,0,1]
	v_pk_fma_f32 v[22:23], v[230:231], s[24:25], v[22:23] op_sel_hi:[1,0,1]
	v_pk_fma_f32 v[24:25], v[232:233], s[24:25], v[24:25] op_sel_hi:[1,0,1]
	v_pk_fma_f32 v[26:27], v[234:235], s[24:25], v[26:27] op_sel_hi:[1,0,1]
	v_pk_fma_f32 v[28:29], v[236:237], s[24:25], v[28:29] op_sel_hi:[1,0,1]
	v_pk_fma_f32 v[30:31], v[238:239], s[24:25], v[30:31] op_sel_hi:[1,0,1]
	v_cvt_pk_f32_fp8_e32 v[224:225], v212
	v_cvt_pk_f32_fp8_sdwa v[226:227], v212 src0_sel:WORD_1
	v_cvt_pk_f32_fp8_e32 v[228:229], v213
	v_cvt_pk_f32_fp8_sdwa v[230:231], v213 src0_sel:WORD_1
	v_cvt_pk_f32_fp8_e32 v[232:233], v214
	v_cvt_pk_f32_fp8_sdwa v[234:235], v214 src0_sel:WORD_1
	v_cvt_pk_f32_fp8_e32 v[236:237], v215
	v_cvt_pk_f32_fp8_sdwa v[238:239], v215 src0_sel:WORD_1
	v_pk_fma_f32 v[16:17], v[224:225], s[26:27], v[16:17] op_sel_hi:[1,0,1]
	v_pk_fma_f32 v[18:19], v[226:227], s[26:27], v[18:19] op_sel_hi:[1,0,1]
	v_pk_fma_f32 v[20:21], v[228:229], s[26:27], v[20:21] op_sel_hi:[1,0,1]
	v_pk_fma_f32 v[22:23], v[230:231], s[26:27], v[22:23] op_sel_hi:[1,0,1]
	v_pk_fma_f32 v[24:25], v[232:233], s[26:27], v[24:25] op_sel_hi:[1,0,1]
	v_pk_fma_f32 v[26:27], v[234:235], s[26:27], v[26:27] op_sel_hi:[1,0,1]
	v_pk_fma_f32 v[28:29], v[236:237], s[26:27], v[28:29] op_sel_hi:[1,0,1]
	v_pk_fma_f32 v[30:31], v[238:239], s[26:27], v[30:31] op_sel_hi:[1,0,1]
	v_cvt_pk_f32_fp8_e32 v[224:225], v216
	v_cvt_pk_f32_fp8_sdwa v[226:227], v216 src0_sel:WORD_1
	v_cvt_pk_f32_fp8_e32 v[228:229], v217
	v_cvt_pk_f32_fp8_sdwa v[230:231], v217 src0_sel:WORD_1
	v_cvt_pk_f32_fp8_e32 v[232:233], v218
	v_cvt_pk_f32_fp8_sdwa v[234:235], v218 src0_sel:WORD_1
	v_cvt_pk_f32_fp8_e32 v[236:237], v219
	v_cvt_pk_f32_fp8_sdwa v[238:239], v219 src0_sel:WORD_1
	v_pk_fma_f32 v[16:17], v[224:225], s[28:29], v[16:17] op_sel_hi:[1,0,1]
	v_pk_fma_f32 v[18:19], v[226:227], s[28:29], v[18:19] op_sel_hi:[1,0,1]
	v_pk_fma_f32 v[20:21], v[228:229], s[28:29], v[20:21] op_sel_hi:[1,0,1]
	v_pk_fma_f32 v[22:23], v[230:231], s[28:29], v[22:23] op_sel_hi:[1,0,1]
	v_pk_fma_f32 v[24:25], v[232:233], s[28:29], v[24:25] op_sel_hi:[1,0,1]
	v_pk_fma_f32 v[26:27], v[234:235], s[28:29], v[26:27] op_sel_hi:[1,0,1]
	v_pk_fma_f32 v[28:29], v[236:237], s[28:29], v[28:29] op_sel_hi:[1,0,1]
	v_pk_fma_f32 v[30:31], v[238:239], s[28:29], v[30:31] op_sel_hi:[1,0,1]
	v_cvt_pk_f32_fp8_e32 v[224:225], v220
	v_cvt_pk_f32_fp8_sdwa v[226:227], v220 src0_sel:WORD_1
	v_cvt_pk_f32_fp8_e32 v[228:229], v221
	v_cvt_pk_f32_fp8_sdwa v[230:231], v221 src0_sel:WORD_1
	v_cvt_pk_f32_fp8_e32 v[232:233], v222
	v_cvt_pk_f32_fp8_sdwa v[234:235], v222 src0_sel:WORD_1
	v_cvt_pk_f32_fp8_e32 v[236:237], v223
	v_cvt_pk_f32_fp8_sdwa v[238:239], v223 src0_sel:WORD_1
	v_pk_fma_f32 v[16:17], v[224:225], s[30:31], v[16:17] op_sel_hi:[1,0,1]
	v_pk_fma_f32 v[18:19], v[226:227], s[30:31], v[18:19] op_sel_hi:[1,0,1]
	v_pk_fma_f32 v[20:21], v[228:229], s[30:31], v[20:21] op_sel_hi:[1,0,1]
	v_pk_fma_f32 v[22:23], v[230:231], s[30:31], v[22:23] op_sel_hi:[1,0,1]
	v_pk_fma_f32 v[24:25], v[232:233], s[30:31], v[24:25] op_sel_hi:[1,0,1]
	v_pk_fma_f32 v[26:27], v[234:235], s[30:31], v[26:27] op_sel_hi:[1,0,1]
	v_pk_fma_f32 v[28:29], v[236:237], s[30:31], v[28:29] op_sel_hi:[1,0,1]
	v_pk_fma_f32 v[30:31], v[238:239], s[30:31], v[30:31] op_sel_hi:[1,0,1]
	v_readlane_b32 s16, v139, s72
	v_readlane_b32 s18, v139, s73
	v_readlane_b32 s20, v139, s74
	v_readlane_b32 s22, v139, s75
	v_readlane_b32 s24, v139, s76
	v_readlane_b32 s26, v139, s77
	v_readlane_b32 s28, v139, s78
	v_readlane_b32 s30, v139, s79
	v_readlane_b32 s48, v141, s72
	v_readlane_b32 s49, v141, s73
	v_readlane_b32 s50, v141, s74
	v_readlane_b32 s51, v141, s75
	v_readlane_b32 s52, v141, s76
	v_readlane_b32 s53, v141, s77
	v_readlane_b32 s54, v141, s78
	v_readlane_b32 s55, v141, s79
	s_add_u32 s32, s0, s48
	s_addc_u32 s33, s1, 0
	s_add_u32 s34, s0, s49
	s_addc_u32 s35, s1, 0
	s_add_u32 s36, s0, s50
	s_addc_u32 s37, s1, 0
	s_add_u32 s38, s0, s51
	s_addc_u32 s39, s1, 0
	s_add_u32 s40, s0, s52
	s_addc_u32 s41, s1, 0
	s_add_u32 s42, s0, s53
	s_addc_u32 s43, s1, 0
	s_add_u32 s44, s0, s54
	s_addc_u32 s45, s1, 0
	s_add_u32 s46, s0, s55
	s_addc_u32 s47, s1, 0
	global_load_dwordx4 v[192:195], v240, s[32:33]
	global_load_dwordx4 v[196:199], v240, s[34:35]
	global_load_dwordx4 v[200:203], v240, s[36:37]
	global_load_dwordx4 v[204:207], v240, s[38:39]
	global_load_dwordx4 v[208:211], v240, s[40:41]
	global_load_dwordx4 v[212:215], v240, s[42:43]
	global_load_dwordx4 v[216:219], v240, s[44:45]
	global_load_dwordx4 v[220:223], v240, s[46:47]
	s_waitcnt vmcnt(8)
	v_cvt_pk_f32_fp8_e32 v[224:225], v160
	v_cvt_pk_f32_fp8_sdwa v[226:227], v160 src0_sel:WORD_1
	v_cvt_pk_f32_fp8_e32 v[228:229], v161
	v_cvt_pk_f32_fp8_sdwa v[230:231], v161 src0_sel:WORD_1
	v_cvt_pk_f32_fp8_e32 v[232:233], v162
	v_cvt_pk_f32_fp8_sdwa v[234:235], v162 src0_sel:WORD_1
	v_cvt_pk_f32_fp8_e32 v[236:237], v163
	v_cvt_pk_f32_fp8_sdwa v[238:239], v163 src0_sel:WORD_1
	v_pk_fma_f32 v[32:33], v[224:225], s[16:17], v[32:33] op_sel_hi:[1,0,1]
	v_pk_fma_f32 v[34:35], v[226:227], s[16:17], v[34:35] op_sel_hi:[1,0,1]
	v_pk_fma_f32 v[36:37], v[228:229], s[16:17], v[36:37] op_sel_hi:[1,0,1]
	v_pk_fma_f32 v[38:39], v[230:231], s[16:17], v[38:39] op_sel_hi:[1,0,1]
	v_pk_fma_f32 v[40:41], v[232:233], s[16:17], v[40:41] op_sel_hi:[1,0,1]
	v_pk_fma_f32 v[42:43], v[234:235], s[16:17], v[42:43] op_sel_hi:[1,0,1]
	v_pk_fma_f32 v[44:45], v[236:237], s[16:17], v[44:45] op_sel_hi:[1,0,1]
	v_pk_fma_f32 v[46:47], v[238:239], s[16:17], v[46:47] op_sel_hi:[1,0,1]
	v_cvt_pk_f32_fp8_e32 v[224:225], v164
	v_cvt_pk_f32_fp8_sdwa v[226:227], v164 src0_sel:WORD_1
	v_cvt_pk_f32_fp8_e32 v[228:229], v165
	v_cvt_pk_f32_fp8_sdwa v[230:231], v165 src0_sel:WORD_1
	v_cvt_pk_f32_fp8_e32 v[232:233], v166
	v_cvt_pk_f32_fp8_sdwa v[234:235], v166 src0_sel:WORD_1
	v_cvt_pk_f32_fp8_e32 v[236:237], v167
	v_cvt_pk_f32_fp8_sdwa v[238:239], v167 src0_sel:WORD_1
	v_pk_fma_f32 v[32:33], v[224:225], s[18:19], v[32:33] op_sel_hi:[1,0,1]
	v_pk_fma_f32 v[34:35], v[226:227], s[18:19], v[34:35] op_sel_hi:[1,0,1]
	v_pk_fma_f32 v[36:37], v[228:229], s[18:19], v[36:37] op_sel_hi:[1,0,1]
	v_pk_fma_f32 v[38:39], v[230:231], s[18:19], v[38:39] op_sel_hi:[1,0,1]
	v_pk_fma_f32 v[40:41], v[232:233], s[18:19], v[40:41] op_sel_hi:[1,0,1]
	v_pk_fma_f32 v[42:43], v[234:235], s[18:19], v[42:43] op_sel_hi:[1,0,1]
	v_pk_fma_f32 v[44:45], v[236:237], s[18:19], v[44:45] op_sel_hi:[1,0,1]
	v_pk_fma_f32 v[46:47], v[238:239], s[18:19], v[46:47] op_sel_hi:[1,0,1]
	v_cvt_pk_f32_fp8_e32 v[224:225], v168
	v_cvt_pk_f32_fp8_sdwa v[226:227], v168 src0_sel:WORD_1
	v_cvt_pk_f32_fp8_e32 v[228:229], v169
	v_cvt_pk_f32_fp8_sdwa v[230:231], v169 src0_sel:WORD_1
	v_cvt_pk_f32_fp8_e32 v[232:233], v170
	v_cvt_pk_f32_fp8_sdwa v[234:235], v170 src0_sel:WORD_1
	v_cvt_pk_f32_fp8_e32 v[236:237], v171
	v_cvt_pk_f32_fp8_sdwa v[238:239], v171 src0_sel:WORD_1
	v_pk_fma_f32 v[32:33], v[224:225], s[20:21], v[32:33] op_sel_hi:[1,0,1]
	v_pk_fma_f32 v[34:35], v[226:227], s[20:21], v[34:35] op_sel_hi:[1,0,1]
	v_pk_fma_f32 v[36:37], v[228:229], s[20:21], v[36:37] op_sel_hi:[1,0,1]
	v_pk_fma_f32 v[38:39], v[230:231], s[20:21], v[38:39] op_sel_hi:[1,0,1]
	v_pk_fma_f32 v[40:41], v[232:233], s[20:21], v[40:41] op_sel_hi:[1,0,1]
	v_pk_fma_f32 v[42:43], v[234:235], s[20:21], v[42:43] op_sel_hi:[1,0,1]
	v_pk_fma_f32 v[44:45], v[236:237], s[20:21], v[44:45] op_sel_hi:[1,0,1]
	v_pk_fma_f32 v[46:47], v[238:239], s[20:21], v[46:47] op_sel_hi:[1,0,1]
	v_cvt_pk_f32_fp8_e32 v[224:225], v172
	v_cvt_pk_f32_fp8_sdwa v[226:227], v172 src0_sel:WORD_1
	v_cvt_pk_f32_fp8_e32 v[228:229], v173
	v_cvt_pk_f32_fp8_sdwa v[230:231], v173 src0_sel:WORD_1
	v_cvt_pk_f32_fp8_e32 v[232:233], v174
	v_cvt_pk_f32_fp8_sdwa v[234:235], v174 src0_sel:WORD_1
	v_cvt_pk_f32_fp8_e32 v[236:237], v175
	v_cvt_pk_f32_fp8_sdwa v[238:239], v175 src0_sel:WORD_1
	v_pk_fma_f32 v[32:33], v[224:225], s[22:23], v[32:33] op_sel_hi:[1,0,1]
	v_pk_fma_f32 v[34:35], v[226:227], s[22:23], v[34:35] op_sel_hi:[1,0,1]
	v_pk_fma_f32 v[36:37], v[228:229], s[22:23], v[36:37] op_sel_hi:[1,0,1]
	v_pk_fma_f32 v[38:39], v[230:231], s[22:23], v[38:39] op_sel_hi:[1,0,1]
	v_pk_fma_f32 v[40:41], v[232:233], s[22:23], v[40:41] op_sel_hi:[1,0,1]
	v_pk_fma_f32 v[42:43], v[234:235], s[22:23], v[42:43] op_sel_hi:[1,0,1]
	v_pk_fma_f32 v[44:45], v[236:237], s[22:23], v[44:45] op_sel_hi:[1,0,1]
	v_pk_fma_f32 v[46:47], v[238:239], s[22:23], v[46:47] op_sel_hi:[1,0,1]
	v_cvt_pk_f32_fp8_e32 v[224:225], v176
	v_cvt_pk_f32_fp8_sdwa v[226:227], v176 src0_sel:WORD_1
	v_cvt_pk_f32_fp8_e32 v[228:229], v177
	v_cvt_pk_f32_fp8_sdwa v[230:231], v177 src0_sel:WORD_1
	v_cvt_pk_f32_fp8_e32 v[232:233], v178
	v_cvt_pk_f32_fp8_sdwa v[234:235], v178 src0_sel:WORD_1
	v_cvt_pk_f32_fp8_e32 v[236:237], v179
	v_cvt_pk_f32_fp8_sdwa v[238:239], v179 src0_sel:WORD_1
	v_pk_fma_f32 v[32:33], v[224:225], s[24:25], v[32:33] op_sel_hi:[1,0,1]
	v_pk_fma_f32 v[34:35], v[226:227], s[24:25], v[34:35] op_sel_hi:[1,0,1]
	v_pk_fma_f32 v[36:37], v[228:229], s[24:25], v[36:37] op_sel_hi:[1,0,1]
	v_pk_fma_f32 v[38:39], v[230:231], s[24:25], v[38:39] op_sel_hi:[1,0,1]
	v_pk_fma_f32 v[40:41], v[232:233], s[24:25], v[40:41] op_sel_hi:[1,0,1]
	v_pk_fma_f32 v[42:43], v[234:235], s[24:25], v[42:43] op_sel_hi:[1,0,1]
	v_pk_fma_f32 v[44:45], v[236:237], s[24:25], v[44:45] op_sel_hi:[1,0,1]
	v_pk_fma_f32 v[46:47], v[238:239], s[24:25], v[46:47] op_sel_hi:[1,0,1]
	v_cvt_pk_f32_fp8_e32 v[224:225], v180
	v_cvt_pk_f32_fp8_sdwa v[226:227], v180 src0_sel:WORD_1
	v_cvt_pk_f32_fp8_e32 v[228:229], v181
	v_cvt_pk_f32_fp8_sdwa v[230:231], v181 src0_sel:WORD_1
	v_cvt_pk_f32_fp8_e32 v[232:233], v182
	v_cvt_pk_f32_fp8_sdwa v[234:235], v182 src0_sel:WORD_1
	v_cvt_pk_f32_fp8_e32 v[236:237], v183
	v_cvt_pk_f32_fp8_sdwa v[238:239], v183 src0_sel:WORD_1
	v_pk_fma_f32 v[32:33], v[224:225], s[26:27], v[32:33] op_sel_hi:[1,0,1]
	v_pk_fma_f32 v[34:35], v[226:227], s[26:27], v[34:35] op_sel_hi:[1,0,1]
	v_pk_fma_f32 v[36:37], v[228:229], s[26:27], v[36:37] op_sel_hi:[1,0,1]
	v_pk_fma_f32 v[38:39], v[230:231], s[26:27], v[38:39] op_sel_hi:[1,0,1]
	v_pk_fma_f32 v[40:41], v[232:233], s[26:27], v[40:41] op_sel_hi:[1,0,1]
	v_pk_fma_f32 v[42:43], v[234:235], s[26:27], v[42:43] op_sel_hi:[1,0,1]
	v_pk_fma_f32 v[44:45], v[236:237], s[26:27], v[44:45] op_sel_hi:[1,0,1]
	v_pk_fma_f32 v[46:47], v[238:239], s[26:27], v[46:47] op_sel_hi:[1,0,1]
	v_cvt_pk_f32_fp8_e32 v[224:225], v184
	v_cvt_pk_f32_fp8_sdwa v[226:227], v184 src0_sel:WORD_1
	v_cvt_pk_f32_fp8_e32 v[228:229], v185
	v_cvt_pk_f32_fp8_sdwa v[230:231], v185 src0_sel:WORD_1
	v_cvt_pk_f32_fp8_e32 v[232:233], v186
	v_cvt_pk_f32_fp8_sdwa v[234:235], v186 src0_sel:WORD_1
	v_cvt_pk_f32_fp8_e32 v[236:237], v187
	v_cvt_pk_f32_fp8_sdwa v[238:239], v187 src0_sel:WORD_1
	v_pk_fma_f32 v[32:33], v[224:225], s[28:29], v[32:33] op_sel_hi:[1,0,1]
	v_pk_fma_f32 v[34:35], v[226:227], s[28:29], v[34:35] op_sel_hi:[1,0,1]
	v_pk_fma_f32 v[36:37], v[228:229], s[28:29], v[36:37] op_sel_hi:[1,0,1]
	v_pk_fma_f32 v[38:39], v[230:231], s[28:29], v[38:39] op_sel_hi:[1,0,1]
	v_pk_fma_f32 v[40:41], v[232:233], s[28:29], v[40:41] op_sel_hi:[1,0,1]
	v_pk_fma_f32 v[42:43], v[234:235], s[28:29], v[42:43] op_sel_hi:[1,0,1]
	v_pk_fma_f32 v[44:45], v[236:237], s[28:29], v[44:45] op_sel_hi:[1,0,1]
	v_pk_fma_f32 v[46:47], v[238:239], s[28:29], v[46:47] op_sel_hi:[1,0,1]
	v_cvt_pk_f32_fp8_e32 v[224:225], v188
	v_cvt_pk_f32_fp8_sdwa v[226:227], v188 src0_sel:WORD_1
	v_cvt_pk_f32_fp8_e32 v[228:229], v189
	v_cvt_pk_f32_fp8_sdwa v[230:231], v189 src0_sel:WORD_1
	v_cvt_pk_f32_fp8_e32 v[232:233], v190
	v_cvt_pk_f32_fp8_sdwa v[234:235], v190 src0_sel:WORD_1
	v_cvt_pk_f32_fp8_e32 v[236:237], v191
	v_cvt_pk_f32_fp8_sdwa v[238:239], v191 src0_sel:WORD_1
	v_pk_fma_f32 v[32:33], v[224:225], s[30:31], v[32:33] op_sel_hi:[1,0,1]
	v_pk_fma_f32 v[34:35], v[226:227], s[30:31], v[34:35] op_sel_hi:[1,0,1]
	v_pk_fma_f32 v[36:37], v[228:229], s[30:31], v[36:37] op_sel_hi:[1,0,1]
	v_pk_fma_f32 v[38:39], v[230:231], s[30:31], v[38:39] op_sel_hi:[1,0,1]
	v_pk_fma_f32 v[40:41], v[232:233], s[30:31], v[40:41] op_sel_hi:[1,0,1]
	v_pk_fma_f32 v[42:43], v[234:235], s[30:31], v[42:43] op_sel_hi:[1,0,1]
	v_pk_fma_f32 v[44:45], v[236:237], s[30:31], v[44:45] op_sel_hi:[1,0,1]
	v_pk_fma_f32 v[46:47], v[238:239], s[30:31], v[46:47] op_sel_hi:[1,0,1]
	v_readlane_b32 s16, v143, s72
	v_readlane_b32 s18, v143, s73
	v_readlane_b32 s20, v143, s74
	v_readlane_b32 s22, v143, s75
	v_readlane_b32 s24, v143, s76
	v_readlane_b32 s26, v143, s77
	v_readlane_b32 s28, v143, s78
	v_readlane_b32 s30, v143, s79
	s_add_u32 s72, s72, 8
	s_add_u32 s73, s73, 8
	s_add_u32 s74, s74, 8
	s_add_u32 s75, s75, 8
	s_add_u32 s76, s76, 8
	s_add_u32 s77, s77, 8
	s_add_u32 s78, s78, 8
	s_add_u32 s79, s79, 8
	s_and_b32 s72, s72, 63
	s_and_b32 s73, s73, 63
	s_and_b32 s74, s74, 63
	s_and_b32 s75, s75, 63
	s_and_b32 s76, s76, 63
	s_and_b32 s77, s77, 63
	s_and_b32 s78, s78, 63
	s_and_b32 s79, s79, 63
	v_readlane_b32 s48, v128, s72
	v_readlane_b32 s49, v128, s73
	v_readlane_b32 s50, v128, s74
	v_readlane_b32 s51, v128, s75
	v_readlane_b32 s52, v128, s76
	v_readlane_b32 s53, v128, s77
	v_readlane_b32 s54, v128, s78
	v_readlane_b32 s55, v128, s79
	s_add_u32 s32, s0, s48
	s_addc_u32 s33, s1, 0
	s_add_u32 s34, s0, s49
	s_addc_u32 s35, s1, 0
	s_add_u32 s36, s0, s50
	s_addc_u32 s37, s1, 0
	s_add_u32 s38, s0, s51
	s_addc_u32 s39, s1, 0
	s_add_u32 s40, s0, s52
	s_addc_u32 s41, s1, 0
	s_add_u32 s42, s0, s53
	s_addc_u32 s43, s1, 0
	s_add_u32 s44, s0, s54
	s_addc_u32 s45, s1, 0
	s_add_u32 s46, s0, s55
	s_addc_u32 s47, s1, 0
	global_load_dwordx4 v[160:163], v240, s[32:33]
	global_load_dwordx4 v[164:167], v240, s[34:35]
	global_load_dwordx4 v[168:171], v240, s[36:37]
	global_load_dwordx4 v[172:175], v240, s[38:39]
	global_load_dwordx4 v[176:179], v240, s[40:41]
	global_load_dwordx4 v[180:183], v240, s[42:43]
	global_load_dwordx4 v[184:187], v240, s[44:45]
	global_load_dwordx4 v[188:191], v240, s[46:47]
	s_waitcnt vmcnt(8)
	v_cvt_pk_f32_fp8_e32 v[224:225], v192
	v_cvt_pk_f32_fp8_sdwa v[226:227], v192 src0_sel:WORD_1
	v_cvt_pk_f32_fp8_e32 v[228:229], v193
	v_cvt_pk_f32_fp8_sdwa v[230:231], v193 src0_sel:WORD_1
	v_cvt_pk_f32_fp8_e32 v[232:233], v194
	v_cvt_pk_f32_fp8_sdwa v[234:235], v194 src0_sel:WORD_1
	v_cvt_pk_f32_fp8_e32 v[236:237], v195
	v_cvt_pk_f32_fp8_sdwa v[238:239], v195 src0_sel:WORD_1
	v_pk_fma_f32 v[48:49], v[224:225], s[16:17], v[48:49] op_sel_hi:[1,0,1]
	v_pk_fma_f32 v[50:51], v[226:227], s[16:17], v[50:51] op_sel_hi:[1,0,1]
	v_pk_fma_f32 v[52:53], v[228:229], s[16:17], v[52:53] op_sel_hi:[1,0,1]
	v_pk_fma_f32 v[54:55], v[230:231], s[16:17], v[54:55] op_sel_hi:[1,0,1]
	v_pk_fma_f32 v[56:57], v[232:233], s[16:17], v[56:57] op_sel_hi:[1,0,1]
	v_pk_fma_f32 v[58:59], v[234:235], s[16:17], v[58:59] op_sel_hi:[1,0,1]
	v_pk_fma_f32 v[60:61], v[236:237], s[16:17], v[60:61] op_sel_hi:[1,0,1]
	v_pk_fma_f32 v[62:63], v[238:239], s[16:17], v[62:63] op_sel_hi:[1,0,1]
	v_cvt_pk_f32_fp8_e32 v[224:225], v196
	v_cvt_pk_f32_fp8_sdwa v[226:227], v196 src0_sel:WORD_1
	v_cvt_pk_f32_fp8_e32 v[228:229], v197
	v_cvt_pk_f32_fp8_sdwa v[230:231], v197 src0_sel:WORD_1
	v_cvt_pk_f32_fp8_e32 v[232:233], v198
	v_cvt_pk_f32_fp8_sdwa v[234:235], v198 src0_sel:WORD_1
	v_cvt_pk_f32_fp8_e32 v[236:237], v199
	v_cvt_pk_f32_fp8_sdwa v[238:239], v199 src0_sel:WORD_1
	v_pk_fma_f32 v[48:49], v[224:225], s[18:19], v[48:49] op_sel_hi:[1,0,1]
	v_pk_fma_f32 v[50:51], v[226:227], s[18:19], v[50:51] op_sel_hi:[1,0,1]
	v_pk_fma_f32 v[52:53], v[228:229], s[18:19], v[52:53] op_sel_hi:[1,0,1]
	v_pk_fma_f32 v[54:55], v[230:231], s[18:19], v[54:55] op_sel_hi:[1,0,1]
	v_pk_fma_f32 v[56:57], v[232:233], s[18:19], v[56:57] op_sel_hi:[1,0,1]
	v_pk_fma_f32 v[58:59], v[234:235], s[18:19], v[58:59] op_sel_hi:[1,0,1]
	v_pk_fma_f32 v[60:61], v[236:237], s[18:19], v[60:61] op_sel_hi:[1,0,1]
	v_pk_fma_f32 v[62:63], v[238:239], s[18:19], v[62:63] op_sel_hi:[1,0,1]
	v_cvt_pk_f32_fp8_e32 v[224:225], v200
	v_cvt_pk_f32_fp8_sdwa v[226:227], v200 src0_sel:WORD_1
	v_cvt_pk_f32_fp8_e32 v[228:229], v201
	v_cvt_pk_f32_fp8_sdwa v[230:231], v201 src0_sel:WORD_1
	v_cvt_pk_f32_fp8_e32 v[232:233], v202
	v_cvt_pk_f32_fp8_sdwa v[234:235], v202 src0_sel:WORD_1
	v_cvt_pk_f32_fp8_e32 v[236:237], v203
	v_cvt_pk_f32_fp8_sdwa v[238:239], v203 src0_sel:WORD_1
	v_pk_fma_f32 v[48:49], v[224:225], s[20:21], v[48:49] op_sel_hi:[1,0,1]
	v_pk_fma_f32 v[50:51], v[226:227], s[20:21], v[50:51] op_sel_hi:[1,0,1]
	v_pk_fma_f32 v[52:53], v[228:229], s[20:21], v[52:53] op_sel_hi:[1,0,1]
	v_pk_fma_f32 v[54:55], v[230:231], s[20:21], v[54:55] op_sel_hi:[1,0,1]
	v_pk_fma_f32 v[56:57], v[232:233], s[20:21], v[56:57] op_sel_hi:[1,0,1]
	v_pk_fma_f32 v[58:59], v[234:235], s[20:21], v[58:59] op_sel_hi:[1,0,1]
	v_pk_fma_f32 v[60:61], v[236:237], s[20:21], v[60:61] op_sel_hi:[1,0,1]
	v_pk_fma_f32 v[62:63], v[238:239], s[20:21], v[62:63] op_sel_hi:[1,0,1]
	v_cvt_pk_f32_fp8_e32 v[224:225], v204
	v_cvt_pk_f32_fp8_sdwa v[226:227], v204 src0_sel:WORD_1
	v_cvt_pk_f32_fp8_e32 v[228:229], v205
	v_cvt_pk_f32_fp8_sdwa v[230:231], v205 src0_sel:WORD_1
	v_cvt_pk_f32_fp8_e32 v[232:233], v206
	v_cvt_pk_f32_fp8_sdwa v[234:235], v206 src0_sel:WORD_1
	v_cvt_pk_f32_fp8_e32 v[236:237], v207
	v_cvt_pk_f32_fp8_sdwa v[238:239], v207 src0_sel:WORD_1
	v_pk_fma_f32 v[48:49], v[224:225], s[22:23], v[48:49] op_sel_hi:[1,0,1]
	v_pk_fma_f32 v[50:51], v[226:227], s[22:23], v[50:51] op_sel_hi:[1,0,1]
	v_pk_fma_f32 v[52:53], v[228:229], s[22:23], v[52:53] op_sel_hi:[1,0,1]
	v_pk_fma_f32 v[54:55], v[230:231], s[22:23], v[54:55] op_sel_hi:[1,0,1]
	v_pk_fma_f32 v[56:57], v[232:233], s[22:23], v[56:57] op_sel_hi:[1,0,1]
	v_pk_fma_f32 v[58:59], v[234:235], s[22:23], v[58:59] op_sel_hi:[1,0,1]
	v_pk_fma_f32 v[60:61], v[236:237], s[22:23], v[60:61] op_sel_hi:[1,0,1]
	v_pk_fma_f32 v[62:63], v[238:239], s[22:23], v[62:63] op_sel_hi:[1,0,1]
	v_cvt_pk_f32_fp8_e32 v[224:225], v208
	v_cvt_pk_f32_fp8_sdwa v[226:227], v208 src0_sel:WORD_1
	v_cvt_pk_f32_fp8_e32 v[228:229], v209
	v_cvt_pk_f32_fp8_sdwa v[230:231], v209 src0_sel:WORD_1
	v_cvt_pk_f32_fp8_e32 v[232:233], v210
	v_cvt_pk_f32_fp8_sdwa v[234:235], v210 src0_sel:WORD_1
	v_cvt_pk_f32_fp8_e32 v[236:237], v211
	v_cvt_pk_f32_fp8_sdwa v[238:239], v211 src0_sel:WORD_1
; DI void peer_item_v(const Params& p, int item) {
;     ...
;     V_ISSUE(vqa, 0)
; #pragma unroll 1
;     for (int g = 0; g < 16; g += 2) {
;       V_ISSUE(vqb, g + 1)
;       V_CONSUME(vqa, g)
;       if (g + 2 < 16) V_ISSUE(vqa, g + 2)
;       V_CONSUME(vqb, g + 1)
;     }
;     ...
;     float* orow = p.out + tok * 1024 + lane * 4;
;     float4 y[4];
;     float ss = 0.f;
; #pragma unroll
;     for (int i = 0; i < 4; ++i) {
;       y[i] = *(const float4*)(orow + 256 * i);
;       y[i].x += out[4 * i]; y[i].y += out[4 * i + 1]; y[i].z += out[4 * i + 2]; y[i].w += out[4 * i + 3];
;       ss += y[i].x * y[i].x + y[i].y * y[i].y + y[i].z * y[i].z + y[i].w * y[i].w;
;     }
;     ss = wave_sum(ss);
	v_pk_fma_f32 v[48:49], v[224:225], s[24:25], v[48:49] op_sel_hi:[1,0,1]
	v_pk_fma_f32 v[50:51], v[226:227], s[24:25], v[50:51] op_sel_hi:[1,0,1]
	v_pk_fma_f32 v[52:53], v[228:229], s[24:25], v[52:53] op_sel_hi:[1,0,1]
	v_pk_fma_f32 v[54:55], v[230:231], s[24:25], v[54:55] op_sel_hi:[1,0,1]
	v_pk_fma_f32 v[56:57], v[232:233], s[24:25], v[56:57] op_sel_hi:[1,0,1]
	v_pk_fma_f32 v[58:59], v[234:235], s[24:25], v[58:59] op_sel_hi:[1,0,1]
	v_pk_fma_f32 v[60:61], v[236:237], s[24:25], v[60:61] op_sel_hi:[1,0,1]
	v_pk_fma_f32 v[62:63], v[238:239], s[24:25], v[62:63] op_sel_hi:[1,0,1]
	v_cvt_pk_f32_fp8_e32 v[224:225], v212
	v_cvt_pk_f32_fp8_sdwa v[226:227], v212 src0_sel:WORD_1
	v_cvt_pk_f32_fp8_e32 v[228:229], v213
	v_cvt_pk_f32_fp8_sdwa v[230:231], v213 src0_sel:WORD_1
	v_cvt_pk_f32_fp8_e32 v[232:233], v214
	v_cvt_pk_f32_fp8_sdwa v[234:235], v214 src0_sel:WORD_1
	v_cvt_pk_f32_fp8_e32 v[236:237], v215
	v_cvt_pk_f32_fp8_sdwa v[238:239], v215 src0_sel:WORD_1
	v_pk_fma_f32 v[48:49], v[224:225], s[26:27], v[48:49] op_sel_hi:[1,0,1]
	v_pk_fma_f32 v[50:51], v[226:227], s[26:27], v[50:51] op_sel_hi:[1,0,1]
	v_pk_fma_f32 v[52:53], v[228:229], s[26:27], v[52:53] op_sel_hi:[1,0,1]
	v_pk_fma_f32 v[54:55], v[230:231], s[26:27], v[54:55] op_sel_hi:[1,0,1]
	v_pk_fma_f32 v[56:57], v[232:233], s[26:27], v[56:57] op_sel_hi:[1,0,1]
	v_pk_fma_f32 v[58:59], v[234:235], s[26:27], v[58:59] op_sel_hi:[1,0,1]
	v_pk_fma_f32 v[60:61], v[236:237], s[26:27], v[60:61] op_sel_hi:[1,0,1]
	v_pk_fma_f32 v[62:63], v[238:239], s[26:27], v[62:63] op_sel_hi:[1,0,1]
	v_cvt_pk_f32_fp8_e32 v[224:225], v216
	v_cvt_pk_f32_fp8_sdwa v[226:227], v216 src0_sel:WORD_1
	v_cvt_pk_f32_fp8_e32 v[228:229], v217
	v_cvt_pk_f32_fp8_sdwa v[230:231], v217 src0_sel:WORD_1
	v_cvt_pk_f32_fp8_e32 v[232:233], v218
	v_cvt_pk_f32_fp8_sdwa v[234:235], v218 src0_sel:WORD_1
	v_cvt_pk_f32_fp8_e32 v[236:237], v219
	v_cvt_pk_f32_fp8_sdwa v[238:239], v219 src0_sel:WORD_1
	v_pk_fma_f32 v[48:49], v[224:225], s[28:29], v[48:49] op_sel_hi:[1,0,1]
	v_pk_fma_f32 v[50:51], v[226:227], s[28:29], v[50:51] op_sel_hi:[1,0,1]
	v_pk_fma_f32 v[52:53], v[228:229], s[28:29], v[52:53] op_sel_hi:[1,0,1]
	v_pk_fma_f32 v[54:55], v[230:231], s[28:29], v[54:55] op_sel_hi:[1,0,1]
	v_pk_fma_f32 v[56:57], v[232:233], s[28:29], v[56:57] op_sel_hi:[1,0,1]
	v_pk_fma_f32 v[58:59], v[234:235], s[28:29], v[58:59] op_sel_hi:[1,0,1]
	v_pk_fma_f32 v[60:61], v[236:237], s[28:29], v[60:61] op_sel_hi:[1,0,1]
	v_pk_fma_f32 v[62:63], v[238:239], s[28:29], v[62:63] op_sel_hi:[1,0,1]
	v_cvt_pk_f32_fp8_e32 v[224:225], v220
	v_cvt_pk_f32_fp8_sdwa v[226:227], v220 src0_sel:WORD_1
	v_cvt_pk_f32_fp8_e32 v[228:229], v221
	v_cvt_pk_f32_fp8_sdwa v[230:231], v221 src0_sel:WORD_1
	v_cvt_pk_f32_fp8_e32 v[232:233], v222
	v_cvt_pk_f32_fp8_sdwa v[234:235], v222 src0_sel:WORD_1
	v_cvt_pk_f32_fp8_e32 v[236:237], v223
	v_cvt_pk_f32_fp8_sdwa v[238:239], v223 src0_sel:WORD_1
	v_pk_fma_f32 v[48:49], v[224:225], s[30:31], v[48:49] op_sel_hi:[1,0,1]
	v_pk_fma_f32 v[50:51], v[226:227], s[30:31], v[50:51] op_sel_hi:[1,0,1]
	v_pk_fma_f32 v[52:53], v[228:229], s[30:31], v[52:53] op_sel_hi:[1,0,1]
	v_pk_fma_f32 v[54:55], v[230:231], s[30:31], v[54:55] op_sel_hi:[1,0,1]
	v_pk_fma_f32 v[56:57], v[232:233], s[30:31], v[56:57] op_sel_hi:[1,0,1]
	v_pk_fma_f32 v[58:59], v[234:235], s[30:31], v[58:59] op_sel_hi:[1,0,1]
	v_pk_fma_f32 v[60:61], v[236:237], s[30:31], v[60:61] op_sel_hi:[1,0,1]
	v_pk_fma_f32 v[62:63], v[238:239], s[30:31], v[62:63] op_sel_hi:[1,0,1]
	s_add_u32 s12, s12, 1
	s_cmp_lt_u32 s12, 8
	s_cbranch_scc1 .Lvq_kA
	s_waitcnt vmcnt(0)
	global_load_dwordx4 v[128:131], v240, s[8:9]
	global_load_dwordx4 v[132:135], v240, s[8:9] offset:1024
	global_load_dwordx4 v[136:139], v240, s[8:9] offset:2048
	global_load_dwordx4 v[140:143], v240, s[8:9] offset:3072
	s_add_u32 s32, s62, 0
	s_addc_u32 s33, s63, 0
	s_add_u32 s34, s62, 4096
	s_addc_u32 s35, s63, 0
	s_add_u32 s36, s62, 8192
	s_addc_u32 s37, s63, 0
	s_add_u32 s38, s62, 12288
	s_addc_u32 s39, s63, 0
	s_waitcnt vmcnt(0)
	v_pk_add_f32 v[64:65], v[64:65], v[0:1]
	v_pk_add_f32 v[66:67], v[66:67], v[2:3]
	v_pk_add_f32 v[68:69], v[68:69], v[4:5]
	v_pk_add_f32 v[70:71], v[70:71], v[6:7]
	v_pk_add_f32 v[72:73], v[72:73], v[8:9]
	v_pk_add_f32 v[74:75], v[74:75], v[10:11]
	v_pk_add_f32 v[76:77], v[76:77], v[12:13]
	v_pk_add_f32 v[78:79], v[78:79], v[14:15]
	v_pk_mul_f32 v[224:225], v[64:65], v[64:65]
	v_pk_mul_f32 v[226:227], v[66:67], v[66:67]
	v_pk_fma_f32 v[224:225], v[68:69], v[68:69], v[224:225]
	v_pk_fma_f32 v[226:227], v[70:71], v[70:71], v[226:227]
	v_pk_fma_f32 v[224:225], v[72:73], v[72:73], v[224:225]
	v_pk_fma_f32 v[226:227], v[74:75], v[74:75], v[226:227]
	v_pk_fma_f32 v[224:225], v[76:77], v[76:77], v[224:225]
	v_pk_fma_f32 v[226:227], v[78:79], v[78:79], v[226:227]
	v_pk_add_f32 v[224:225], v[224:225], v[226:227]
	s_nop 0
	v_add_f32_e32 v224, v224, v225
	ds_bpermute_b32 v225, v242, v224
	s_waitcnt lgkmcnt(0)
	v_add_f32_e32 v224, v224, v225
	ds_bpermute_b32 v225, v243, v224
	s_waitcnt lgkmcnt(0)
	v_add_f32_e32 v224, v224, v225
	ds_bpermute_b32 v225, v244, v224
	s_waitcnt lgkmcnt(0)
	v_add_f32_e32 v224, v224, v225
	ds_bpermute_b32 v225, v245, v224
	s_waitcnt lgkmcnt(0)
	v_add_f32_e32 v224, v224, v225
	ds_bpermute_b32 v225, v246, v224
	s_waitcnt lgkmcnt(0)
	v_add_f32_e32 v224, v224, v225
	ds_bpermute_b32 v225, v247, v224
	s_waitcnt lgkmcnt(0)
; DI void peer_item_v(const Params& p, int item) {
;     ...
;     ss = wave_sum(ss);
;     const float r = rsqrtf(ss * (1.f / 1024.f) + 1e-6f);
; #pragma unroll
;     for (int i = 0; i < 4; ++i) {
;       float4 g = *(const float4*)(p.g_final + 256 * i + lane * 4);
;       y[i].x *= r * g.x; y[i].y *= r * g.y; y[i].z *= r * g.z; y[i].w *= r * g.w;
;       *(float4*)(orow + 256 * i) = y[i];
	v_add_f32_e32 v224, v224, v225
	v_fmamk_f32 v224, v224, 0x3a800000, v248
	v_rsq_f32_e32 v224, v224
	s_nop 1
	v_pk_mul_f32 v[226:227], v[128:129], v[224:225] op_sel_hi:[1,0]
	v_pk_mul_f32 v[64:65], v[64:65], v[226:227]
	v_pk_mul_f32 v[228:229], v[130:131], v[224:225] op_sel_hi:[1,0]
	v_pk_mul_f32 v[66:67], v[66:67], v[228:229]
	v_pk_mul_f32 v[230:231], v[132:133], v[224:225] op_sel_hi:[1,0]
	v_pk_mul_f32 v[68:69], v[68:69], v[230:231]
	v_pk_mul_f32 v[232:233], v[134:135], v[224:225] op_sel_hi:[1,0]
	v_pk_mul_f32 v[70:71], v[70:71], v[232:233]
	v_pk_mul_f32 v[226:227], v[136:137], v[224:225] op_sel_hi:[1,0]
	v_pk_mul_f32 v[72:73], v[72:73], v[226:227]
	v_pk_mul_f32 v[228:229], v[138:139], v[224:225] op_sel_hi:[1,0]
	v_pk_mul_f32 v[74:75], v[74:75], v[228:229]
	v_pk_mul_f32 v[230:231], v[140:141], v[224:225] op_sel_hi:[1,0]
	v_pk_mul_f32 v[76:77], v[76:77], v[230:231]
	v_pk_mul_f32 v[232:233], v[142:143], v[224:225] op_sel_hi:[1,0]
	v_pk_mul_f32 v[78:79], v[78:79], v[232:233]
	v_pk_add_f32 v[80:81], v[80:81], v[16:17]
	v_pk_add_f32 v[82:83], v[82:83], v[18:19]
	v_pk_add_f32 v[84:85], v[84:85], v[20:21]
	v_pk_add_f32 v[86:87], v[86:87], v[22:23]
	v_pk_add_f32 v[88:89], v[88:89], v[24:25]
	v_pk_add_f32 v[90:91], v[90:91], v[26:27]
	v_pk_add_f32 v[92:93], v[92:93], v[28:29]
	v_pk_add_f32 v[94:95], v[94:95], v[30:31]
	v_pk_mul_f32 v[224:225], v[80:81], v[80:81]
	v_pk_mul_f32 v[226:227], v[82:83], v[82:83]
	v_pk_fma_f32 v[224:225], v[84:85], v[84:85], v[224:225]
	v_pk_fma_f32 v[226:227], v[86:87], v[86:87], v[226:227]
	v_pk_fma_f32 v[224:225], v[88:89], v[88:89], v[224:225]
	v_pk_fma_f32 v[226:227], v[90:91], v[90:91], v[226:227]
	v_pk_fma_f32 v[224:225], v[92:93], v[92:93], v[224:225]
	v_pk_fma_f32 v[226:227], v[94:95], v[94:95], v[226:227]
	v_pk_add_f32 v[224:225], v[224:225], v[226:227]
	s_nop 0
	v_add_f32_e32 v224, v224, v225
	ds_bpermute_b32 v225, v242, v224
	s_waitcnt lgkmcnt(0)
	v_add_f32_e32 v224, v224, v225
	ds_bpermute_b32 v225, v243, v224
	s_waitcnt lgkmcnt(0)
	v_add_f32_e32 v224, v224, v225
	ds_bpermute_b32 v225, v244, v224
	s_waitcnt lgkmcnt(0)
	v_add_f32_e32 v224, v224, v225
	ds_bpermute_b32 v225, v245, v224
	s_waitcnt lgkmcnt(0)
	v_add_f32_e32 v224, v224, v225
	ds_bpermute_b32 v225, v246, v224
	s_waitcnt lgkmcnt(0)
	v_add_f32_e32 v224, v224, v225
	ds_bpermute_b32 v225, v247, v224
	s_waitcnt lgkmcnt(0)
	v_add_f32_e32 v224, v224, v225
	v_fmamk_f32 v224, v224, 0x3a800000, v248
	v_rsq_f32_e32 v224, v224
	s_nop 1
	v_pk_mul_f32 v[226:227], v[128:129], v[224:225] op_sel_hi:[1,0]
	v_pk_mul_f32 v[80:81], v[80:81], v[226:227]
	v_pk_mul_f32 v[228:229], v[130:131], v[224:225] op_sel_hi:[1,0]
	v_pk_mul_f32 v[82:83], v[82:83], v[228:229]
	v_pk_mul_f32 v[230:231], v[132:133], v[224:225] op_sel_hi:[1,0]
	v_pk_mul_f32 v[84:85], v[84:85], v[230:231]
	v_pk_mul_f32 v[232:233], v[134:135], v[224:225] op_sel_hi:[1,0]
	v_pk_mul_f32 v[86:87], v[86:87], v[232:233]
	v_pk_mul_f32 v[226:227], v[136:137], v[224:225] op_sel_hi:[1,0]
	v_pk_mul_f32 v[88:89], v[88:89], v[226:227]
	v_pk_mul_f32 v[228:229], v[138:139], v[224:225] op_sel_hi:[1,0]
	v_pk_mul_f32 v[90:91], v[90:91], v[228:229]
	v_pk_mul_f32 v[230:231], v[140:141], v[224:225] op_sel_hi:[1,0]
	v_pk_mul_f32 v[92:93], v[92:93], v[230:231]
	v_pk_mul_f32 v[232:233], v[142:143], v[224:225] op_sel_hi:[1,0]
	v_pk_mul_f32 v[94:95], v[94:95], v[232:233]
	v_pk_add_f32 v[96:97], v[96:97], v[32:33]
	v_pk_add_f32 v[98:99], v[98:99], v[34:35]
	v_pk_add_f32 v[100:101], v[100:101], v[36:37]
	v_pk_add_f32 v[102:103], v[102:103], v[38:39]
	v_pk_add_f32 v[104:105], v[104:105], v[40:41]
	v_pk_add_f32 v[106:107], v[106:107], v[42:43]
	v_pk_add_f32 v[108:109], v[108:109], v[44:45]
	v_pk_add_f32 v[110:111], v[110:111], v[46:47]
	v_pk_mul_f32 v[224:225], v[96:97], v[96:97]
	v_pk_mul_f32 v[226:227], v[98:99], v[98:99]
	v_pk_fma_f32 v[224:225], v[100:101], v[100:101], v[224:225]
	v_pk_fma_f32 v[226:227], v[102:103], v[102:103], v[226:227]
	v_pk_fma_f32 v[224:225], v[104:105], v[104:105], v[224:225]
	v_pk_fma_f32 v[226:227], v[106:107], v[106:107], v[226:227]
	v_pk_fma_f32 v[224:225], v[108:109], v[108:109], v[224:225]
	v_pk_fma_f32 v[226:227], v[110:111], v[110:111], v[226:227]
	v_pk_add_f32 v[224:225], v[224:225], v[226:227]
	s_nop 0
	v_add_f32_e32 v224, v224, v225
	ds_bpermute_b32 v225, v242, v224
	s_waitcnt lgkmcnt(0)
	v_add_f32_e32 v224, v224, v225
	ds_bpermute_b32 v225, v243, v224
	s_waitcnt lgkmcnt(0)
	v_add_f32_e32 v224, v224, v225
	ds_bpermute_b32 v225, v244, v224
	s_waitcnt lgkmcnt(0)
	v_add_f32_e32 v224, v224, v225
	ds_bpermute_b32 v225, v245, v224
	s_waitcnt lgkmcnt(0)
	v_add_f32_e32 v224, v224, v225
	ds_bpermute_b32 v225, v246, v224
	s_waitcnt lgkmcnt(0)
	v_add_f32_e32 v224, v224, v225
	ds_bpermute_b32 v225, v247, v224
	s_waitcnt lgkmcnt(0)
; DI void peer_item_v(const Params& p, int item) {
;     ...
;     float out[16];
; #pragma unroll
;     for (int i = 0; i < 16; ++i) out[i] = 0.f;
;     ...
;     const float r = rsqrtf(ss * (1.f / 1024.f) + 1e-6f);
; #pragma unroll
;     for (int i = 0; i < 4; ++i) {
;       float4 g = *(const float4*)(p.g_final + 256 * i + lane * 4);
;       y[i].x *= r * g.x; y[i].y *= r * g.y; y[i].z *= r * g.z; y[i].w *= r * g.w;
;       *(float4*)(orow + 256 * i) = y[i];
	v_add_f32_e32 v224, v224, v225
	v_fmamk_f32 v224, v224, 0x3a800000, v248
	v_rsq_f32_e32 v224, v224
	s_nop 1
	v_pk_mul_f32 v[226:227], v[128:129], v[224:225] op_sel_hi:[1,0]
	v_pk_mul_f32 v[96:97], v[96:97], v[226:227]
	v_pk_mul_f32 v[228:229], v[130:131], v[224:225] op_sel_hi:[1,0]
	v_pk_mul_f32 v[98:99], v[98:99], v[228:229]
	v_pk_mul_f32 v[230:231], v[132:133], v[224:225] op_sel_hi:[1,0]
	v_pk_mul_f32 v[100:101], v[100:101], v[230:231]
	v_pk_mul_f32 v[232:233], v[134:135], v[224:225] op_sel_hi:[1,0]
	v_pk_mul_f32 v[102:103], v[102:103], v[232:233]
	v_pk_mul_f32 v[226:227], v[136:137], v[224:225] op_sel_hi:[1,0]
	v_pk_mul_f32 v[104:105], v[104:105], v[226:227]
	v_pk_mul_f32 v[228:229], v[138:139], v[224:225] op_sel_hi:[1,0]
	v_pk_mul_f32 v[106:107], v[106:107], v[228:229]
	v_pk_mul_f32 v[230:231], v[140:141], v[224:225] op_sel_hi:[1,0]
	v_pk_mul_f32 v[108:109], v[108:109], v[230:231]
	v_pk_mul_f32 v[232:233], v[142:143], v[224:225] op_sel_hi:[1,0]
	v_pk_mul_f32 v[110:111], v[110:111], v[232:233]
	v_pk_add_f32 v[112:113], v[112:113], v[48:49]
	v_pk_add_f32 v[114:115], v[114:115], v[50:51]
	v_pk_add_f32 v[116:117], v[116:117], v[52:53]
	v_pk_add_f32 v[118:119], v[118:119], v[54:55]
	v_pk_add_f32 v[120:121], v[120:121], v[56:57]
	v_pk_add_f32 v[122:123], v[122:123], v[58:59]
	v_pk_add_f32 v[124:125], v[124:125], v[60:61]
	v_pk_add_f32 v[126:127], v[126:127], v[62:63]
	v_pk_mul_f32 v[224:225], v[112:113], v[112:113]
	v_pk_mul_f32 v[226:227], v[114:115], v[114:115]
	v_pk_fma_f32 v[224:225], v[116:117], v[116:117], v[224:225]
	v_pk_fma_f32 v[226:227], v[118:119], v[118:119], v[226:227]
	v_pk_fma_f32 v[224:225], v[120:121], v[120:121], v[224:225]
	v_pk_fma_f32 v[226:227], v[122:123], v[122:123], v[226:227]
	v_pk_fma_f32 v[224:225], v[124:125], v[124:125], v[224:225]
	v_pk_fma_f32 v[226:227], v[126:127], v[126:127], v[226:227]
	v_pk_add_f32 v[224:225], v[224:225], v[226:227]
	s_nop 0
	v_add_f32_e32 v224, v224, v225
	ds_bpermute_b32 v225, v242, v224
	s_waitcnt lgkmcnt(0)
	v_add_f32_e32 v224, v224, v225
	ds_bpermute_b32 v225, v243, v224
	s_waitcnt lgkmcnt(0)
	v_add_f32_e32 v224, v224, v225
	ds_bpermute_b32 v225, v244, v224
	s_waitcnt lgkmcnt(0)
	v_add_f32_e32 v224, v224, v225
	ds_bpermute_b32 v225, v245, v224
	s_waitcnt lgkmcnt(0)
	v_add_f32_e32 v224, v224, v225
	ds_bpermute_b32 v225, v246, v224
	s_waitcnt lgkmcnt(0)
	v_add_f32_e32 v224, v224, v225
	ds_bpermute_b32 v225, v247, v224
	s_waitcnt lgkmcnt(0)
	v_add_f32_e32 v224, v224, v225
	v_fmamk_f32 v224, v224, 0x3a800000, v248
	v_rsq_f32_e32 v224, v224
	s_nop 1
	v_pk_mul_f32 v[226:227], v[128:129], v[224:225] op_sel_hi:[1,0]
	v_pk_mul_f32 v[112:113], v[112:113], v[226:227]
	v_pk_mul_f32 v[228:229], v[130:131], v[224:225] op_sel_hi:[1,0]
	v_pk_mul_f32 v[114:115], v[114:115], v[228:229]
	v_pk_mul_f32 v[230:231], v[132:133], v[224:225] op_sel_hi:[1,0]
	v_pk_mul_f32 v[116:117], v[116:117], v[230:231]
	v_pk_mul_f32 v[232:233], v[134:135], v[224:225] op_sel_hi:[1,0]
	v_pk_mul_f32 v[118:119], v[118:119], v[232:233]
	v_pk_mul_f32 v[226:227], v[136:137], v[224:225] op_sel_hi:[1,0]
	v_pk_mul_f32 v[120:121], v[120:121], v[226:227]
	v_pk_mul_f32 v[228:229], v[138:139], v[224:225] op_sel_hi:[1,0]
	v_pk_mul_f32 v[122:123], v[122:123], v[228:229]
	v_pk_mul_f32 v[230:231], v[140:141], v[224:225] op_sel_hi:[1,0]
	v_pk_mul_f32 v[124:125], v[124:125], v[230:231]
	v_pk_mul_f32 v[232:233], v[142:143], v[224:225] op_sel_hi:[1,0]
	v_pk_mul_f32 v[126:127], v[126:127], v[232:233]
	global_store_dwordx4 v240, v[64:67], s[32:33] nt
	global_store_dwordx4 v240, v[68:71], s[32:33] offset:1024 nt
	global_store_dwordx4 v240, v[72:75], s[32:33] offset:2048 nt
	global_store_dwordx4 v240, v[76:79], s[32:33] offset:3072 nt
	global_store_dwordx4 v240, v[80:83], s[34:35] nt
	global_store_dwordx4 v240, v[84:87], s[34:35] offset:1024 nt
	global_store_dwordx4 v240, v[88:91], s[34:35] offset:2048 nt
	global_store_dwordx4 v240, v[92:95], s[34:35] offset:3072 nt
	global_store_dwordx4 v240, v[96:99], s[36:37] nt
	global_store_dwordx4 v240, v[100:103], s[36:37] offset:1024 nt
	global_store_dwordx4 v240, v[104:107], s[36:37] offset:2048 nt
	global_store_dwordx4 v240, v[108:111], s[36:37] offset:3072 nt
	global_store_dwordx4 v240, v[112:115], s[38:39] nt
	global_store_dwordx4 v240, v[116:119], s[38:39] offset:1024 nt
	global_store_dwordx4 v240, v[120:123], s[38:39] offset:2048 nt
	global_store_dwordx4 v240, v[124:127], s[38:39] offset:3072 nt
	s_nop 1
	v_mov_b32_e32 v64, 0
	v_mov_b32_e32 v65, 0
	v_mov_b32_e32 v66, 0
	v_mov_b32_e32 v67, 0
	v_mov_b32_e32 v68, 0
	v_mov_b32_e32 v69, 0
	v_mov_b32_e32 v70, 0
	v_mov_b32_e32 v71, 0
	v_mov_b32_e32 v72, 0
	v_mov_b32_e32 v73, 0
	v_mov_b32_e32 v74, 0
	v_mov_b32_e32 v75, 0
	v_mov_b32_e32 v76, 0
	v_mov_b32_e32 v77, 0
	v_mov_b32_e32 v78, 0
	v_mov_b32_e32 v79, 0
	v_mov_b32_e32 v80, 0
	v_mov_b32_e32 v81, 0
	v_mov_b32_e32 v82, 0
	v_mov_b32_e32 v83, 0
	v_mov_b32_e32 v84, 0
	v_mov_b32_e32 v85, 0
	v_mov_b32_e32 v86, 0
	v_mov_b32_e32 v87, 0
	v_mov_b32_e32 v88, 0
	v_mov_b32_e32 v89, 0
	v_mov_b32_e32 v90, 0
	v_mov_b32_e32 v91, 0
	v_mov_b32_e32 v92, 0
	v_mov_b32_e32 v93, 0
	v_mov_b32_e32 v94, 0
	v_mov_b32_e32 v95, 0
	v_mov_b32_e32 v96, 0
	v_mov_b32_e32 v97, 0
	v_mov_b32_e32 v98, 0
	v_mov_b32_e32 v99, 0
	v_mov_b32_e32 v100, 0
	v_mov_b32_e32 v101, 0
	v_mov_b32_e32 v102, 0
	v_mov_b32_e32 v103, 0
	v_mov_b32_e32 v104, 0
	v_mov_b32_e32 v105, 0
	v_mov_b32_e32 v106, 0
	v_mov_b32_e32 v107, 0
	v_mov_b32_e32 v108, 0
	v_mov_b32_e32 v109, 0
	v_mov_b32_e32 v110, 0
	v_mov_b32_e32 v111, 0
	v_mov_b32_e32 v112, 0
	v_mov_b32_e32 v113, 0
	v_mov_b32_e32 v114, 0
	v_mov_b32_e32 v115, 0
	v_mov_b32_e32 v116, 0
	v_mov_b32_e32 v117, 0
; DI void peer_item_v(const Params& p, int item) {
;     ...
; #pragma unroll 1
;   for (int ti = 0; ti < 8; ++ti) {
;     const size_t tok = (size_t)item * 32 + wave * 8 + ti;
;     const int e_lo = EG[tok * 128 + lane], e_hi = EG[tok * 128 + 64 + lane];
;     const int a_lo = __float_as_int(AG[tok * 128 + lane]), a_hi = __float_as_int(AG[tok * 128 + 64 + lane]);
;     float out[16];
; #pragma unroll
;     for (int i = 0; i < 16; ++i) out[i] = 0.f;
;     u32x4 vqa[8], vqb[8];
;     ...
;     float* orow = p.out + tok * 1024 + lane * 4;
;     float4 y[4];
;     float ss = 0.f;
; #pragma unroll
;     for (int i = 0; i < 4; ++i) {
;       y[i] = *(const float4*)(orow + 256 * i);
;       y[i].x += out[4 * i]; y[i].y += out[4 * i + 1]; y[i].z += out[4 * i + 2]; y[i].w += out[4 * i + 3];
	v_mov_b32_e32 v118, 0
	v_mov_b32_e32 v119, 0
	v_mov_b32_e32 v120, 0
	v_mov_b32_e32 v121, 0
	v_mov_b32_e32 v122, 0
	v_mov_b32_e32 v123, 0
	v_mov_b32_e32 v124, 0
	v_mov_b32_e32 v125, 0
	v_mov_b32_e32 v126, 0
	v_mov_b32_e32 v127, 0
	s_add_u32 s32, s62, 16384
	s_addc_u32 s33, s63, 0
	s_add_u32 s34, s62, 20480
	s_addc_u32 s35, s63, 0
	s_add_u32 s36, s62, 24576
	s_addc_u32 s37, s63, 0
	s_add_u32 s38, s62, 28672
	s_addc_u32 s39, s63, 0
	global_load_dwordx4 v[0:3], v240, s[32:33] nt
	global_load_dwordx4 v[4:7], v240, s[32:33] offset:1024 nt
	global_load_dwordx4 v[8:11], v240, s[32:33] offset:2048 nt
	global_load_dwordx4 v[12:15], v240, s[32:33] offset:3072 nt
	global_load_dwordx4 v[16:19], v240, s[34:35] nt
	global_load_dwordx4 v[20:23], v240, s[34:35] offset:1024 nt
	global_load_dwordx4 v[24:27], v240, s[34:35] offset:2048 nt
	global_load_dwordx4 v[28:31], v240, s[34:35] offset:3072 nt
	global_load_dwordx4 v[32:35], v240, s[36:37] nt
	global_load_dwordx4 v[36:39], v240, s[36:37] offset:1024 nt
	global_load_dwordx4 v[40:43], v240, s[36:37] offset:2048 nt
	global_load_dwordx4 v[44:47], v240, s[36:37] offset:3072 nt
	global_load_dwordx4 v[48:51], v240, s[38:39] nt
	global_load_dwordx4 v[52:55], v240, s[38:39] offset:1024 nt
	global_load_dwordx4 v[56:59], v240, s[38:39] offset:2048 nt
	global_load_dwordx4 v[60:63], v240, s[38:39] offset:3072 nt
	s_mov_b32 s72, 0
	s_mov_b32 s73, 1
	s_mov_b32 s74, 2
	s_mov_b32 s75, 3
	s_mov_b32 s76, 4
	s_mov_b32 s77, 5
	s_mov_b32 s78, 6
	s_mov_b32 s79, 7
	s_nop 0
	v_readlane_b32 s48, v144, s72
	v_readlane_b32 s49, v144, s73
	v_readlane_b32 s50, v144, s74
	v_readlane_b32 s51, v144, s75
	v_readlane_b32 s52, v144, s76
	v_readlane_b32 s53, v144, s77
	v_readlane_b32 s54, v144, s78
	v_readlane_b32 s55, v144, s79
	s_add_u32 s32, s0, s48
	s_addc_u32 s33, s1, 0
	s_add_u32 s34, s0, s49
	s_addc_u32 s35, s1, 0
	s_add_u32 s36, s0, s50
	s_addc_u32 s37, s1, 0
	s_add_u32 s38, s0, s51
	s_addc_u32 s39, s1, 0
	s_add_u32 s40, s0, s52
	s_addc_u32 s41, s1, 0
	s_add_u32 s42, s0, s53
	s_addc_u32 s43, s1, 0
	s_add_u32 s44, s0, s54
	s_addc_u32 s45, s1, 0
	s_add_u32 s46, s0, s55
	s_addc_u32 s47, s1, 0
	global_load_dwordx4 v[160:163], v240, s[32:33]
	global_load_dwordx4 v[164:167], v240, s[34:35]
	global_load_dwordx4 v[168:171], v240, s[36:37]
	global_load_dwordx4 v[172:175], v240, s[38:39]
	global_load_dwordx4 v[176:179], v240, s[40:41]
	global_load_dwordx4 v[180:183], v240, s[42:43]
	global_load_dwordx4 v[184:187], v240, s[44:45]
	global_load_dwordx4 v[188:191], v240, s[46:47]
	s_mov_b32 s12, 0
.Lvq_kB:
	v_readlane_b32 s16, v146, s72
	v_readlane_b32 s18, v146, s73
	v_readlane_b32 s20, v146, s74
	v_readlane_b32 s22, v146, s75
	v_readlane_b32 s24, v146, s76
	v_readlane_b32 s26, v146, s77
	v_readlane_b32 s28, v146, s78
	v_readlane_b32 s30, v146, s79
	v_readlane_b32 s48, v148, s72
	v_readlane_b32 s49, v148, s73
	v_readlane_b32 s50, v148, s74
	v_readlane_b32 s51, v148, s75
	v_readlane_b32 s52, v148, s76
	v_readlane_b32 s53, v148, s77
	v_readlane_b32 s54, v148, s78
	v_readlane_b32 s55, v148, s79
	s_add_u32 s32, s0, s48
	s_addc_u32 s33, s1, 0
	s_add_u32 s34, s0, s49
	s_addc_u32 s35, s1, 0
	s_add_u32 s36, s0, s50
	s_addc_u32 s37, s1, 0
	s_add_u32 s38, s0, s51
	s_addc_u32 s39, s1, 0
	s_add_u32 s40, s0, s52
	s_addc_u32 s41, s1, 0
	s_add_u32 s42, s0, s53
	s_addc_u32 s43, s1, 0
	s_add_u32 s44, s0, s54
	s_addc_u32 s45, s1, 0
	s_add_u32 s46, s0, s55
	s_addc_u32 s47, s1, 0
	global_load_dwordx4 v[192:195], v240, s[32:33]
	global_load_dwordx4 v[196:199], v240, s[34:35]
	global_load_dwordx4 v[200:203], v240, s[36:37]
	global_load_dwordx4 v[204:207], v240, s[38:39]
	global_load_dwordx4 v[208:211], v240, s[40:41]
	global_load_dwordx4 v[212:215], v240, s[42:43]
	global_load_dwordx4 v[216:219], v240, s[44:45]
	global_load_dwordx4 v[220:223], v240, s[46:47]
	s_waitcnt vmcnt(8)
	v_cvt_pk_f32_fp8_e32 v[224:225], v160
	v_cvt_pk_f32_fp8_sdwa v[226:227], v160 src0_sel:WORD_1
	v_cvt_pk_f32_fp8_e32 v[228:229], v161
	v_cvt_pk_f32_fp8_sdwa v[230:231], v161 src0_sel:WORD_1
	v_cvt_pk_f32_fp8_e32 v[232:233], v162
	v_cvt_pk_f32_fp8_sdwa v[234:235], v162 src0_sel:WORD_1
	v_cvt_pk_f32_fp8_e32 v[236:237], v163
	v_cvt_pk_f32_fp8_sdwa v[238:239], v163 src0_sel:WORD_1
	v_pk_fma_f32 v[64:65], v[224:225], s[16:17], v[64:65] op_sel_hi:[1,0,1]
	v_pk_fma_f32 v[66:67], v[226:227], s[16:17], v[66:67] op_sel_hi:[1,0,1]
	v_pk_fma_f32 v[68:69], v[228:229], s[16:17], v[68:69] op_sel_hi:[1,0,1]
	v_pk_fma_f32 v[70:71], v[230:231], s[16:17], v[70:71] op_sel_hi:[1,0,1]
	v_pk_fma_f32 v[72:73], v[232:233], s[16:17], v[72:73] op_sel_hi:[1,0,1]
	v_pk_fma_f32 v[74:75], v[234:235], s[16:17], v[74:75] op_sel_hi:[1,0,1]
	v_pk_fma_f32 v[76:77], v[236:237], s[16:17], v[76:77] op_sel_hi:[1,0,1]
	v_pk_fma_f32 v[78:79], v[238:239], s[16:17], v[78:79] op_sel_hi:[1,0,1]
	v_cvt_pk_f32_fp8_e32 v[224:225], v164
	v_cvt_pk_f32_fp8_sdwa v[226:227], v164 src0_sel:WORD_1
	v_cvt_pk_f32_fp8_e32 v[228:229], v165
	v_cvt_pk_f32_fp8_sdwa v[230:231], v165 src0_sel:WORD_1
	v_cvt_pk_f32_fp8_e32 v[232:233], v166
	v_cvt_pk_f32_fp8_sdwa v[234:235], v166 src0_sel:WORD_1
	v_cvt_pk_f32_fp8_e32 v[236:237], v167
	v_cvt_pk_f32_fp8_sdwa v[238:239], v167 src0_sel:WORD_1
	v_pk_fma_f32 v[64:65], v[224:225], s[18:19], v[64:65] op_sel_hi:[1,0,1]
	v_pk_fma_f32 v[66:67], v[226:227], s[18:19], v[66:67] op_sel_hi:[1,0,1]
	v_pk_fma_f32 v[68:69], v[228:229], s[18:19], v[68:69] op_sel_hi:[1,0,1]
	v_pk_fma_f32 v[70:71], v[230:231], s[18:19], v[70:71] op_sel_hi:[1,0,1]
	v_pk_fma_f32 v[72:73], v[232:233], s[18:19], v[72:73] op_sel_hi:[1,0,1]
	v_pk_fma_f32 v[74:75], v[234:235], s[18:19], v[74:75] op_sel_hi:[1,0,1]
	v_pk_fma_f32 v[76:77], v[236:237], s[18:19], v[76:77] op_sel_hi:[1,0,1]
	v_pk_fma_f32 v[78:79], v[238:239], s[18:19], v[78:79] op_sel_hi:[1,0,1]
	v_cvt_pk_f32_fp8_e32 v[224:225], v168
	v_cvt_pk_f32_fp8_sdwa v[226:227], v168 src0_sel:WORD_1
	v_cvt_pk_f32_fp8_e32 v[228:229], v169
	v_cvt_pk_f32_fp8_sdwa v[230:231], v169 src0_sel:WORD_1
	v_cvt_pk_f32_fp8_e32 v[232:233], v170
	v_cvt_pk_f32_fp8_sdwa v[234:235], v170 src0_sel:WORD_1
	v_cvt_pk_f32_fp8_e32 v[236:237], v171
	v_cvt_pk_f32_fp8_sdwa v[238:239], v171 src0_sel:WORD_1
	v_pk_fma_f32 v[64:65], v[224:225], s[20:21], v[64:65] op_sel_hi:[1,0,1]
	v_pk_fma_f32 v[66:67], v[226:227], s[20:21], v[66:67] op_sel_hi:[1,0,1]
	v_pk_fma_f32 v[68:69], v[228:229], s[20:21], v[68:69] op_sel_hi:[1,0,1]
	v_pk_fma_f32 v[70:71], v[230:231], s[20:21], v[70:71] op_sel_hi:[1,0,1]
	v_pk_fma_f32 v[72:73], v[232:233], s[20:21], v[72:73] op_sel_hi:[1,0,1]
	v_pk_fma_f32 v[74:75], v[234:235], s[20:21], v[74:75] op_sel_hi:[1,0,1]
	v_pk_fma_f32 v[76:77], v[236:237], s[20:21], v[76:77] op_sel_hi:[1,0,1]
	v_pk_fma_f32 v[78:79], v[238:239], s[20:21], v[78:79] op_sel_hi:[1,0,1]
	v_cvt_pk_f32_fp8_e32 v[224:225], v172
	v_cvt_pk_f32_fp8_sdwa v[226:227], v172 src0_sel:WORD_1
	v_cvt_pk_f32_fp8_e32 v[228:229], v173
	v_cvt_pk_f32_fp8_sdwa v[230:231], v173 src0_sel:WORD_1
	v_cvt_pk_f32_fp8_e32 v[232:233], v174
	v_cvt_pk_f32_fp8_sdwa v[234:235], v174 src0_sel:WORD_1
	v_cvt_pk_f32_fp8_e32 v[236:237], v175
	v_cvt_pk_f32_fp8_sdwa v[238:239], v175 src0_sel:WORD_1
	v_pk_fma_f32 v[64:65], v[224:225], s[22:23], v[64:65] op_sel_hi:[1,0,1]
	v_pk_fma_f32 v[66:67], v[226:227], s[22:23], v[66:67] op_sel_hi:[1,0,1]
	v_pk_fma_f32 v[68:69], v[228:229], s[22:23], v[68:69] op_sel_hi:[1,0,1]
	v_pk_fma_f32 v[70:71], v[230:231], s[22:23], v[70:71] op_sel_hi:[1,0,1]
	v_pk_fma_f32 v[72:73], v[232:233], s[22:23], v[72:73] op_sel_hi:[1,0,1]
	v_pk_fma_f32 v[74:75], v[234:235], s[22:23], v[74:75] op_sel_hi:[1,0,1]
	v_pk_fma_f32 v[76:77], v[236:237], s[22:23], v[76:77] op_sel_hi:[1,0,1]
	v_pk_fma_f32 v[78:79], v[238:239], s[22:23], v[78:79] op_sel_hi:[1,0,1]
	v_cvt_pk_f32_fp8_e32 v[224:225], v176
	v_cvt_pk_f32_fp8_sdwa v[226:227], v176 src0_sel:WORD_1
	v_cvt_pk_f32_fp8_e32 v[228:229], v177
	v_cvt_pk_f32_fp8_sdwa v[230:231], v177 src0_sel:WORD_1
	v_cvt_pk_f32_fp8_e32 v[232:233], v178
	v_cvt_pk_f32_fp8_sdwa v[234:235], v178 src0_sel:WORD_1
	v_cvt_pk_f32_fp8_e32 v[236:237], v179
	v_cvt_pk_f32_fp8_sdwa v[238:239], v179 src0_sel:WORD_1
	v_pk_fma_f32 v[64:65], v[224:225], s[24:25], v[64:65] op_sel_hi:[1,0,1]
	v_pk_fma_f32 v[66:67], v[226:227], s[24:25], v[66:67] op_sel_hi:[1,0,1]
	v_pk_fma_f32 v[68:69], v[228:229], s[24:25], v[68:69] op_sel_hi:[1,0,1]
	v_pk_fma_f32 v[70:71], v[230:231], s[24:25], v[70:71] op_sel_hi:[1,0,1]
	v_pk_fma_f32 v[72:73], v[232:233], s[24:25], v[72:73] op_sel_hi:[1,0,1]
	v_pk_fma_f32 v[74:75], v[234:235], s[24:25], v[74:75] op_sel_hi:[1,0,1]
	v_pk_fma_f32 v[76:77], v[236:237], s[24:25], v[76:77] op_sel_hi:[1,0,1]
	v_pk_fma_f32 v[78:79], v[238:239], s[24:25], v[78:79] op_sel_hi:[1,0,1]
	v_cvt_pk_f32_fp8_e32 v[224:225], v180
	v_cvt_pk_f32_fp8_sdwa v[226:227], v180 src0_sel:WORD_1
	v_cvt_pk_f32_fp8_e32 v[228:229], v181
	v_cvt_pk_f32_fp8_sdwa v[230:231], v181 src0_sel:WORD_1
	v_cvt_pk_f32_fp8_e32 v[232:233], v182
	v_cvt_pk_f32_fp8_sdwa v[234:235], v182 src0_sel:WORD_1
	v_cvt_pk_f32_fp8_e32 v[236:237], v183
	v_cvt_pk_f32_fp8_sdwa v[238:239], v183 src0_sel:WORD_1
	v_pk_fma_f32 v[64:65], v[224:225], s[26:27], v[64:65] op_sel_hi:[1,0,1]
	v_pk_fma_f32 v[66:67], v[226:227], s[26:27], v[66:67] op_sel_hi:[1,0,1]
	v_pk_fma_f32 v[68:69], v[228:229], s[26:27], v[68:69] op_sel_hi:[1,0,1]
	v_pk_fma_f32 v[70:71], v[230:231], s[26:27], v[70:71] op_sel_hi:[1,0,1]
	v_pk_fma_f32 v[72:73], v[232:233], s[26:27], v[72:73] op_sel_hi:[1,0,1]
	v_pk_fma_f32 v[74:75], v[234:235], s[26:27], v[74:75] op_sel_hi:[1,0,1]
	v_pk_fma_f32 v[76:77], v[236:237], s[26:27], v[76:77] op_sel_hi:[1,0,1]
	v_pk_fma_f32 v[78:79], v[238:239], s[26:27], v[78:79] op_sel_hi:[1,0,1]
	v_cvt_pk_f32_fp8_e32 v[224:225], v184
	v_cvt_pk_f32_fp8_sdwa v[226:227], v184 src0_sel:WORD_1
	v_cvt_pk_f32_fp8_e32 v[228:229], v185
	v_cvt_pk_f32_fp8_sdwa v[230:231], v185 src0_sel:WORD_1
	v_cvt_pk_f32_fp8_e32 v[232:233], v186
	v_cvt_pk_f32_fp8_sdwa v[234:235], v186 src0_sel:WORD_1
	v_cvt_pk_f32_fp8_e32 v[236:237], v187
	v_cvt_pk_f32_fp8_sdwa v[238:239], v187 src0_sel:WORD_1
	v_pk_fma_f32 v[64:65], v[224:225], s[28:29], v[64:65] op_sel_hi:[1,0,1]
	v_pk_fma_f32 v[66:67], v[226:227], s[28:29], v[66:67] op_sel_hi:[1,0,1]
	v_pk_fma_f32 v[68:69], v[228:229], s[28:29], v[68:69] op_sel_hi:[1,0,1]
	v_pk_fma_f32 v[70:71], v[230:231], s[28:29], v[70:71] op_sel_hi:[1,0,1]
	v_pk_fma_f32 v[72:73], v[232:233], s[28:29], v[72:73] op_sel_hi:[1,0,1]
	v_pk_fma_f32 v[74:75], v[234:235], s[28:29], v[74:75] op_sel_hi:[1,0,1]
	v_pk_fma_f32 v[76:77], v[236:237], s[28:29], v[76:77] op_sel_hi:[1,0,1]
	v_pk_fma_f32 v[78:79], v[238:239], s[28:29], v[78:79] op_sel_hi:[1,0,1]
	v_cvt_pk_f32_fp8_e32 v[224:225], v188
	v_cvt_pk_f32_fp8_sdwa v[226:227], v188 src0_sel:WORD_1
	v_cvt_pk_f32_fp8_e32 v[228:229], v189
	v_cvt_pk_f32_fp8_sdwa v[230:231], v189 src0_sel:WORD_1
	v_cvt_pk_f32_fp8_e32 v[232:233], v190
	v_cvt_pk_f32_fp8_sdwa v[234:235], v190 src0_sel:WORD_1
	v_cvt_pk_f32_fp8_e32 v[236:237], v191
	v_cvt_pk_f32_fp8_sdwa v[238:239], v191 src0_sel:WORD_1
	v_pk_fma_f32 v[64:65], v[224:225], s[30:31], v[64:65] op_sel_hi:[1,0,1]
	v_pk_fma_f32 v[66:67], v[226:227], s[30:31], v[66:67] op_sel_hi:[1,0,1]
	v_pk_fma_f32 v[68:69], v[228:229], s[30:31], v[68:69] op_sel_hi:[1,0,1]
	v_pk_fma_f32 v[70:71], v[230:231], s[30:31], v[70:71] op_sel_hi:[1,0,1]
	v_pk_fma_f32 v[72:73], v[232:233], s[30:31], v[72:73] op_sel_hi:[1,0,1]
	v_pk_fma_f32 v[74:75], v[234:235], s[30:31], v[74:75] op_sel_hi:[1,0,1]
	v_pk_fma_f32 v[76:77], v[236:237], s[30:31], v[76:77] op_sel_hi:[1,0,1]
	v_pk_fma_f32 v[78:79], v[238:239], s[30:31], v[78:79] op_sel_hi:[1,0,1]
	v_readlane_b32 s16, v150, s72
	v_readlane_b32 s18, v150, s73
	v_readlane_b32 s20, v150, s74
	v_readlane_b32 s22, v150, s75
	v_readlane_b32 s24, v150, s76
	v_readlane_b32 s26, v150, s77
	v_readlane_b32 s28, v150, s78
	v_readlane_b32 s30, v150, s79
	v_readlane_b32 s48, v152, s72
	v_readlane_b32 s49, v152, s73
	v_readlane_b32 s50, v152, s74
	v_readlane_b32 s51, v152, s75
	v_readlane_b32 s52, v152, s76
	v_readlane_b32 s53, v152, s77
	v_readlane_b32 s54, v152, s78
	v_readlane_b32 s55, v152, s79
	s_add_u32 s32, s0, s48
	s_addc_u32 s33, s1, 0
	s_add_u32 s34, s0, s49
	s_addc_u32 s35, s1, 0
	s_add_u32 s36, s0, s50
	s_addc_u32 s37, s1, 0
	s_add_u32 s38, s0, s51
	s_addc_u32 s39, s1, 0
	s_add_u32 s40, s0, s52
	s_addc_u32 s41, s1, 0
	s_add_u32 s42, s0, s53
	s_addc_u32 s43, s1, 0
	s_add_u32 s44, s0, s54
	s_addc_u32 s45, s1, 0
	s_add_u32 s46, s0, s55
	s_addc_u32 s47, s1, 0
	global_load_dwordx4 v[160:163], v240, s[32:33]
	global_load_dwordx4 v[164:167], v240, s[34:35]
	global_load_dwordx4 v[168:171], v240, s[36:37]
	global_load_dwordx4 v[172:175], v240, s[38:39]
	global_load_dwordx4 v[176:179], v240, s[40:41]
	global_load_dwordx4 v[180:183], v240, s[42:43]
	global_load_dwordx4 v[184:187], v240, s[44:45]
	global_load_dwordx4 v[188:191], v240, s[46:47]
	s_waitcnt vmcnt(8)
	v_cvt_pk_f32_fp8_e32 v[224:225], v192
	v_cvt_pk_f32_fp8_sdwa v[226:227], v192 src0_sel:WORD_1
	v_cvt_pk_f32_fp8_e32 v[228:229], v193
	v_cvt_pk_f32_fp8_sdwa v[230:231], v193 src0_sel:WORD_1
	v_cvt_pk_f32_fp8_e32 v[232:233], v194
	v_cvt_pk_f32_fp8_sdwa v[234:235], v194 src0_sel:WORD_1
	v_cvt_pk_f32_fp8_e32 v[236:237], v195
	v_cvt_pk_f32_fp8_sdwa v[238:239], v195 src0_sel:WORD_1
	v_pk_fma_f32 v[80:81], v[224:225], s[16:17], v[80:81] op_sel_hi:[1,0,1]
	v_pk_fma_f32 v[82:83], v[226:227], s[16:17], v[82:83] op_sel_hi:[1,0,1]
	v_pk_fma_f32 v[84:85], v[228:229], s[16:17], v[84:85] op_sel_hi:[1,0,1]
	v_pk_fma_f32 v[86:87], v[230:231], s[16:17], v[86:87] op_sel_hi:[1,0,1]
	v_pk_fma_f32 v[88:89], v[232:233], s[16:17], v[88:89] op_sel_hi:[1,0,1]
	v_pk_fma_f32 v[90:91], v[234:235], s[16:17], v[90:91] op_sel_hi:[1,0,1]
	v_pk_fma_f32 v[92:93], v[236:237], s[16:17], v[92:93] op_sel_hi:[1,0,1]
	v_pk_fma_f32 v[94:95], v[238:239], s[16:17], v[94:95] op_sel_hi:[1,0,1]
	v_cvt_pk_f32_fp8_e32 v[224:225], v196
	v_cvt_pk_f32_fp8_sdwa v[226:227], v196 src0_sel:WORD_1
	v_cvt_pk_f32_fp8_e32 v[228:229], v197
	v_cvt_pk_f32_fp8_sdwa v[230:231], v197 src0_sel:WORD_1
	v_cvt_pk_f32_fp8_e32 v[232:233], v198
	v_cvt_pk_f32_fp8_sdwa v[234:235], v198 src0_sel:WORD_1
	v_cvt_pk_f32_fp8_e32 v[236:237], v199
	v_cvt_pk_f32_fp8_sdwa v[238:239], v199 src0_sel:WORD_1
	v_pk_fma_f32 v[80:81], v[224:225], s[18:19], v[80:81] op_sel_hi:[1,0,1]
	v_pk_fma_f32 v[82:83], v[226:227], s[18:19], v[82:83] op_sel_hi:[1,0,1]
	v_pk_fma_f32 v[84:85], v[228:229], s[18:19], v[84:85] op_sel_hi:[1,0,1]
	v_pk_fma_f32 v[86:87], v[230:231], s[18:19], v[86:87] op_sel_hi:[1,0,1]
	v_pk_fma_f32 v[88:89], v[232:233], s[18:19], v[88:89] op_sel_hi:[1,0,1]
	v_pk_fma_f32 v[90:91], v[234:235], s[18:19], v[90:91] op_sel_hi:[1,0,1]
	v_pk_fma_f32 v[92:93], v[236:237], s[18:19], v[92:93] op_sel_hi:[1,0,1]
	v_pk_fma_f32 v[94:95], v[238:239], s[18:19], v[94:95] op_sel_hi:[1,0,1]
	v_cvt_pk_f32_fp8_e32 v[224:225], v200
	v_cvt_pk_f32_fp8_sdwa v[226:227], v200 src0_sel:WORD_1
	v_cvt_pk_f32_fp8_e32 v[228:229], v201
	v_cvt_pk_f32_fp8_sdwa v[230:231], v201 src0_sel:WORD_1
	v_cvt_pk_f32_fp8_e32 v[232:233], v202
	v_cvt_pk_f32_fp8_sdwa v[234:235], v202 src0_sel:WORD_1
	v_cvt_pk_f32_fp8_e32 v[236:237], v203
	v_cvt_pk_f32_fp8_sdwa v[238:239], v203 src0_sel:WORD_1
	v_pk_fma_f32 v[80:81], v[224:225], s[20:21], v[80:81] op_sel_hi:[1,0,1]
	v_pk_fma_f32 v[82:83], v[226:227], s[20:21], v[82:83] op_sel_hi:[1,0,1]
	v_pk_fma_f32 v[84:85], v[228:229], s[20:21], v[84:85] op_sel_hi:[1,0,1]
	v_pk_fma_f32 v[86:87], v[230:231], s[20:21], v[86:87] op_sel_hi:[1,0,1]
	v_pk_fma_f32 v[88:89], v[232:233], s[20:21], v[88:89] op_sel_hi:[1,0,1]
	v_pk_fma_f32 v[90:91], v[234:235], s[20:21], v[90:91] op_sel_hi:[1,0,1]
	v_pk_fma_f32 v[92:93], v[236:237], s[20:21], v[92:93] op_sel_hi:[1,0,1]
	v_pk_fma_f32 v[94:95], v[238:239], s[20:21], v[94:95] op_sel_hi:[1,0,1]
	v_cvt_pk_f32_fp8_e32 v[224:225], v204
	v_cvt_pk_f32_fp8_sdwa v[226:227], v204 src0_sel:WORD_1
	v_cvt_pk_f32_fp8_e32 v[228:229], v205
	v_cvt_pk_f32_fp8_sdwa v[230:231], v205 src0_sel:WORD_1
	v_cvt_pk_f32_fp8_e32 v[232:233], v206
	v_cvt_pk_f32_fp8_sdwa v[234:235], v206 src0_sel:WORD_1
	v_cvt_pk_f32_fp8_e32 v[236:237], v207
	v_cvt_pk_f32_fp8_sdwa v[238:239], v207 src0_sel:WORD_1
	v_pk_fma_f32 v[80:81], v[224:225], s[22:23], v[80:81] op_sel_hi:[1,0,1]
	v_pk_fma_f32 v[82:83], v[226:227], s[22:23], v[82:83] op_sel_hi:[1,0,1]
	v_pk_fma_f32 v[84:85], v[228:229], s[22:23], v[84:85] op_sel_hi:[1,0,1]
	v_pk_fma_f32 v[86:87], v[230:231], s[22:23], v[86:87] op_sel_hi:[1,0,1]
	v_pk_fma_f32 v[88:89], v[232:233], s[22:23], v[88:89] op_sel_hi:[1,0,1]
	v_pk_fma_f32 v[90:91], v[234:235], s[22:23], v[90:91] op_sel_hi:[1,0,1]
	v_pk_fma_f32 v[92:93], v[236:237], s[22:23], v[92:93] op_sel_hi:[1,0,1]
	v_pk_fma_f32 v[94:95], v[238:239], s[22:23], v[94:95] op_sel_hi:[1,0,1]
	v_cvt_pk_f32_fp8_e32 v[224:225], v208
	v_cvt_pk_f32_fp8_sdwa v[226:227], v208 src0_sel:WORD_1
	v_cvt_pk_f32_fp8_e32 v[228:229], v209
	v_cvt_pk_f32_fp8_sdwa v[230:231], v209 src0_sel:WORD_1
	v_cvt_pk_f32_fp8_e32 v[232:233], v210
	v_cvt_pk_f32_fp8_sdwa v[234:235], v210 src0_sel:WORD_1
	v_cvt_pk_f32_fp8_e32 v[236:237], v211
	v_cvt_pk_f32_fp8_sdwa v[238:239], v211 src0_sel:WORD_1
	v_pk_fma_f32 v[80:81], v[224:225], s[24:25], v[80:81] op_sel_hi:[1,0,1]
	v_pk_fma_f32 v[82:83], v[226:227], s[24:25], v[82:83] op_sel_hi:[1,0,1]
	v_pk_fma_f32 v[84:85], v[228:229], s[24:25], v[84:85] op_sel_hi:[1,0,1]
	v_pk_fma_f32 v[86:87], v[230:231], s[24:25], v[86:87] op_sel_hi:[1,0,1]
	v_pk_fma_f32 v[88:89], v[232:233], s[24:25], v[88:89] op_sel_hi:[1,0,1]
	v_pk_fma_f32 v[90:91], v[234:235], s[24:25], v[90:91] op_sel_hi:[1,0,1]
	v_pk_fma_f32 v[92:93], v[236:237], s[24:25], v[92:93] op_sel_hi:[1,0,1]
	v_pk_fma_f32 v[94:95], v[238:239], s[24:25], v[94:95] op_sel_hi:[1,0,1]
	v_cvt_pk_f32_fp8_e32 v[224:225], v212
	v_cvt_pk_f32_fp8_sdwa v[226:227], v212 src0_sel:WORD_1
	v_cvt_pk_f32_fp8_e32 v[228:229], v213
	v_cvt_pk_f32_fp8_sdwa v[230:231], v213 src0_sel:WORD_1
	v_cvt_pk_f32_fp8_e32 v[232:233], v214
	v_cvt_pk_f32_fp8_sdwa v[234:235], v214 src0_sel:WORD_1
	v_cvt_pk_f32_fp8_e32 v[236:237], v215
	v_cvt_pk_f32_fp8_sdwa v[238:239], v215 src0_sel:WORD_1
	v_pk_fma_f32 v[80:81], v[224:225], s[26:27], v[80:81] op_sel_hi:[1,0,1]
	v_pk_fma_f32 v[82:83], v[226:227], s[26:27], v[82:83] op_sel_hi:[1,0,1]
	v_pk_fma_f32 v[84:85], v[228:229], s[26:27], v[84:85] op_sel_hi:[1,0,1]
	v_pk_fma_f32 v[86:87], v[230:231], s[26:27], v[86:87] op_sel_hi:[1,0,1]
	v_pk_fma_f32 v[88:89], v[232:233], s[26:27], v[88:89] op_sel_hi:[1,0,1]
	v_pk_fma_f32 v[90:91], v[234:235], s[26:27], v[90:91] op_sel_hi:[1,0,1]
	v_pk_fma_f32 v[92:93], v[236:237], s[26:27], v[92:93] op_sel_hi:[1,0,1]
	v_pk_fma_f32 v[94:95], v[238:239], s[26:27], v[94:95] op_sel_hi:[1,0,1]
	v_cvt_pk_f32_fp8_e32 v[224:225], v216
	v_cvt_pk_f32_fp8_sdwa v[226:227], v216 src0_sel:WORD_1
	v_cvt_pk_f32_fp8_e32 v[228:229], v217
	v_cvt_pk_f32_fp8_sdwa v[230:231], v217 src0_sel:WORD_1
	v_cvt_pk_f32_fp8_e32 v[232:233], v218
	v_cvt_pk_f32_fp8_sdwa v[234:235], v218 src0_sel:WORD_1
	v_cvt_pk_f32_fp8_e32 v[236:237], v219
	v_cvt_pk_f32_fp8_sdwa v[238:239], v219 src0_sel:WORD_1
	v_pk_fma_f32 v[80:81], v[224:225], s[28:29], v[80:81] op_sel_hi:[1,0,1]
	v_pk_fma_f32 v[82:83], v[226:227], s[28:29], v[82:83] op_sel_hi:[1,0,1]
	v_pk_fma_f32 v[84:85], v[228:229], s[28:29], v[84:85] op_sel_hi:[1,0,1]
	v_pk_fma_f32 v[86:87], v[230:231], s[28:29], v[86:87] op_sel_hi:[1,0,1]
	v_pk_fma_f32 v[88:89], v[232:233], s[28:29], v[88:89] op_sel_hi:[1,0,1]
	v_pk_fma_f32 v[90:91], v[234:235], s[28:29], v[90:91] op_sel_hi:[1,0,1]
	v_pk_fma_f32 v[92:93], v[236:237], s[28:29], v[92:93] op_sel_hi:[1,0,1]
	v_pk_fma_f32 v[94:95], v[238:239], s[28:29], v[94:95] op_sel_hi:[1,0,1]
	v_cvt_pk_f32_fp8_e32 v[224:225], v220
	v_cvt_pk_f32_fp8_sdwa v[226:227], v220 src0_sel:WORD_1
	v_cvt_pk_f32_fp8_e32 v[228:229], v221
	v_cvt_pk_f32_fp8_sdwa v[230:231], v221 src0_sel:WORD_1
	v_cvt_pk_f32_fp8_e32 v[232:233], v222
	v_cvt_pk_f32_fp8_sdwa v[234:235], v222 src0_sel:WORD_1
	v_cvt_pk_f32_fp8_e32 v[236:237], v223
	v_cvt_pk_f32_fp8_sdwa v[238:239], v223 src0_sel:WORD_1
	v_pk_fma_f32 v[80:81], v[224:225], s[30:31], v[80:81] op_sel_hi:[1,0,1]
	v_pk_fma_f32 v[82:83], v[226:227], s[30:31], v[82:83] op_sel_hi:[1,0,1]
	v_pk_fma_f32 v[84:85], v[228:229], s[30:31], v[84:85] op_sel_hi:[1,0,1]
	v_pk_fma_f32 v[86:87], v[230:231], s[30:31], v[86:87] op_sel_hi:[1,0,1]
	v_pk_fma_f32 v[88:89], v[232:233], s[30:31], v[88:89] op_sel_hi:[1,0,1]
	v_pk_fma_f32 v[90:91], v[234:235], s[30:31], v[90:91] op_sel_hi:[1,0,1]
	v_pk_fma_f32 v[92:93], v[236:237], s[30:31], v[92:93] op_sel_hi:[1,0,1]
	v_pk_fma_f32 v[94:95], v[238:239], s[30:31], v[94:95] op_sel_hi:[1,0,1]
	v_readlane_b32 s16, v154, s72
	v_readlane_b32 s18, v154, s73
	v_readlane_b32 s20, v154, s74
	v_readlane_b32 s22, v154, s75
	v_readlane_b32 s24, v154, s76
	v_readlane_b32 s26, v154, s77
	v_readlane_b32 s28, v154, s78
	v_readlane_b32 s30, v154, s79
	v_readlane_b32 s48, v156, s72
	v_readlane_b32 s49, v156, s73
	v_readlane_b32 s50, v156, s74
	v_readlane_b32 s51, v156, s75
	v_readlane_b32 s52, v156, s76
	v_readlane_b32 s53, v156, s77
	v_readlane_b32 s54, v156, s78
	v_readlane_b32 s55, v156, s79
	s_add_u32 s32, s0, s48
	s_addc_u32 s33, s1, 0
	s_add_u32 s34, s0, s49
	s_addc_u32 s35, s1, 0
	s_add_u32 s36, s0, s50
	s_addc_u32 s37, s1, 0
	s_add_u32 s38, s0, s51
	s_addc_u32 s39, s1, 0
	s_add_u32 s40, s0, s52
	s_addc_u32 s41, s1, 0
	s_add_u32 s42, s0, s53
	s_addc_u32 s43, s1, 0
	s_add_u32 s44, s0, s54
	s_addc_u32 s45, s1, 0
	s_add_u32 s46, s0, s55
	s_addc_u32 s47, s1, 0
	global_load_dwordx4 v[192:195], v240, s[32:33]
	global_load_dwordx4 v[196:199], v240, s[34:35]
	global_load_dwordx4 v[200:203], v240, s[36:37]
	global_load_dwordx4 v[204:207], v240, s[38:39]
	global_load_dwordx4 v[208:211], v240, s[40:41]
	global_load_dwordx4 v[212:215], v240, s[42:43]
	global_load_dwordx4 v[216:219], v240, s[44:45]
	global_load_dwordx4 v[220:223], v240, s[46:47]
	s_waitcnt vmcnt(8)
	v_cvt_pk_f32_fp8_e32 v[224:225], v160
	v_cvt_pk_f32_fp8_sdwa v[226:227], v160 src0_sel:WORD_1
	v_cvt_pk_f32_fp8_e32 v[228:229], v161
	v_cvt_pk_f32_fp8_sdwa v[230:231], v161 src0_sel:WORD_1
	v_cvt_pk_f32_fp8_e32 v[232:233], v162
	v_cvt_pk_f32_fp8_sdwa v[234:235], v162 src0_sel:WORD_1
	v_cvt_pk_f32_fp8_e32 v[236:237], v163
	v_cvt_pk_f32_fp8_sdwa v[238:239], v163 src0_sel:WORD_1
	v_pk_fma_f32 v[96:97], v[224:225], s[16:17], v[96:97] op_sel_hi:[1,0,1]
	v_pk_fma_f32 v[98:99], v[226:227], s[16:17], v[98:99] op_sel_hi:[1,0,1]
	v_pk_fma_f32 v[100:101], v[228:229], s[16:17], v[100:101] op_sel_hi:[1,0,1]
	v_pk_fma_f32 v[102:103], v[230:231], s[16:17], v[102:103] op_sel_hi:[1,0,1]
	v_pk_fma_f32 v[104:105], v[232:233], s[16:17], v[104:105] op_sel_hi:[1,0,1]
	v_pk_fma_f32 v[106:107], v[234:235], s[16:17], v[106:107] op_sel_hi:[1,0,1]
	v_pk_fma_f32 v[108:109], v[236:237], s[16:17], v[108:109] op_sel_hi:[1,0,1]
	v_pk_fma_f32 v[110:111], v[238:239], s[16:17], v[110:111] op_sel_hi:[1,0,1]
	v_cvt_pk_f32_fp8_e32 v[224:225], v164
	v_cvt_pk_f32_fp8_sdwa v[226:227], v164 src0_sel:WORD_1
	v_cvt_pk_f32_fp8_e32 v[228:229], v165
	v_cvt_pk_f32_fp8_sdwa v[230:231], v165 src0_sel:WORD_1
	v_cvt_pk_f32_fp8_e32 v[232:233], v166
	v_cvt_pk_f32_fp8_sdwa v[234:235], v166 src0_sel:WORD_1
	v_cvt_pk_f32_fp8_e32 v[236:237], v167
	v_cvt_pk_f32_fp8_sdwa v[238:239], v167 src0_sel:WORD_1
	v_pk_fma_f32 v[96:97], v[224:225], s[18:19], v[96:97] op_sel_hi:[1,0,1]
	v_pk_fma_f32 v[98:99], v[226:227], s[18:19], v[98:99] op_sel_hi:[1,0,1]
	v_pk_fma_f32 v[100:101], v[228:229], s[18:19], v[100:101] op_sel_hi:[1,0,1]
	v_pk_fma_f32 v[102:103], v[230:231], s[18:19], v[102:103] op_sel_hi:[1,0,1]
	v_pk_fma_f32 v[104:105], v[232:233], s[18:19], v[104:105] op_sel_hi:[1,0,1]
	v_pk_fma_f32 v[106:107], v[234:235], s[18:19], v[106:107] op_sel_hi:[1,0,1]
	v_pk_fma_f32 v[108:109], v[236:237], s[18:19], v[108:109] op_sel_hi:[1,0,1]
	v_pk_fma_f32 v[110:111], v[238:239], s[18:19], v[110:111] op_sel_hi:[1,0,1]
	v_cvt_pk_f32_fp8_e32 v[224:225], v168
	v_cvt_pk_f32_fp8_sdwa v[226:227], v168 src0_sel:WORD_1
	v_cvt_pk_f32_fp8_e32 v[228:229], v169
	v_cvt_pk_f32_fp8_sdwa v[230:231], v169 src0_sel:WORD_1
	v_cvt_pk_f32_fp8_e32 v[232:233], v170
	v_cvt_pk_f32_fp8_sdwa v[234:235], v170 src0_sel:WORD_1
	v_cvt_pk_f32_fp8_e32 v[236:237], v171
	v_cvt_pk_f32_fp8_sdwa v[238:239], v171 src0_sel:WORD_1
	v_pk_fma_f32 v[96:97], v[224:225], s[20:21], v[96:97] op_sel_hi:[1,0,1]
	v_pk_fma_f32 v[98:99], v[226:227], s[20:21], v[98:99] op_sel_hi:[1,0,1]
	v_pk_fma_f32 v[100:101], v[228:229], s[20:21], v[100:101] op_sel_hi:[1,0,1]
	v_pk_fma_f32 v[102:103], v[230:231], s[20:21], v[102:103] op_sel_hi:[1,0,1]
	v_pk_fma_f32 v[104:105], v[232:233], s[20:21], v[104:105] op_sel_hi:[1,0,1]
	v_pk_fma_f32 v[106:107], v[234:235], s[20:21], v[106:107] op_sel_hi:[1,0,1]
	v_pk_fma_f32 v[108:109], v[236:237], s[20:21], v[108:109] op_sel_hi:[1,0,1]
	v_pk_fma_f32 v[110:111], v[238:239], s[20:21], v[110:111] op_sel_hi:[1,0,1]
	v_cvt_pk_f32_fp8_e32 v[224:225], v172
	v_cvt_pk_f32_fp8_sdwa v[226:227], v172 src0_sel:WORD_1
	v_cvt_pk_f32_fp8_e32 v[228:229], v173
	v_cvt_pk_f32_fp8_sdwa v[230:231], v173 src0_sel:WORD_1
	v_cvt_pk_f32_fp8_e32 v[232:233], v174
	v_cvt_pk_f32_fp8_sdwa v[234:235], v174 src0_sel:WORD_1
	v_cvt_pk_f32_fp8_e32 v[236:237], v175
	v_cvt_pk_f32_fp8_sdwa v[238:239], v175 src0_sel:WORD_1
	v_pk_fma_f32 v[96:97], v[224:225], s[22:23], v[96:97] op_sel_hi:[1,0,1]
	v_pk_fma_f32 v[98:99], v[226:227], s[22:23], v[98:99] op_sel_hi:[1,0,1]
	v_pk_fma_f32 v[100:101], v[228:229], s[22:23], v[100:101] op_sel_hi:[1,0,1]
	v_pk_fma_f32 v[102:103], v[230:231], s[22:23], v[102:103] op_sel_hi:[1,0,1]
	v_pk_fma_f32 v[104:105], v[232:233], s[22:23], v[104:105] op_sel_hi:[1,0,1]
	v_pk_fma_f32 v[106:107], v[234:235], s[22:23], v[106:107] op_sel_hi:[1,0,1]
	v_pk_fma_f32 v[108:109], v[236:237], s[22:23], v[108:109] op_sel_hi:[1,0,1]
	v_pk_fma_f32 v[110:111], v[238:239], s[22:23], v[110:111] op_sel_hi:[1,0,1]
	v_cvt_pk_f32_fp8_e32 v[224:225], v176
	v_cvt_pk_f32_fp8_sdwa v[226:227], v176 src0_sel:WORD_1
	v_cvt_pk_f32_fp8_e32 v[228:229], v177
	v_cvt_pk_f32_fp8_sdwa v[230:231], v177 src0_sel:WORD_1
	v_cvt_pk_f32_fp8_e32 v[232:233], v178
	v_cvt_pk_f32_fp8_sdwa v[234:235], v178 src0_sel:WORD_1
	v_cvt_pk_f32_fp8_e32 v[236:237], v179
	v_cvt_pk_f32_fp8_sdwa v[238:239], v179 src0_sel:WORD_1
	v_pk_fma_f32 v[96:97], v[224:225], s[24:25], v[96:97] op_sel_hi:[1,0,1]
	v_pk_fma_f32 v[98:99], v[226:227], s[24:25], v[98:99] op_sel_hi:[1,0,1]
	v_pk_fma_f32 v[100:101], v[228:229], s[24:25], v[100:101] op_sel_hi:[1,0,1]
	v_pk_fma_f32 v[102:103], v[230:231], s[24:25], v[102:103] op_sel_hi:[1,0,1]
	v_pk_fma_f32 v[104:105], v[232:233], s[24:25], v[104:105] op_sel_hi:[1,0,1]
	v_pk_fma_f32 v[106:107], v[234:235], s[24:25], v[106:107] op_sel_hi:[1,0,1]
	v_pk_fma_f32 v[108:109], v[236:237], s[24:25], v[108:109] op_sel_hi:[1,0,1]
	v_pk_fma_f32 v[110:111], v[238:239], s[24:25], v[110:111] op_sel_hi:[1,0,1]
	v_cvt_pk_f32_fp8_e32 v[224:225], v180
	v_cvt_pk_f32_fp8_sdwa v[226:227], v180 src0_sel:WORD_1
	v_cvt_pk_f32_fp8_e32 v[228:229], v181
	v_cvt_pk_f32_fp8_sdwa v[230:231], v181 src0_sel:WORD_1
	v_cvt_pk_f32_fp8_e32 v[232:233], v182
	v_cvt_pk_f32_fp8_sdwa v[234:235], v182 src0_sel:WORD_1
	v_cvt_pk_f32_fp8_e32 v[236:237], v183
	v_cvt_pk_f32_fp8_sdwa v[238:239], v183 src0_sel:WORD_1
	v_pk_fma_f32 v[96:97], v[224:225], s[26:27], v[96:97] op_sel_hi:[1,0,1]
	v_pk_fma_f32 v[98:99], v[226:227], s[26:27], v[98:99] op_sel_hi:[1,0,1]
	v_pk_fma_f32 v[100:101], v[228:229], s[26:27], v[100:101] op_sel_hi:[1,0,1]
	v_pk_fma_f32 v[102:103], v[230:231], s[26:27], v[102:103] op_sel_hi:[1,0,1]
	v_pk_fma_f32 v[104:105], v[232:233], s[26:27], v[104:105] op_sel_hi:[1,0,1]
	v_pk_fma_f32 v[106:107], v[234:235], s[26:27], v[106:107] op_sel_hi:[1,0,1]
	v_pk_fma_f32 v[108:109], v[236:237], s[26:27], v[108:109] op_sel_hi:[1,0,1]
	v_pk_fma_f32 v[110:111], v[238:239], s[26:27], v[110:111] op_sel_hi:[1,0,1]
	v_cvt_pk_f32_fp8_e32 v[224:225], v184
	v_cvt_pk_f32_fp8_sdwa v[226:227], v184 src0_sel:WORD_1
	v_cvt_pk_f32_fp8_e32 v[228:229], v185
	v_cvt_pk_f32_fp8_sdwa v[230:231], v185 src0_sel:WORD_1
	v_cvt_pk_f32_fp8_e32 v[232:233], v186
	v_cvt_pk_f32_fp8_sdwa v[234:235], v186 src0_sel:WORD_1
	v_cvt_pk_f32_fp8_e32 v[236:237], v187
	v_cvt_pk_f32_fp8_sdwa v[238:239], v187 src0_sel:WORD_1
	v_pk_fma_f32 v[96:97], v[224:225], s[28:29], v[96:97] op_sel_hi:[1,0,1]
	v_pk_fma_f32 v[98:99], v[226:227], s[28:29], v[98:99] op_sel_hi:[1,0,1]
	v_pk_fma_f32 v[100:101], v[228:229], s[28:29], v[100:101] op_sel_hi:[1,0,1]
	v_pk_fma_f32 v[102:103], v[230:231], s[28:29], v[102:103] op_sel_hi:[1,0,1]
	v_pk_fma_f32 v[104:105], v[232:233], s[28:29], v[104:105] op_sel_hi:[1,0,1]
	v_pk_fma_f32 v[106:107], v[234:235], s[28:29], v[106:107] op_sel_hi:[1,0,1]
	v_pk_fma_f32 v[108:109], v[236:237], s[28:29], v[108:109] op_sel_hi:[1,0,1]
	v_pk_fma_f32 v[110:111], v[238:239], s[28:29], v[110:111] op_sel_hi:[1,0,1]
	v_cvt_pk_f32_fp8_e32 v[224:225], v188
	v_cvt_pk_f32_fp8_sdwa v[226:227], v188 src0_sel:WORD_1
	v_cvt_pk_f32_fp8_e32 v[228:229], v189
	v_cvt_pk_f32_fp8_sdwa v[230:231], v189 src0_sel:WORD_1
	v_cvt_pk_f32_fp8_e32 v[232:233], v190
	v_cvt_pk_f32_fp8_sdwa v[234:235], v190 src0_sel:WORD_1
	v_cvt_pk_f32_fp8_e32 v[236:237], v191
	v_cvt_pk_f32_fp8_sdwa v[238:239], v191 src0_sel:WORD_1
	v_pk_fma_f32 v[96:97], v[224:225], s[30:31], v[96:97] op_sel_hi:[1,0,1]
	v_pk_fma_f32 v[98:99], v[226:227], s[30:31], v[98:99] op_sel_hi:[1,0,1]
	v_pk_fma_f32 v[100:101], v[228:229], s[30:31], v[100:101] op_sel_hi:[1,0,1]
	v_pk_fma_f32 v[102:103], v[230:231], s[30:31], v[102:103] op_sel_hi:[1,0,1]
	v_pk_fma_f32 v[104:105], v[232:233], s[30:31], v[104:105] op_sel_hi:[1,0,1]
	v_pk_fma_f32 v[106:107], v[234:235], s[30:31], v[106:107] op_sel_hi:[1,0,1]
	v_pk_fma_f32 v[108:109], v[236:237], s[30:31], v[108:109] op_sel_hi:[1,0,1]
	v_pk_fma_f32 v[110:111], v[238:239], s[30:31], v[110:111] op_sel_hi:[1,0,1]
	v_readlane_b32 s16, v158, s72
	v_readlane_b32 s18, v158, s73
	v_readlane_b32 s20, v158, s74
	v_readlane_b32 s22, v158, s75
	v_readlane_b32 s24, v158, s76
	v_readlane_b32 s26, v158, s77
	v_readlane_b32 s28, v158, s78
	v_readlane_b32 s30, v158, s79
	v_readlane_b32 s48, v145, s72
	v_readlane_b32 s49, v145, s73
	v_readlane_b32 s50, v145, s74
	v_readlane_b32 s51, v145, s75
	v_readlane_b32 s52, v145, s76
	v_readlane_b32 s53, v145, s77
	v_readlane_b32 s54, v145, s78
	v_readlane_b32 s55, v145, s79
	s_add_u32 s32, s0, s48
	s_addc_u32 s33, s1, 0
	s_add_u32 s34, s0, s49
	s_addc_u32 s35, s1, 0
	s_add_u32 s36, s0, s50
	s_addc_u32 s37, s1, 0
	s_add_u32 s38, s0, s51
	s_addc_u32 s39, s1, 0
	s_add_u32 s40, s0, s52
	s_addc_u32 s41, s1, 0
	s_add_u32 s42, s0, s53
	s_addc_u32 s43, s1, 0
	s_add_u32 s44, s0, s54
	s_addc_u32 s45, s1, 0
	s_add_u32 s46, s0, s55
	s_addc_u32 s47, s1, 0
	global_load_dwordx4 v[160:163], v240, s[32:33]
	global_load_dwordx4 v[164:167], v240, s[34:35]
	global_load_dwordx4 v[168:171], v240, s[36:37]
	global_load_dwordx4 v[172:175], v240, s[38:39]
	global_load_dwordx4 v[176:179], v240, s[40:41]
	global_load_dwordx4 v[180:183], v240, s[42:43]
	global_load_dwordx4 v[184:187], v240, s[44:45]
	global_load_dwordx4 v[188:191], v240, s[46:47]
	s_waitcnt vmcnt(8)
	v_cvt_pk_f32_fp8_e32 v[224:225], v192
	v_cvt_pk_f32_fp8_sdwa v[226:227], v192 src0_sel:WORD_1
	v_cvt_pk_f32_fp8_e32 v[228:229], v193
	v_cvt_pk_f32_fp8_sdwa v[230:231], v193 src0_sel:WORD_1
	v_cvt_pk_f32_fp8_e32 v[232:233], v194
	v_cvt_pk_f32_fp8_sdwa v[234:235], v194 src0_sel:WORD_1
	v_cvt_pk_f32_fp8_e32 v[236:237], v195
	v_cvt_pk_f32_fp8_sdwa v[238:239], v195 src0_sel:WORD_1
	v_pk_fma_f32 v[112:113], v[224:225], s[16:17], v[112:113] op_sel_hi:[1,0,1]
	v_pk_fma_f32 v[114:115], v[226:227], s[16:17], v[114:115] op_sel_hi:[1,0,1]
	v_pk_fma_f32 v[116:117], v[228:229], s[16:17], v[116:117] op_sel_hi:[1,0,1]
	v_pk_fma_f32 v[118:119], v[230:231], s[16:17], v[118:119] op_sel_hi:[1,0,1]
	v_pk_fma_f32 v[120:121], v[232:233], s[16:17], v[120:121] op_sel_hi:[1,0,1]
	v_pk_fma_f32 v[122:123], v[234:235], s[16:17], v[122:123] op_sel_hi:[1,0,1]
	v_pk_fma_f32 v[124:125], v[236:237], s[16:17], v[124:125] op_sel_hi:[1,0,1]
	v_pk_fma_f32 v[126:127], v[238:239], s[16:17], v[126:127] op_sel_hi:[1,0,1]
	v_cvt_pk_f32_fp8_e32 v[224:225], v196
	v_cvt_pk_f32_fp8_sdwa v[226:227], v196 src0_sel:WORD_1
	v_cvt_pk_f32_fp8_e32 v[228:229], v197
	v_cvt_pk_f32_fp8_sdwa v[230:231], v197 src0_sel:WORD_1
	v_cvt_pk_f32_fp8_e32 v[232:233], v198
	v_cvt_pk_f32_fp8_sdwa v[234:235], v198 src0_sel:WORD_1
	v_cvt_pk_f32_fp8_e32 v[236:237], v199
	v_cvt_pk_f32_fp8_sdwa v[238:239], v199 src0_sel:WORD_1
	v_pk_fma_f32 v[112:113], v[224:225], s[18:19], v[112:113] op_sel_hi:[1,0,1]
	v_pk_fma_f32 v[114:115], v[226:227], s[18:19], v[114:115] op_sel_hi:[1,0,1]
	v_pk_fma_f32 v[116:117], v[228:229], s[18:19], v[116:117] op_sel_hi:[1,0,1]
	v_pk_fma_f32 v[118:119], v[230:231], s[18:19], v[118:119] op_sel_hi:[1,0,1]
	v_pk_fma_f32 v[120:121], v[232:233], s[18:19], v[120:121] op_sel_hi:[1,0,1]
	v_pk_fma_f32 v[122:123], v[234:235], s[18:19], v[122:123] op_sel_hi:[1,0,1]
	v_pk_fma_f32 v[124:125], v[236:237], s[18:19], v[124:125] op_sel_hi:[1,0,1]
	v_pk_fma_f32 v[126:127], v[238:239], s[18:19], v[126:127] op_sel_hi:[1,0,1]
	v_cvt_pk_f32_fp8_e32 v[224:225], v200
	v_cvt_pk_f32_fp8_sdwa v[226:227], v200 src0_sel:WORD_1
	v_cvt_pk_f32_fp8_e32 v[228:229], v201
	v_cvt_pk_f32_fp8_sdwa v[230:231], v201 src0_sel:WORD_1
	v_cvt_pk_f32_fp8_e32 v[232:233], v202
	v_cvt_pk_f32_fp8_sdwa v[234:235], v202 src0_sel:WORD_1
	v_cvt_pk_f32_fp8_e32 v[236:237], v203
	v_cvt_pk_f32_fp8_sdwa v[238:239], v203 src0_sel:WORD_1
	v_pk_fma_f32 v[112:113], v[224:225], s[20:21], v[112:113] op_sel_hi:[1,0,1]
	v_pk_fma_f32 v[114:115], v[226:227], s[20:21], v[114:115] op_sel_hi:[1,0,1]
	v_pk_fma_f32 v[116:117], v[228:229], s[20:21], v[116:117] op_sel_hi:[1,0,1]
	v_pk_fma_f32 v[118:119], v[230:231], s[20:21], v[118:119] op_sel_hi:[1,0,1]
	v_pk_fma_f32 v[120:121], v[232:233], s[20:21], v[120:121] op_sel_hi:[1,0,1]
	v_pk_fma_f32 v[122:123], v[234:235], s[20:21], v[122:123] op_sel_hi:[1,0,1]
	v_pk_fma_f32 v[124:125], v[236:237], s[20:21], v[124:125] op_sel_hi:[1,0,1]
	v_pk_fma_f32 v[126:127], v[238:239], s[20:21], v[126:127] op_sel_hi:[1,0,1]
	v_cvt_pk_f32_fp8_e32 v[224:225], v204
	v_cvt_pk_f32_fp8_sdwa v[226:227], v204 src0_sel:WORD_1
	v_cvt_pk_f32_fp8_e32 v[228:229], v205
	v_cvt_pk_f32_fp8_sdwa v[230:231], v205 src0_sel:WORD_1
	v_cvt_pk_f32_fp8_e32 v[232:233], v206
	v_cvt_pk_f32_fp8_sdwa v[234:235], v206 src0_sel:WORD_1
	v_cvt_pk_f32_fp8_e32 v[236:237], v207
	v_cvt_pk_f32_fp8_sdwa v[238:239], v207 src0_sel:WORD_1
	v_pk_fma_f32 v[112:113], v[224:225], s[22:23], v[112:113] op_sel_hi:[1,0,1]
	v_pk_fma_f32 v[114:115], v[226:227], s[22:23], v[114:115] op_sel_hi:[1,0,1]
	v_pk_fma_f32 v[116:117], v[228:229], s[22:23], v[116:117] op_sel_hi:[1,0,1]
	v_pk_fma_f32 v[118:119], v[230:231], s[22:23], v[118:119] op_sel_hi:[1,0,1]
	v_pk_fma_f32 v[120:121], v[232:233], s[22:23], v[120:121] op_sel_hi:[1,0,1]
	v_pk_fma_f32 v[122:123], v[234:235], s[22:23], v[122:123] op_sel_hi:[1,0,1]
	v_pk_fma_f32 v[124:125], v[236:237], s[22:23], v[124:125] op_sel_hi:[1,0,1]
	v_pk_fma_f32 v[126:127], v[238:239], s[22:23], v[126:127] op_sel_hi:[1,0,1]
	v_cvt_pk_f32_fp8_e32 v[224:225], v208
	v_cvt_pk_f32_fp8_sdwa v[226:227], v208 src0_sel:WORD_1
	v_cvt_pk_f32_fp8_e32 v[228:229], v209
	v_cvt_pk_f32_fp8_sdwa v[230:231], v209 src0_sel:WORD_1
	v_cvt_pk_f32_fp8_e32 v[232:233], v210
	v_cvt_pk_f32_fp8_sdwa v[234:235], v210 src0_sel:WORD_1
	v_cvt_pk_f32_fp8_e32 v[236:237], v211
	v_cvt_pk_f32_fp8_sdwa v[238:239], v211 src0_sel:WORD_1
	v_pk_fma_f32 v[112:113], v[224:225], s[24:25], v[112:113] op_sel_hi:[1,0,1]
	v_pk_fma_f32 v[114:115], v[226:227], s[24:25], v[114:115] op_sel_hi:[1,0,1]
	v_pk_fma_f32 v[116:117], v[228:229], s[24:25], v[116:117] op_sel_hi:[1,0,1]
	v_pk_fma_f32 v[118:119], v[230:231], s[24:25], v[118:119] op_sel_hi:[1,0,1]
	v_pk_fma_f32 v[120:121], v[232:233], s[24:25], v[120:121] op_sel_hi:[1,0,1]
	v_pk_fma_f32 v[122:123], v[234:235], s[24:25], v[122:123] op_sel_hi:[1,0,1]
	v_pk_fma_f32 v[124:125], v[236:237], s[24:25], v[124:125] op_sel_hi:[1,0,1]
	v_pk_fma_f32 v[126:127], v[238:239], s[24:25], v[126:127] op_sel_hi:[1,0,1]
	v_cvt_pk_f32_fp8_e32 v[224:225], v212
	v_cvt_pk_f32_fp8_sdwa v[226:227], v212 src0_sel:WORD_1
	v_cvt_pk_f32_fp8_e32 v[228:229], v213
	v_cvt_pk_f32_fp8_sdwa v[230:231], v213 src0_sel:WORD_1
	v_cvt_pk_f32_fp8_e32 v[232:233], v214
	v_cvt_pk_f32_fp8_sdwa v[234:235], v214 src0_sel:WORD_1
	v_cvt_pk_f32_fp8_e32 v[236:237], v215
	v_cvt_pk_f32_fp8_sdwa v[238:239], v215 src0_sel:WORD_1
	v_pk_fma_f32 v[112:113], v[224:225], s[26:27], v[112:113] op_sel_hi:[1,0,1]
	v_pk_fma_f32 v[114:115], v[226:227], s[26:27], v[114:115] op_sel_hi:[1,0,1]
	v_pk_fma_f32 v[116:117], v[228:229], s[26:27], v[116:117] op_sel_hi:[1,0,1]
	v_pk_fma_f32 v[118:119], v[230:231], s[26:27], v[118:119] op_sel_hi:[1,0,1]
	v_pk_fma_f32 v[120:121], v[232:233], s[26:27], v[120:121] op_sel_hi:[1,0,1]
	v_pk_fma_f32 v[122:123], v[234:235], s[26:27], v[122:123] op_sel_hi:[1,0,1]
	v_pk_fma_f32 v[124:125], v[236:237], s[26:27], v[124:125] op_sel_hi:[1,0,1]
	v_pk_fma_f32 v[126:127], v[238:239], s[26:27], v[126:127] op_sel_hi:[1,0,1]
	v_cvt_pk_f32_fp8_e32 v[224:225], v216
	v_cvt_pk_f32_fp8_sdwa v[226:227], v216 src0_sel:WORD_1
	v_cvt_pk_f32_fp8_e32 v[228:229], v217
	v_cvt_pk_f32_fp8_sdwa v[230:231], v217 src0_sel:WORD_1
	v_cvt_pk_f32_fp8_e32 v[232:233], v218
	v_cvt_pk_f32_fp8_sdwa v[234:235], v218 src0_sel:WORD_1
	v_cvt_pk_f32_fp8_e32 v[236:237], v219
	v_cvt_pk_f32_fp8_sdwa v[238:239], v219 src0_sel:WORD_1
	v_pk_fma_f32 v[112:113], v[224:225], s[28:29], v[112:113] op_sel_hi:[1,0,1]
	v_pk_fma_f32 v[114:115], v[226:227], s[28:29], v[114:115] op_sel_hi:[1,0,1]
	v_pk_fma_f32 v[116:117], v[228:229], s[28:29], v[116:117] op_sel_hi:[1,0,1]
	v_pk_fma_f32 v[118:119], v[230:231], s[28:29], v[118:119] op_sel_hi:[1,0,1]
	v_pk_fma_f32 v[120:121], v[232:233], s[28:29], v[120:121] op_sel_hi:[1,0,1]
	v_pk_fma_f32 v[122:123], v[234:235], s[28:29], v[122:123] op_sel_hi:[1,0,1]
	v_pk_fma_f32 v[124:125], v[236:237], s[28:29], v[124:125] op_sel_hi:[1,0,1]
	v_pk_fma_f32 v[126:127], v[238:239], s[28:29], v[126:127] op_sel_hi:[1,0,1]
	v_cvt_pk_f32_fp8_e32 v[224:225], v220
	v_cvt_pk_f32_fp8_sdwa v[226:227], v220 src0_sel:WORD_1
	v_cvt_pk_f32_fp8_e32 v[228:229], v221
	v_cvt_pk_f32_fp8_sdwa v[230:231], v221 src0_sel:WORD_1
	v_cvt_pk_f32_fp8_e32 v[232:233], v222
	v_cvt_pk_f32_fp8_sdwa v[234:235], v222 src0_sel:WORD_1
	v_cvt_pk_f32_fp8_e32 v[236:237], v223
	v_cvt_pk_f32_fp8_sdwa v[238:239], v223 src0_sel:WORD_1
	v_pk_fma_f32 v[112:113], v[224:225], s[30:31], v[112:113] op_sel_hi:[1,0,1]
	v_pk_fma_f32 v[114:115], v[226:227], s[30:31], v[114:115] op_sel_hi:[1,0,1]
	v_pk_fma_f32 v[116:117], v[228:229], s[30:31], v[116:117] op_sel_hi:[1,0,1]
	v_pk_fma_f32 v[118:119], v[230:231], s[30:31], v[118:119] op_sel_hi:[1,0,1]
	v_pk_fma_f32 v[120:121], v[232:233], s[30:31], v[120:121] op_sel_hi:[1,0,1]
	v_pk_fma_f32 v[122:123], v[234:235], s[30:31], v[122:123] op_sel_hi:[1,0,1]
	v_pk_fma_f32 v[124:125], v[236:237], s[30:31], v[124:125] op_sel_hi:[1,0,1]
	v_pk_fma_f32 v[126:127], v[238:239], s[30:31], v[126:127] op_sel_hi:[1,0,1]
	v_readlane_b32 s16, v147, s72
	v_readlane_b32 s18, v147, s73
	v_readlane_b32 s20, v147, s74
	v_readlane_b32 s22, v147, s75
	v_readlane_b32 s24, v147, s76
	v_readlane_b32 s26, v147, s77
	v_readlane_b32 s28, v147, s78
	v_readlane_b32 s30, v147, s79
	v_readlane_b32 s48, v149, s72
	v_readlane_b32 s49, v149, s73
	v_readlane_b32 s50, v149, s74
	v_readlane_b32 s51, v149, s75
	v_readlane_b32 s52, v149, s76
	v_readlane_b32 s53, v149, s77
	v_readlane_b32 s54, v149, s78
	v_readlane_b32 s55, v149, s79
	s_add_u32 s32, s0, s48
	s_addc_u32 s33, s1, 0
	s_add_u32 s34, s0, s49
	s_addc_u32 s35, s1, 0
	s_add_u32 s36, s0, s50
	s_addc_u32 s37, s1, 0
	s_add_u32 s38, s0, s51
	s_addc_u32 s39, s1, 0
	s_add_u32 s40, s0, s52
	s_addc_u32 s41, s1, 0
	s_add_u32 s42, s0, s53
	s_addc_u32 s43, s1, 0
	s_add_u32 s44, s0, s54
	s_addc_u32 s45, s1, 0
	s_add_u32 s46, s0, s55
	s_addc_u32 s47, s1, 0
	global_load_dwordx4 v[192:195], v240, s[32:33]
	global_load_dwordx4 v[196:199], v240, s[34:35]
	global_load_dwordx4 v[200:203], v240, s[36:37]
	global_load_dwordx4 v[204:207], v240, s[38:39]
	global_load_dwordx4 v[208:211], v240, s[40:41]
	global_load_dwordx4 v[212:215], v240, s[42:43]
	global_load_dwordx4 v[216:219], v240, s[44:45]
	global_load_dwordx4 v[220:223], v240, s[46:47]
	s_waitcnt vmcnt(8)
	v_cvt_pk_f32_fp8_e32 v[224:225], v160
	v_cvt_pk_f32_fp8_sdwa v[226:227], v160 src0_sel:WORD_1
	v_cvt_pk_f32_fp8_e32 v[228:229], v161
	v_cvt_pk_f32_fp8_sdwa v[230:231], v161 src0_sel:WORD_1
	v_cvt_pk_f32_fp8_e32 v[232:233], v162
	v_cvt_pk_f32_fp8_sdwa v[234:235], v162 src0_sel:WORD_1
	v_cvt_pk_f32_fp8_e32 v[236:237], v163
	v_cvt_pk_f32_fp8_sdwa v[238:239], v163 src0_sel:WORD_1
	v_pk_fma_f32 v[64:65], v[224:225], s[16:17], v[64:65] op_sel_hi:[1,0,1]
	v_pk_fma_f32 v[66:67], v[226:227], s[16:17], v[66:67] op_sel_hi:[1,0,1]
	v_pk_fma_f32 v[68:69], v[228:229], s[16:17], v[68:69] op_sel_hi:[1,0,1]
	v_pk_fma_f32 v[70:71], v[230:231], s[16:17], v[70:71] op_sel_hi:[1,0,1]
	v_pk_fma_f32 v[72:73], v[232:233], s[16:17], v[72:73] op_sel_hi:[1,0,1]
	v_pk_fma_f32 v[74:75], v[234:235], s[16:17], v[74:75] op_sel_hi:[1,0,1]
	v_pk_fma_f32 v[76:77], v[236:237], s[16:17], v[76:77] op_sel_hi:[1,0,1]
	v_pk_fma_f32 v[78:79], v[238:239], s[16:17], v[78:79] op_sel_hi:[1,0,1]
	v_cvt_pk_f32_fp8_e32 v[224:225], v164
	v_cvt_pk_f32_fp8_sdwa v[226:227], v164 src0_sel:WORD_1
	v_cvt_pk_f32_fp8_e32 v[228:229], v165
	v_cvt_pk_f32_fp8_sdwa v[230:231], v165 src0_sel:WORD_1
	v_cvt_pk_f32_fp8_e32 v[232:233], v166
	v_cvt_pk_f32_fp8_sdwa v[234:235], v166 src0_sel:WORD_1
	v_cvt_pk_f32_fp8_e32 v[236:237], v167
	v_cvt_pk_f32_fp8_sdwa v[238:239], v167 src0_sel:WORD_1
	v_pk_fma_f32 v[64:65], v[224:225], s[18:19], v[64:65] op_sel_hi:[1,0,1]
	v_pk_fma_f32 v[66:67], v[226:227], s[18:19], v[66:67] op_sel_hi:[1,0,1]
	v_pk_fma_f32 v[68:69], v[228:229], s[18:19], v[68:69] op_sel_hi:[1,0,1]
	v_pk_fma_f32 v[70:71], v[230:231], s[18:19], v[70:71] op_sel_hi:[1,0,1]
	v_pk_fma_f32 v[72:73], v[232:233], s[18:19], v[72:73] op_sel_hi:[1,0,1]
	v_pk_fma_f32 v[74:75], v[234:235], s[18:19], v[74:75] op_sel_hi:[1,0,1]
	v_pk_fma_f32 v[76:77], v[236:237], s[18:19], v[76:77] op_sel_hi:[1,0,1]
	v_pk_fma_f32 v[78:79], v[238:239], s[18:19], v[78:79] op_sel_hi:[1,0,1]
	v_cvt_pk_f32_fp8_e32 v[224:225], v168
	v_cvt_pk_f32_fp8_sdwa v[226:227], v168 src0_sel:WORD_1
	v_cvt_pk_f32_fp8_e32 v[228:229], v169
	v_cvt_pk_f32_fp8_sdwa v[230:231], v169 src0_sel:WORD_1
	v_cvt_pk_f32_fp8_e32 v[232:233], v170
	v_cvt_pk_f32_fp8_sdwa v[234:235], v170 src0_sel:WORD_1
	v_cvt_pk_f32_fp8_e32 v[236:237], v171
	v_cvt_pk_f32_fp8_sdwa v[238:239], v171 src0_sel:WORD_1
	v_pk_fma_f32 v[64:65], v[224:225], s[20:21], v[64:65] op_sel_hi:[1,0,1]
	v_pk_fma_f32 v[66:67], v[226:227], s[20:21], v[66:67] op_sel_hi:[1,0,1]
	v_pk_fma_f32 v[68:69], v[228:229], s[20:21], v[68:69] op_sel_hi:[1,0,1]
	v_pk_fma_f32 v[70:71], v[230:231], s[20:21], v[70:71] op_sel_hi:[1,0,1]
	v_pk_fma_f32 v[72:73], v[232:233], s[20:21], v[72:73] op_sel_hi:[1,0,1]
	v_pk_fma_f32 v[74:75], v[234:235], s[20:21], v[74:75] op_sel_hi:[1,0,1]
	v_pk_fma_f32 v[76:77], v[236:237], s[20:21], v[76:77] op_sel_hi:[1,0,1]
	v_pk_fma_f32 v[78:79], v[238:239], s[20:21], v[78:79] op_sel_hi:[1,0,1]
	v_cvt_pk_f32_fp8_e32 v[224:225], v172
	v_cvt_pk_f32_fp8_sdwa v[226:227], v172 src0_sel:WORD_1
	v_cvt_pk_f32_fp8_e32 v[228:229], v173
	v_cvt_pk_f32_fp8_sdwa v[230:231], v173 src0_sel:WORD_1
	v_cvt_pk_f32_fp8_e32 v[232:233], v174
	v_cvt_pk_f32_fp8_sdwa v[234:235], v174 src0_sel:WORD_1
	v_cvt_pk_f32_fp8_e32 v[236:237], v175
	v_cvt_pk_f32_fp8_sdwa v[238:239], v175 src0_sel:WORD_1
	v_pk_fma_f32 v[64:65], v[224:225], s[22:23], v[64:65] op_sel_hi:[1,0,1]
	v_pk_fma_f32 v[66:67], v[226:227], s[22:23], v[66:67] op_sel_hi:[1,0,1]
	v_pk_fma_f32 v[68:69], v[228:229], s[22:23], v[68:69] op_sel_hi:[1,0,1]
	v_pk_fma_f32 v[70:71], v[230:231], s[22:23], v[70:71] op_sel_hi:[1,0,1]
	v_pk_fma_f32 v[72:73], v[232:233], s[22:23], v[72:73] op_sel_hi:[1,0,1]
	v_pk_fma_f32 v[74:75], v[234:235], s[22:23], v[74:75] op_sel_hi:[1,0,1]
	v_pk_fma_f32 v[76:77], v[236:237], s[22:23], v[76:77] op_sel_hi:[1,0,1]
	v_pk_fma_f32 v[78:79], v[238:239], s[22:23], v[78:79] op_sel_hi:[1,0,1]
	v_cvt_pk_f32_fp8_e32 v[224:225], v176
	v_cvt_pk_f32_fp8_sdwa v[226:227], v176 src0_sel:WORD_1
	v_cvt_pk_f32_fp8_e32 v[228:229], v177
	v_cvt_pk_f32_fp8_sdwa v[230:231], v177 src0_sel:WORD_1
	v_cvt_pk_f32_fp8_e32 v[232:233], v178
	v_cvt_pk_f32_fp8_sdwa v[234:235], v178 src0_sel:WORD_1
	v_cvt_pk_f32_fp8_e32 v[236:237], v179
	v_cvt_pk_f32_fp8_sdwa v[238:239], v179 src0_sel:WORD_1
	v_pk_fma_f32 v[64:65], v[224:225], s[24:25], v[64:65] op_sel_hi:[1,0,1]
	v_pk_fma_f32 v[66:67], v[226:227], s[24:25], v[66:67] op_sel_hi:[1,0,1]
	v_pk_fma_f32 v[68:69], v[228:229], s[24:25], v[68:69] op_sel_hi:[1,0,1]
	v_pk_fma_f32 v[70:71], v[230:231], s[24:25], v[70:71] op_sel_hi:[1,0,1]
	v_pk_fma_f32 v[72:73], v[232:233], s[24:25], v[72:73] op_sel_hi:[1,0,1]
	v_pk_fma_f32 v[74:75], v[234:235], s[24:25], v[74:75] op_sel_hi:[1,0,1]
	v_pk_fma_f32 v[76:77], v[236:237], s[24:25], v[76:77] op_sel_hi:[1,0,1]
	v_pk_fma_f32 v[78:79], v[238:239], s[24:25], v[78:79] op_sel_hi:[1,0,1]
	v_cvt_pk_f32_fp8_e32 v[224:225], v180
	v_cvt_pk_f32_fp8_sdwa v[226:227], v180 src0_sel:WORD_1
	v_cvt_pk_f32_fp8_e32 v[228:229], v181
	v_cvt_pk_f32_fp8_sdwa v[230:231], v181 src0_sel:WORD_1
	v_cvt_pk_f32_fp8_e32 v[232:233], v182
	v_cvt_pk_f32_fp8_sdwa v[234:235], v182 src0_sel:WORD_1
	v_cvt_pk_f32_fp8_e32 v[236:237], v183
	v_cvt_pk_f32_fp8_sdwa v[238:239], v183 src0_sel:WORD_1
	v_pk_fma_f32 v[64:65], v[224:225], s[26:27], v[64:65] op_sel_hi:[1,0,1]
	v_pk_fma_f32 v[66:67], v[226:227], s[26:27], v[66:67] op_sel_hi:[1,0,1]
	v_pk_fma_f32 v[68:69], v[228:229], s[26:27], v[68:69] op_sel_hi:[1,0,1]
	v_pk_fma_f32 v[70:71], v[230:231], s[26:27], v[70:71] op_sel_hi:[1,0,1]
	v_pk_fma_f32 v[72:73], v[232:233], s[26:27], v[72:73] op_sel_hi:[1,0,1]
	v_pk_fma_f32 v[74:75], v[234:235], s[26:27], v[74:75] op_sel_hi:[1,0,1]
	v_pk_fma_f32 v[76:77], v[236:237], s[26:27], v[76:77] op_sel_hi:[1,0,1]
	v_pk_fma_f32 v[78:79], v[238:239], s[26:27], v[78:79] op_sel_hi:[1,0,1]
	v_cvt_pk_f32_fp8_e32 v[224:225], v184
	v_cvt_pk_f32_fp8_sdwa v[226:227], v184 src0_sel:WORD_1
	v_cvt_pk_f32_fp8_e32 v[228:229], v185
	v_cvt_pk_f32_fp8_sdwa v[230:231], v185 src0_sel:WORD_1
	v_cvt_pk_f32_fp8_e32 v[232:233], v186
	v_cvt_pk_f32_fp8_sdwa v[234:235], v186 src0_sel:WORD_1
	v_cvt_pk_f32_fp8_e32 v[236:237], v187
	v_cvt_pk_f32_fp8_sdwa v[238:239], v187 src0_sel:WORD_1
	v_pk_fma_f32 v[64:65], v[224:225], s[28:29], v[64:65] op_sel_hi:[1,0,1]
	v_pk_fma_f32 v[66:67], v[226:227], s[28:29], v[66:67] op_sel_hi:[1,0,1]
	v_pk_fma_f32 v[68:69], v[228:229], s[28:29], v[68:69] op_sel_hi:[1,0,1]
	v_pk_fma_f32 v[70:71], v[230:231], s[28:29], v[70:71] op_sel_hi:[1,0,1]
	v_pk_fma_f32 v[72:73], v[232:233], s[28:29], v[72:73] op_sel_hi:[1,0,1]
	v_pk_fma_f32 v[74:75], v[234:235], s[28:29], v[74:75] op_sel_hi:[1,0,1]
	v_pk_fma_f32 v[76:77], v[236:237], s[28:29], v[76:77] op_sel_hi:[1,0,1]
	v_pk_fma_f32 v[78:79], v[238:239], s[28:29], v[78:79] op_sel_hi:[1,0,1]
	v_cvt_pk_f32_fp8_e32 v[224:225], v188
	v_cvt_pk_f32_fp8_sdwa v[226:227], v188 src0_sel:WORD_1
	v_cvt_pk_f32_fp8_e32 v[228:229], v189
	v_cvt_pk_f32_fp8_sdwa v[230:231], v189 src0_sel:WORD_1
	v_cvt_pk_f32_fp8_e32 v[232:233], v190
	v_cvt_pk_f32_fp8_sdwa v[234:235], v190 src0_sel:WORD_1
	v_cvt_pk_f32_fp8_e32 v[236:237], v191
	v_cvt_pk_f32_fp8_sdwa v[238:239], v191 src0_sel:WORD_1
	v_pk_fma_f32 v[64:65], v[224:225], s[30:31], v[64:65] op_sel_hi:[1,0,1]
	v_pk_fma_f32 v[66:67], v[226:227], s[30:31], v[66:67] op_sel_hi:[1,0,1]
	v_pk_fma_f32 v[68:69], v[228:229], s[30:31], v[68:69] op_sel_hi:[1,0,1]
	v_pk_fma_f32 v[70:71], v[230:231], s[30:31], v[70:71] op_sel_hi:[1,0,1]
	v_pk_fma_f32 v[72:73], v[232:233], s[30:31], v[72:73] op_sel_hi:[1,0,1]
	v_pk_fma_f32 v[74:75], v[234:235], s[30:31], v[74:75] op_sel_hi:[1,0,1]
	v_pk_fma_f32 v[76:77], v[236:237], s[30:31], v[76:77] op_sel_hi:[1,0,1]
	v_pk_fma_f32 v[78:79], v[238:239], s[30:31], v[78:79] op_sel_hi:[1,0,1]
	v_readlane_b32 s16, v151, s72
	v_readlane_b32 s18, v151, s73
	v_readlane_b32 s20, v151, s74
	v_readlane_b32 s22, v151, s75
	v_readlane_b32 s24, v151, s76
	v_readlane_b32 s26, v151, s77
	v_readlane_b32 s28, v151, s78
	v_readlane_b32 s30, v151, s79
	v_readlane_b32 s48, v153, s72
	v_readlane_b32 s49, v153, s73
	v_readlane_b32 s50, v153, s74
	v_readlane_b32 s51, v153, s75
	v_readlane_b32 s52, v153, s76
	v_readlane_b32 s53, v153, s77
	v_readlane_b32 s54, v153, s78
	v_readlane_b32 s55, v153, s79
	s_add_u32 s32, s0, s48
	s_addc_u32 s33, s1, 0
	s_add_u32 s34, s0, s49
	s_addc_u32 s35, s1, 0
	s_add_u32 s36, s0, s50
	s_addc_u32 s37, s1, 0
	s_add_u32 s38, s0, s51
	s_addc_u32 s39, s1, 0
	s_add_u32 s40, s0, s52
	s_addc_u32 s41, s1, 0
	s_add_u32 s42, s0, s53
	s_addc_u32 s43, s1, 0
	s_add_u32 s44, s0, s54
	s_addc_u32 s45, s1, 0
	s_add_u32 s46, s0, s55
	s_addc_u32 s47, s1, 0
	global_load_dwordx4 v[160:163], v240, s[32:33]
	global_load_dwordx4 v[164:167], v240, s[34:35]
	global_load_dwordx4 v[168:171], v240, s[36:37]
	global_load_dwordx4 v[172:175], v240, s[38:39]
	global_load_dwordx4 v[176:179], v240, s[40:41]
	global_load_dwordx4 v[180:183], v240, s[42:43]
	global_load_dwordx4 v[184:187], v240, s[44:45]
	global_load_dwordx4 v[188:191], v240, s[46:47]
	s_waitcnt vmcnt(8)
	v_cvt_pk_f32_fp8_e32 v[224:225], v192
	v_cvt_pk_f32_fp8_sdwa v[226:227], v192 src0_sel:WORD_1
	v_cvt_pk_f32_fp8_e32 v[228:229], v193
	v_cvt_pk_f32_fp8_sdwa v[230:231], v193 src0_sel:WORD_1
	v_cvt_pk_f32_fp8_e32 v[232:233], v194
	v_cvt_pk_f32_fp8_sdwa v[234:235], v194 src0_sel:WORD_1
	v_cvt_pk_f32_fp8_e32 v[236:237], v195
	v_cvt_pk_f32_fp8_sdwa v[238:239], v195 src0_sel:WORD_1
	v_pk_fma_f32 v[80:81], v[224:225], s[16:17], v[80:81] op_sel_hi:[1,0,1]
	v_pk_fma_f32 v[82:83], v[226:227], s[16:17], v[82:83] op_sel_hi:[1,0,1]
	v_pk_fma_f32 v[84:85], v[228:229], s[16:17], v[84:85] op_sel_hi:[1,0,1]
	v_pk_fma_f32 v[86:87], v[230:231], s[16:17], v[86:87] op_sel_hi:[1,0,1]
	v_pk_fma_f32 v[88:89], v[232:233], s[16:17], v[88:89] op_sel_hi:[1,0,1]
	v_pk_fma_f32 v[90:91], v[234:235], s[16:17], v[90:91] op_sel_hi:[1,0,1]
	v_pk_fma_f32 v[92:93], v[236:237], s[16:17], v[92:93] op_sel_hi:[1,0,1]
	v_pk_fma_f32 v[94:95], v[238:239], s[16:17], v[94:95] op_sel_hi:[1,0,1]
	v_cvt_pk_f32_fp8_e32 v[224:225], v196
	v_cvt_pk_f32_fp8_sdwa v[226:227], v196 src0_sel:WORD_1
	v_cvt_pk_f32_fp8_e32 v[228:229], v197
	v_cvt_pk_f32_fp8_sdwa v[230:231], v197 src0_sel:WORD_1
	v_cvt_pk_f32_fp8_e32 v[232:233], v198
	v_cvt_pk_f32_fp8_sdwa v[234:235], v198 src0_sel:WORD_1
	v_cvt_pk_f32_fp8_e32 v[236:237], v199
	v_cvt_pk_f32_fp8_sdwa v[238:239], v199 src0_sel:WORD_1
	v_pk_fma_f32 v[80:81], v[224:225], s[18:19], v[80:81] op_sel_hi:[1,0,1]
	v_pk_fma_f32 v[82:83], v[226:227], s[18:19], v[82:83] op_sel_hi:[1,0,1]
	v_pk_fma_f32 v[84:85], v[228:229], s[18:19], v[84:85] op_sel_hi:[1,0,1]
	v_pk_fma_f32 v[86:87], v[230:231], s[18:19], v[86:87] op_sel_hi:[1,0,1]
	v_pk_fma_f32 v[88:89], v[232:233], s[18:19], v[88:89] op_sel_hi:[1,0,1]
	v_pk_fma_f32 v[90:91], v[234:235], s[18:19], v[90:91] op_sel_hi:[1,0,1]
	v_pk_fma_f32 v[92:93], v[236:237], s[18:19], v[92:93] op_sel_hi:[1,0,1]
	v_pk_fma_f32 v[94:95], v[238:239], s[18:19], v[94:95] op_sel_hi:[1,0,1]
	v_cvt_pk_f32_fp8_e32 v[224:225], v200
	v_cvt_pk_f32_fp8_sdwa v[226:227], v200 src0_sel:WORD_1
	v_cvt_pk_f32_fp8_e32 v[228:229], v201
	v_cvt_pk_f32_fp8_sdwa v[230:231], v201 src0_sel:WORD_1
	v_cvt_pk_f32_fp8_e32 v[232:233], v202
	v_cvt_pk_f32_fp8_sdwa v[234:235], v202 src0_sel:WORD_1
	v_cvt_pk_f32_fp8_e32 v[236:237], v203
	v_cvt_pk_f32_fp8_sdwa v[238:239], v203 src0_sel:WORD_1
	v_pk_fma_f32 v[80:81], v[224:225], s[20:21], v[80:81] op_sel_hi:[1,0,1]
	v_pk_fma_f32 v[82:83], v[226:227], s[20:21], v[82:83] op_sel_hi:[1,0,1]
	v_pk_fma_f32 v[84:85], v[228:229], s[20:21], v[84:85] op_sel_hi:[1,0,1]
	v_pk_fma_f32 v[86:87], v[230:231], s[20:21], v[86:87] op_sel_hi:[1,0,1]
	v_pk_fma_f32 v[88:89], v[232:233], s[20:21], v[88:89] op_sel_hi:[1,0,1]
	v_pk_fma_f32 v[90:91], v[234:235], s[20:21], v[90:91] op_sel_hi:[1,0,1]
	v_pk_fma_f32 v[92:93], v[236:237], s[20:21], v[92:93] op_sel_hi:[1,0,1]
	v_pk_fma_f32 v[94:95], v[238:239], s[20:21], v[94:95] op_sel_hi:[1,0,1]
	v_cvt_pk_f32_fp8_e32 v[224:225], v204
	v_cvt_pk_f32_fp8_sdwa v[226:227], v204 src0_sel:WORD_1
	v_cvt_pk_f32_fp8_e32 v[228:229], v205
	v_cvt_pk_f32_fp8_sdwa v[230:231], v205 src0_sel:WORD_1
	v_cvt_pk_f32_fp8_e32 v[232:233], v206
	v_cvt_pk_f32_fp8_sdwa v[234:235], v206 src0_sel:WORD_1
	v_cvt_pk_f32_fp8_e32 v[236:237], v207
	v_cvt_pk_f32_fp8_sdwa v[238:239], v207 src0_sel:WORD_1
	v_pk_fma_f32 v[80:81], v[224:225], s[22:23], v[80:81] op_sel_hi:[1,0,1]
	v_pk_fma_f32 v[82:83], v[226:227], s[22:23], v[82:83] op_sel_hi:[1,0,1]
	v_pk_fma_f32 v[84:85], v[228:229], s[22:23], v[84:85] op_sel_hi:[1,0,1]
	v_pk_fma_f32 v[86:87], v[230:231], s[22:23], v[86:87] op_sel_hi:[1,0,1]
	v_pk_fma_f32 v[88:89], v[232:233], s[22:23], v[88:89] op_sel_hi:[1,0,1]
	v_pk_fma_f32 v[90:91], v[234:235], s[22:23], v[90:91] op_sel_hi:[1,0,1]
	v_pk_fma_f32 v[92:93], v[236:237], s[22:23], v[92:93] op_sel_hi:[1,0,1]
	v_pk_fma_f32 v[94:95], v[238:239], s[22:23], v[94:95] op_sel_hi:[1,0,1]
	v_cvt_pk_f32_fp8_e32 v[224:225], v208
	v_cvt_pk_f32_fp8_sdwa v[226:227], v208 src0_sel:WORD_1
	v_cvt_pk_f32_fp8_e32 v[228:229], v209
	v_cvt_pk_f32_fp8_sdwa v[230:231], v209 src0_sel:WORD_1
	v_cvt_pk_f32_fp8_e32 v[232:233], v210
	v_cvt_pk_f32_fp8_sdwa v[234:235], v210 src0_sel:WORD_1
	v_cvt_pk_f32_fp8_e32 v[236:237], v211
	v_cvt_pk_f32_fp8_sdwa v[238:239], v211 src0_sel:WORD_1
	v_pk_fma_f32 v[80:81], v[224:225], s[24:25], v[80:81] op_sel_hi:[1,0,1]
	v_pk_fma_f32 v[82:83], v[226:227], s[24:25], v[82:83] op_sel_hi:[1,0,1]
	v_pk_fma_f32 v[84:85], v[228:229], s[24:25], v[84:85] op_sel_hi:[1,0,1]
	v_pk_fma_f32 v[86:87], v[230:231], s[24:25], v[86:87] op_sel_hi:[1,0,1]
	v_pk_fma_f32 v[88:89], v[232:233], s[24:25], v[88:89] op_sel_hi:[1,0,1]
	v_pk_fma_f32 v[90:91], v[234:235], s[24:25], v[90:91] op_sel_hi:[1,0,1]
	v_pk_fma_f32 v[92:93], v[236:237], s[24:25], v[92:93] op_sel_hi:[1,0,1]
	v_pk_fma_f32 v[94:95], v[238:239], s[24:25], v[94:95] op_sel_hi:[1,0,1]
	v_cvt_pk_f32_fp8_e32 v[224:225], v212
	v_cvt_pk_f32_fp8_sdwa v[226:227], v212 src0_sel:WORD_1
	v_cvt_pk_f32_fp8_e32 v[228:229], v213
	v_cvt_pk_f32_fp8_sdwa v[230:231], v213 src0_sel:WORD_1
	v_cvt_pk_f32_fp8_e32 v[232:233], v214
	v_cvt_pk_f32_fp8_sdwa v[234:235], v214 src0_sel:WORD_1
	v_cvt_pk_f32_fp8_e32 v[236:237], v215
	v_cvt_pk_f32_fp8_sdwa v[238:239], v215 src0_sel:WORD_1
	v_pk_fma_f32 v[80:81], v[224:225], s[26:27], v[80:81] op_sel_hi:[1,0,1]
	v_pk_fma_f32 v[82:83], v[226:227], s[26:27], v[82:83] op_sel_hi:[1,0,1]
	v_pk_fma_f32 v[84:85], v[228:229], s[26:27], v[84:85] op_sel_hi:[1,0,1]
	v_pk_fma_f32 v[86:87], v[230:231], s[26:27], v[86:87] op_sel_hi:[1,0,1]
	v_pk_fma_f32 v[88:89], v[232:233], s[26:27], v[88:89] op_sel_hi:[1,0,1]
	v_pk_fma_f32 v[90:91], v[234:235], s[26:27], v[90:91] op_sel_hi:[1,0,1]
	v_pk_fma_f32 v[92:93], v[236:237], s[26:27], v[92:93] op_sel_hi:[1,0,1]
	v_pk_fma_f32 v[94:95], v[238:239], s[26:27], v[94:95] op_sel_hi:[1,0,1]
	v_cvt_pk_f32_fp8_e32 v[224:225], v216
	v_cvt_pk_f32_fp8_sdwa v[226:227], v216 src0_sel:WORD_1
	v_cvt_pk_f32_fp8_e32 v[228:229], v217
	v_cvt_pk_f32_fp8_sdwa v[230:231], v217 src0_sel:WORD_1
	v_cvt_pk_f32_fp8_e32 v[232:233], v218
	v_cvt_pk_f32_fp8_sdwa v[234:235], v218 src0_sel:WORD_1
	v_cvt_pk_f32_fp8_e32 v[236:237], v219
	v_cvt_pk_f32_fp8_sdwa v[238:239], v219 src0_sel:WORD_1
	v_pk_fma_f32 v[80:81], v[224:225], s[28:29], v[80:81] op_sel_hi:[1,0,1]
	v_pk_fma_f32 v[82:83], v[226:227], s[28:29], v[82:83] op_sel_hi:[1,0,1]
	v_pk_fma_f32 v[84:85], v[228:229], s[28:29], v[84:85] op_sel_hi:[1,0,1]
	v_pk_fma_f32 v[86:87], v[230:231], s[28:29], v[86:87] op_sel_hi:[1,0,1]
	v_pk_fma_f32 v[88:89], v[232:233], s[28:29], v[88:89] op_sel_hi:[1,0,1]
	v_pk_fma_f32 v[90:91], v[234:235], s[28:29], v[90:91] op_sel_hi:[1,0,1]
	v_pk_fma_f32 v[92:93], v[236:237], s[28:29], v[92:93] op_sel_hi:[1,0,1]
	v_pk_fma_f32 v[94:95], v[238:239], s[28:29], v[94:95] op_sel_hi:[1,0,1]
	v_cvt_pk_f32_fp8_e32 v[224:225], v220
	v_cvt_pk_f32_fp8_sdwa v[226:227], v220 src0_sel:WORD_1
	v_cvt_pk_f32_fp8_e32 v[228:229], v221
	v_cvt_pk_f32_fp8_sdwa v[230:231], v221 src0_sel:WORD_1
	v_cvt_pk_f32_fp8_e32 v[232:233], v222
	v_cvt_pk_f32_fp8_sdwa v[234:235], v222 src0_sel:WORD_1
	v_cvt_pk_f32_fp8_e32 v[236:237], v223
	v_cvt_pk_f32_fp8_sdwa v[238:239], v223 src0_sel:WORD_1
	v_pk_fma_f32 v[80:81], v[224:225], s[30:31], v[80:81] op_sel_hi:[1,0,1]
	v_pk_fma_f32 v[82:83], v[226:227], s[30:31], v[82:83] op_sel_hi:[1,0,1]
	v_pk_fma_f32 v[84:85], v[228:229], s[30:31], v[84:85] op_sel_hi:[1,0,1]
	v_pk_fma_f32 v[86:87], v[230:231], s[30:31], v[86:87] op_sel_hi:[1,0,1]
	v_pk_fma_f32 v[88:89], v[232:233], s[30:31], v[88:89] op_sel_hi:[1,0,1]
	v_pk_fma_f32 v[90:91], v[234:235], s[30:31], v[90:91] op_sel_hi:[1,0,1]
	v_pk_fma_f32 v[92:93], v[236:237], s[30:31], v[92:93] op_sel_hi:[1,0,1]
	v_pk_fma_f32 v[94:95], v[238:239], s[30:31], v[94:95] op_sel_hi:[1,0,1]
	v_readlane_b32 s16, v155, s72
	v_readlane_b32 s18, v155, s73
	v_readlane_b32 s20, v155, s74
	v_readlane_b32 s22, v155, s75
	v_readlane_b32 s24, v155, s76
	v_readlane_b32 s26, v155, s77
	v_readlane_b32 s28, v155, s78
	v_readlane_b32 s30, v155, s79
	v_readlane_b32 s48, v157, s72
	v_readlane_b32 s49, v157, s73
	v_readlane_b32 s50, v157, s74
	v_readlane_b32 s51, v157, s75
	v_readlane_b32 s52, v157, s76
	v_readlane_b32 s53, v157, s77
	v_readlane_b32 s54, v157, s78
	v_readlane_b32 s55, v157, s79
	s_add_u32 s32, s0, s48
	s_addc_u32 s33, s1, 0
	s_add_u32 s34, s0, s49
	s_addc_u32 s35, s1, 0
	s_add_u32 s36, s0, s50
	s_addc_u32 s37, s1, 0
	s_add_u32 s38, s0, s51
	s_addc_u32 s39, s1, 0
	s_add_u32 s40, s0, s52
	s_addc_u32 s41, s1, 0
	s_add_u32 s42, s0, s53
	s_addc_u32 s43, s1, 0
	s_add_u32 s44, s0, s54
	s_addc_u32 s45, s1, 0
	s_add_u32 s46, s0, s55
	s_addc_u32 s47, s1, 0
	global_load_dwordx4 v[192:195], v240, s[32:33]
	global_load_dwordx4 v[196:199], v240, s[34:35]
	global_load_dwordx4 v[200:203], v240, s[36:37]
	global_load_dwordx4 v[204:207], v240, s[38:39]
	global_load_dwordx4 v[208:211], v240, s[40:41]
	global_load_dwordx4 v[212:215], v240, s[42:43]
	global_load_dwordx4 v[216:219], v240, s[44:45]
	global_load_dwordx4 v[220:223], v240, s[46:47]
	s_waitcnt vmcnt(8)
	v_cvt_pk_f32_fp8_e32 v[224:225], v160
	v_cvt_pk_f32_fp8_sdwa v[226:227], v160 src0_sel:WORD_1
	v_cvt_pk_f32_fp8_e32 v[228:229], v161
	v_cvt_pk_f32_fp8_sdwa v[230:231], v161 src0_sel:WORD_1
	v_cvt_pk_f32_fp8_e32 v[232:233], v162
	v_cvt_pk_f32_fp8_sdwa v[234:235], v162 src0_sel:WORD_1
	v_cvt_pk_f32_fp8_e32 v[236:237], v163
	v_cvt_pk_f32_fp8_sdwa v[238:239], v163 src0_sel:WORD_1
	v_pk_fma_f32 v[96:97], v[224:225], s[16:17], v[96:97] op_sel_hi:[1,0,1]
	v_pk_fma_f32 v[98:99], v[226:227], s[16:17], v[98:99] op_sel_hi:[1,0,1]
	v_pk_fma_f32 v[100:101], v[228:229], s[16:17], v[100:101] op_sel_hi:[1,0,1]
	v_pk_fma_f32 v[102:103], v[230:231], s[16:17], v[102:103] op_sel_hi:[1,0,1]
	v_pk_fma_f32 v[104:105], v[232:233], s[16:17], v[104:105] op_sel_hi:[1,0,1]
	v_pk_fma_f32 v[106:107], v[234:235], s[16:17], v[106:107] op_sel_hi:[1,0,1]
	v_pk_fma_f32 v[108:109], v[236:237], s[16:17], v[108:109] op_sel_hi:[1,0,1]
	v_pk_fma_f32 v[110:111], v[238:239], s[16:17], v[110:111] op_sel_hi:[1,0,1]
	v_cvt_pk_f32_fp8_e32 v[224:225], v164
	v_cvt_pk_f32_fp8_sdwa v[226:227], v164 src0_sel:WORD_1
	v_cvt_pk_f32_fp8_e32 v[228:229], v165
	v_cvt_pk_f32_fp8_sdwa v[230:231], v165 src0_sel:WORD_1
	v_cvt_pk_f32_fp8_e32 v[232:233], v166
	v_cvt_pk_f32_fp8_sdwa v[234:235], v166 src0_sel:WORD_1
	v_cvt_pk_f32_fp8_e32 v[236:237], v167
	v_cvt_pk_f32_fp8_sdwa v[238:239], v167 src0_sel:WORD_1
	v_pk_fma_f32 v[96:97], v[224:225], s[18:19], v[96:97] op_sel_hi:[1,0,1]
	v_pk_fma_f32 v[98:99], v[226:227], s[18:19], v[98:99] op_sel_hi:[1,0,1]
	v_pk_fma_f32 v[100:101], v[228:229], s[18:19], v[100:101] op_sel_hi:[1,0,1]
	v_pk_fma_f32 v[102:103], v[230:231], s[18:19], v[102:103] op_sel_hi:[1,0,1]
	v_pk_fma_f32 v[104:105], v[232:233], s[18:19], v[104:105] op_sel_hi:[1,0,1]
	v_pk_fma_f32 v[106:107], v[234:235], s[18:19], v[106:107] op_sel_hi:[1,0,1]
	v_pk_fma_f32 v[108:109], v[236:237], s[18:19], v[108:109] op_sel_hi:[1,0,1]
	v_pk_fma_f32 v[110:111], v[238:239], s[18:19], v[110:111] op_sel_hi:[1,0,1]
	v_cvt_pk_f32_fp8_e32 v[224:225], v168
	v_cvt_pk_f32_fp8_sdwa v[226:227], v168 src0_sel:WORD_1
	v_cvt_pk_f32_fp8_e32 v[228:229], v169
	v_cvt_pk_f32_fp8_sdwa v[230:231], v169 src0_sel:WORD_1
	v_cvt_pk_f32_fp8_e32 v[232:233], v170
	v_cvt_pk_f32_fp8_sdwa v[234:235], v170 src0_sel:WORD_1
	v_cvt_pk_f32_fp8_e32 v[236:237], v171
	v_cvt_pk_f32_fp8_sdwa v[238:239], v171 src0_sel:WORD_1
	v_pk_fma_f32 v[96:97], v[224:225], s[20:21], v[96:97] op_sel_hi:[1,0,1]
	v_pk_fma_f32 v[98:99], v[226:227], s[20:21], v[98:99] op_sel_hi:[1,0,1]
	v_pk_fma_f32 v[100:101], v[228:229], s[20:21], v[100:101] op_sel_hi:[1,0,1]
	v_pk_fma_f32 v[102:103], v[230:231], s[20:21], v[102:103] op_sel_hi:[1,0,1]
	v_pk_fma_f32 v[104:105], v[232:233], s[20:21], v[104:105] op_sel_hi:[1,0,1]
	v_pk_fma_f32 v[106:107], v[234:235], s[20:21], v[106:107] op_sel_hi:[1,0,1]
	v_pk_fma_f32 v[108:109], v[236:237], s[20:21], v[108:109] op_sel_hi:[1,0,1]
	v_pk_fma_f32 v[110:111], v[238:239], s[20:21], v[110:111] op_sel_hi:[1,0,1]
	v_cvt_pk_f32_fp8_e32 v[224:225], v172
	v_cvt_pk_f32_fp8_sdwa v[226:227], v172 src0_sel:WORD_1
	v_cvt_pk_f32_fp8_e32 v[228:229], v173
	v_cvt_pk_f32_fp8_sdwa v[230:231], v173 src0_sel:WORD_1
	v_cvt_pk_f32_fp8_e32 v[232:233], v174
	v_cvt_pk_f32_fp8_sdwa v[234:235], v174 src0_sel:WORD_1
	v_cvt_pk_f32_fp8_e32 v[236:237], v175
	v_cvt_pk_f32_fp8_sdwa v[238:239], v175 src0_sel:WORD_1
	v_pk_fma_f32 v[96:97], v[224:225], s[22:23], v[96:97] op_sel_hi:[1,0,1]
	v_pk_fma_f32 v[98:99], v[226:227], s[22:23], v[98:99] op_sel_hi:[1,0,1]
	v_pk_fma_f32 v[100:101], v[228:229], s[22:23], v[100:101] op_sel_hi:[1,0,1]
	v_pk_fma_f32 v[102:103], v[230:231], s[22:23], v[102:103] op_sel_hi:[1,0,1]
	v_pk_fma_f32 v[104:105], v[232:233], s[22:23], v[104:105] op_sel_hi:[1,0,1]
	v_pk_fma_f32 v[106:107], v[234:235], s[22:23], v[106:107] op_sel_hi:[1,0,1]
	v_pk_fma_f32 v[108:109], v[236:237], s[22:23], v[108:109] op_sel_hi:[1,0,1]
	v_pk_fma_f32 v[110:111], v[238:239], s[22:23], v[110:111] op_sel_hi:[1,0,1]
	v_cvt_pk_f32_fp8_e32 v[224:225], v176
	v_cvt_pk_f32_fp8_sdwa v[226:227], v176 src0_sel:WORD_1
	v_cvt_pk_f32_fp8_e32 v[228:229], v177
	v_cvt_pk_f32_fp8_sdwa v[230:231], v177 src0_sel:WORD_1
	v_cvt_pk_f32_fp8_e32 v[232:233], v178
	v_cvt_pk_f32_fp8_sdwa v[234:235], v178 src0_sel:WORD_1
	v_cvt_pk_f32_fp8_e32 v[236:237], v179
	v_cvt_pk_f32_fp8_sdwa v[238:239], v179 src0_sel:WORD_1
	v_pk_fma_f32 v[96:97], v[224:225], s[24:25], v[96:97] op_sel_hi:[1,0,1]
	v_pk_fma_f32 v[98:99], v[226:227], s[24:25], v[98:99] op_sel_hi:[1,0,1]
	v_pk_fma_f32 v[100:101], v[228:229], s[24:25], v[100:101] op_sel_hi:[1,0,1]
	v_pk_fma_f32 v[102:103], v[230:231], s[24:25], v[102:103] op_sel_hi:[1,0,1]
	v_pk_fma_f32 v[104:105], v[232:233], s[24:25], v[104:105] op_sel_hi:[1,0,1]
	v_pk_fma_f32 v[106:107], v[234:235], s[24:25], v[106:107] op_sel_hi:[1,0,1]
	v_pk_fma_f32 v[108:109], v[236:237], s[24:25], v[108:109] op_sel_hi:[1,0,1]
	v_pk_fma_f32 v[110:111], v[238:239], s[24:25], v[110:111] op_sel_hi:[1,0,1]
	v_cvt_pk_f32_fp8_e32 v[224:225], v180
	v_cvt_pk_f32_fp8_sdwa v[226:227], v180 src0_sel:WORD_1
	v_cvt_pk_f32_fp8_e32 v[228:229], v181
	v_cvt_pk_f32_fp8_sdwa v[230:231], v181 src0_sel:WORD_1
	v_cvt_pk_f32_fp8_e32 v[232:233], v182
	v_cvt_pk_f32_fp8_sdwa v[234:235], v182 src0_sel:WORD_1
	v_cvt_pk_f32_fp8_e32 v[236:237], v183
	v_cvt_pk_f32_fp8_sdwa v[238:239], v183 src0_sel:WORD_1
	v_pk_fma_f32 v[96:97], v[224:225], s[26:27], v[96:97] op_sel_hi:[1,0,1]
	v_pk_fma_f32 v[98:99], v[226:227], s[26:27], v[98:99] op_sel_hi:[1,0,1]
	v_pk_fma_f32 v[100:101], v[228:229], s[26:27], v[100:101] op_sel_hi:[1,0,1]
	v_pk_fma_f32 v[102:103], v[230:231], s[26:27], v[102:103] op_sel_hi:[1,0,1]
	v_pk_fma_f32 v[104:105], v[232:233], s[26:27], v[104:105] op_sel_hi:[1,0,1]
	v_pk_fma_f32 v[106:107], v[234:235], s[26:27], v[106:107] op_sel_hi:[1,0,1]
	v_pk_fma_f32 v[108:109], v[236:237], s[26:27], v[108:109] op_sel_hi:[1,0,1]
	v_pk_fma_f32 v[110:111], v[238:239], s[26:27], v[110:111] op_sel_hi:[1,0,1]
	v_cvt_pk_f32_fp8_e32 v[224:225], v184
	v_cvt_pk_f32_fp8_sdwa v[226:227], v184 src0_sel:WORD_1
	v_cvt_pk_f32_fp8_e32 v[228:229], v185
	v_cvt_pk_f32_fp8_sdwa v[230:231], v185 src0_sel:WORD_1
	v_cvt_pk_f32_fp8_e32 v[232:233], v186
	v_cvt_pk_f32_fp8_sdwa v[234:235], v186 src0_sel:WORD_1
	v_cvt_pk_f32_fp8_e32 v[236:237], v187
	v_cvt_pk_f32_fp8_sdwa v[238:239], v187 src0_sel:WORD_1
	v_pk_fma_f32 v[96:97], v[224:225], s[28:29], v[96:97] op_sel_hi:[1,0,1]
	v_pk_fma_f32 v[98:99], v[226:227], s[28:29], v[98:99] op_sel_hi:[1,0,1]
	v_pk_fma_f32 v[100:101], v[228:229], s[28:29], v[100:101] op_sel_hi:[1,0,1]
	v_pk_fma_f32 v[102:103], v[230:231], s[28:29], v[102:103] op_sel_hi:[1,0,1]
	v_pk_fma_f32 v[104:105], v[232:233], s[28:29], v[104:105] op_sel_hi:[1,0,1]
	v_pk_fma_f32 v[106:107], v[234:235], s[28:29], v[106:107] op_sel_hi:[1,0,1]
	v_pk_fma_f32 v[108:109], v[236:237], s[28:29], v[108:109] op_sel_hi:[1,0,1]
	v_pk_fma_f32 v[110:111], v[238:239], s[28:29], v[110:111] op_sel_hi:[1,0,1]
	v_cvt_pk_f32_fp8_e32 v[224:225], v188
	v_cvt_pk_f32_fp8_sdwa v[226:227], v188 src0_sel:WORD_1
	v_cvt_pk_f32_fp8_e32 v[228:229], v189
	v_cvt_pk_f32_fp8_sdwa v[230:231], v189 src0_sel:WORD_1
	v_cvt_pk_f32_fp8_e32 v[232:233], v190
	v_cvt_pk_f32_fp8_sdwa v[234:235], v190 src0_sel:WORD_1
	v_cvt_pk_f32_fp8_e32 v[236:237], v191
	v_cvt_pk_f32_fp8_sdwa v[238:239], v191 src0_sel:WORD_1
	v_pk_fma_f32 v[96:97], v[224:225], s[30:31], v[96:97] op_sel_hi:[1,0,1]
	v_pk_fma_f32 v[98:99], v[226:227], s[30:31], v[98:99] op_sel_hi:[1,0,1]
	v_pk_fma_f32 v[100:101], v[228:229], s[30:31], v[100:101] op_sel_hi:[1,0,1]
	v_pk_fma_f32 v[102:103], v[230:231], s[30:31], v[102:103] op_sel_hi:[1,0,1]
	v_pk_fma_f32 v[104:105], v[232:233], s[30:31], v[104:105] op_sel_hi:[1,0,1]
	v_pk_fma_f32 v[106:107], v[234:235], s[30:31], v[106:107] op_sel_hi:[1,0,1]
	v_pk_fma_f32 v[108:109], v[236:237], s[30:31], v[108:109] op_sel_hi:[1,0,1]
	v_pk_fma_f32 v[110:111], v[238:239], s[30:31], v[110:111] op_sel_hi:[1,0,1]
	v_readlane_b32 s16, v159, s72
	v_readlane_b32 s18, v159, s73
	v_readlane_b32 s20, v159, s74
	v_readlane_b32 s22, v159, s75
	v_readlane_b32 s24, v159, s76
	v_readlane_b32 s26, v159, s77
	v_readlane_b32 s28, v159, s78
	v_readlane_b32 s30, v159, s79
	s_add_u32 s72, s72, 8
	s_add_u32 s73, s73, 8
	s_add_u32 s74, s74, 8
	s_add_u32 s75, s75, 8
	s_add_u32 s76, s76, 8
	s_add_u32 s77, s77, 8
	s_add_u32 s78, s78, 8
	s_add_u32 s79, s79, 8
	s_and_b32 s72, s72, 63
	s_and_b32 s73, s73, 63
	s_and_b32 s74, s74, 63
	s_and_b32 s75, s75, 63
	s_and_b32 s76, s76, 63
	s_and_b32 s77, s77, 63
	s_and_b32 s78, s78, 63
	s_and_b32 s79, s79, 63
	v_readlane_b32 s48, v144, s72
	v_readlane_b32 s49, v144, s73
	v_readlane_b32 s50, v144, s74
	v_readlane_b32 s51, v144, s75
	v_readlane_b32 s52, v144, s76
	v_readlane_b32 s53, v144, s77
	v_readlane_b32 s54, v144, s78
	v_readlane_b32 s55, v144, s79
	s_add_u32 s32, s0, s48
	s_addc_u32 s33, s1, 0
	s_add_u32 s34, s0, s49
	s_addc_u32 s35, s1, 0
	s_add_u32 s36, s0, s50
	s_addc_u32 s37, s1, 0
	s_add_u32 s38, s0, s51
	s_addc_u32 s39, s1, 0
	s_add_u32 s40, s0, s52
	s_addc_u32 s41, s1, 0
	s_add_u32 s42, s0, s53
	s_addc_u32 s43, s1, 0
	s_add_u32 s44, s0, s54
	s_addc_u32 s45, s1, 0
	s_add_u32 s46, s0, s55
	s_addc_u32 s47, s1, 0
	global_load_dwordx4 v[160:163], v240, s[32:33]
	global_load_dwordx4 v[164:167], v240, s[34:35]
	global_load_dwordx4 v[168:171], v240, s[36:37]
	global_load_dwordx4 v[172:175], v240, s[38:39]
	global_load_dwordx4 v[176:179], v240, s[40:41]
	global_load_dwordx4 v[180:183], v240, s[42:43]
	global_load_dwordx4 v[184:187], v240, s[44:45]
	global_load_dwordx4 v[188:191], v240, s[46:47]
	s_waitcnt vmcnt(8)
	v_cvt_pk_f32_fp8_e32 v[224:225], v192
	v_cvt_pk_f32_fp8_sdwa v[226:227], v192 src0_sel:WORD_1
	v_cvt_pk_f32_fp8_e32 v[228:229], v193
	v_cvt_pk_f32_fp8_sdwa v[230:231], v193 src0_sel:WORD_1
	v_cvt_pk_f32_fp8_e32 v[232:233], v194
	v_cvt_pk_f32_fp8_sdwa v[234:235], v194 src0_sel:WORD_1
	v_cvt_pk_f32_fp8_e32 v[236:237], v195
	v_cvt_pk_f32_fp8_sdwa v[238:239], v195 src0_sel:WORD_1
	v_pk_fma_f32 v[112:113], v[224:225], s[16:17], v[112:113] op_sel_hi:[1,0,1]
	v_pk_fma_f32 v[114:115], v[226:227], s[16:17], v[114:115] op_sel_hi:[1,0,1]
	v_pk_fma_f32 v[116:117], v[228:229], s[16:17], v[116:117] op_sel_hi:[1,0,1]
	v_pk_fma_f32 v[118:119], v[230:231], s[16:17], v[118:119] op_sel_hi:[1,0,1]
	v_pk_fma_f32 v[120:121], v[232:233], s[16:17], v[120:121] op_sel_hi:[1,0,1]
	v_pk_fma_f32 v[122:123], v[234:235], s[16:17], v[122:123] op_sel_hi:[1,0,1]
	v_pk_fma_f32 v[124:125], v[236:237], s[16:17], v[124:125] op_sel_hi:[1,0,1]
	v_pk_fma_f32 v[126:127], v[238:239], s[16:17], v[126:127] op_sel_hi:[1,0,1]
	v_cvt_pk_f32_fp8_e32 v[224:225], v196
	v_cvt_pk_f32_fp8_sdwa v[226:227], v196 src0_sel:WORD_1
	v_cvt_pk_f32_fp8_e32 v[228:229], v197
	v_cvt_pk_f32_fp8_sdwa v[230:231], v197 src0_sel:WORD_1
	v_cvt_pk_f32_fp8_e32 v[232:233], v198
	v_cvt_pk_f32_fp8_sdwa v[234:235], v198 src0_sel:WORD_1
	v_cvt_pk_f32_fp8_e32 v[236:237], v199
	v_cvt_pk_f32_fp8_sdwa v[238:239], v199 src0_sel:WORD_1
	v_pk_fma_f32 v[112:113], v[224:225], s[18:19], v[112:113] op_sel_hi:[1,0,1]
	v_pk_fma_f32 v[114:115], v[226:227], s[18:19], v[114:115] op_sel_hi:[1,0,1]
	v_pk_fma_f32 v[116:117], v[228:229], s[18:19], v[116:117] op_sel_hi:[1,0,1]
	v_pk_fma_f32 v[118:119], v[230:231], s[18:19], v[118:119] op_sel_hi:[1,0,1]
	v_pk_fma_f32 v[120:121], v[232:233], s[18:19], v[120:121] op_sel_hi:[1,0,1]
	v_pk_fma_f32 v[122:123], v[234:235], s[18:19], v[122:123] op_sel_hi:[1,0,1]
	v_pk_fma_f32 v[124:125], v[236:237], s[18:19], v[124:125] op_sel_hi:[1,0,1]
	v_pk_fma_f32 v[126:127], v[238:239], s[18:19], v[126:127] op_sel_hi:[1,0,1]
	v_cvt_pk_f32_fp8_e32 v[224:225], v200
	v_cvt_pk_f32_fp8_sdwa v[226:227], v200 src0_sel:WORD_1
	v_cvt_pk_f32_fp8_e32 v[228:229], v201
	v_cvt_pk_f32_fp8_sdwa v[230:231], v201 src0_sel:WORD_1
	v_cvt_pk_f32_fp8_e32 v[232:233], v202
	v_cvt_pk_f32_fp8_sdwa v[234:235], v202 src0_sel:WORD_1
	v_cvt_pk_f32_fp8_e32 v[236:237], v203
	v_cvt_pk_f32_fp8_sdwa v[238:239], v203 src0_sel:WORD_1
	v_pk_fma_f32 v[112:113], v[224:225], s[20:21], v[112:113] op_sel_hi:[1,0,1]
	v_pk_fma_f32 v[114:115], v[226:227], s[20:21], v[114:115] op_sel_hi:[1,0,1]
	v_pk_fma_f32 v[116:117], v[228:229], s[20:21], v[116:117] op_sel_hi:[1,0,1]
	v_pk_fma_f32 v[118:119], v[230:231], s[20:21], v[118:119] op_sel_hi:[1,0,1]
	v_pk_fma_f32 v[120:121], v[232:233], s[20:21], v[120:121] op_sel_hi:[1,0,1]
	v_pk_fma_f32 v[122:123], v[234:235], s[20:21], v[122:123] op_sel_hi:[1,0,1]
	v_pk_fma_f32 v[124:125], v[236:237], s[20:21], v[124:125] op_sel_hi:[1,0,1]
	v_pk_fma_f32 v[126:127], v[238:239], s[20:21], v[126:127] op_sel_hi:[1,0,1]
	v_cvt_pk_f32_fp8_e32 v[224:225], v204
	v_cvt_pk_f32_fp8_sdwa v[226:227], v204 src0_sel:WORD_1
	v_cvt_pk_f32_fp8_e32 v[228:229], v205
	v_cvt_pk_f32_fp8_sdwa v[230:231], v205 src0_sel:WORD_1
	v_cvt_pk_f32_fp8_e32 v[232:233], v206
	v_cvt_pk_f32_fp8_sdwa v[234:235], v206 src0_sel:WORD_1
	v_cvt_pk_f32_fp8_e32 v[236:237], v207
	v_cvt_pk_f32_fp8_sdwa v[238:239], v207 src0_sel:WORD_1
	v_pk_fma_f32 v[112:113], v[224:225], s[22:23], v[112:113] op_sel_hi:[1,0,1]
	v_pk_fma_f32 v[114:115], v[226:227], s[22:23], v[114:115] op_sel_hi:[1,0,1]
	v_pk_fma_f32 v[116:117], v[228:229], s[22:23], v[116:117] op_sel_hi:[1,0,1]
	v_pk_fma_f32 v[118:119], v[230:231], s[22:23], v[118:119] op_sel_hi:[1,0,1]
	v_pk_fma_f32 v[120:121], v[232:233], s[22:23], v[120:121] op_sel_hi:[1,0,1]
	v_pk_fma_f32 v[122:123], v[234:235], s[22:23], v[122:123] op_sel_hi:[1,0,1]
	v_pk_fma_f32 v[124:125], v[236:237], s[22:23], v[124:125] op_sel_hi:[1,0,1]
	v_pk_fma_f32 v[126:127], v[238:239], s[22:23], v[126:127] op_sel_hi:[1,0,1]
	v_cvt_pk_f32_fp8_e32 v[224:225], v208
; DI void peer_item_v(const Params& p, int item) {
;     ...
;     V_ISSUE(vqa, 0)
; #pragma unroll 1
;     for (int g = 0; g < 16; g += 2) {
;       V_ISSUE(vqb, g + 1)
;       V_CONSUME(vqa, g)
;       if (g + 2 < 16) V_ISSUE(vqa, g + 2)
;       V_CONSUME(vqb, g + 1)
;     }
;     ...
;     float* orow = p.out + tok * 1024 + lane * 4;
;     float4 y[4];
;     float ss = 0.f;
; #pragma unroll
;     for (int i = 0; i < 4; ++i) {
;       y[i] = *(const float4*)(orow + 256 * i);
;       y[i].x += out[4 * i]; y[i].y += out[4 * i + 1]; y[i].z += out[4 * i + 2]; y[i].w += out[4 * i + 3];
;       ss += y[i].x * y[i].x + y[i].y * y[i].y + y[i].z * y[i].z + y[i].w * y[i].w;
;     }
;     ss = wave_sum(ss);
	v_cvt_pk_f32_fp8_sdwa v[226:227], v208 src0_sel:WORD_1
	v_cvt_pk_f32_fp8_e32 v[228:229], v209
	v_cvt_pk_f32_fp8_sdwa v[230:231], v209 src0_sel:WORD_1
	v_cvt_pk_f32_fp8_e32 v[232:233], v210
	v_cvt_pk_f32_fp8_sdwa v[234:235], v210 src0_sel:WORD_1
	v_cvt_pk_f32_fp8_e32 v[236:237], v211
	v_cvt_pk_f32_fp8_sdwa v[238:239], v211 src0_sel:WORD_1
	v_pk_fma_f32 v[112:113], v[224:225], s[24:25], v[112:113] op_sel_hi:[1,0,1]
	v_pk_fma_f32 v[114:115], v[226:227], s[24:25], v[114:115] op_sel_hi:[1,0,1]
	v_pk_fma_f32 v[116:117], v[228:229], s[24:25], v[116:117] op_sel_hi:[1,0,1]
	v_pk_fma_f32 v[118:119], v[230:231], s[24:25], v[118:119] op_sel_hi:[1,0,1]
	v_pk_fma_f32 v[120:121], v[232:233], s[24:25], v[120:121] op_sel_hi:[1,0,1]
	v_pk_fma_f32 v[122:123], v[234:235], s[24:25], v[122:123] op_sel_hi:[1,0,1]
	v_pk_fma_f32 v[124:125], v[236:237], s[24:25], v[124:125] op_sel_hi:[1,0,1]
	v_pk_fma_f32 v[126:127], v[238:239], s[24:25], v[126:127] op_sel_hi:[1,0,1]
	v_cvt_pk_f32_fp8_e32 v[224:225], v212
	v_cvt_pk_f32_fp8_sdwa v[226:227], v212 src0_sel:WORD_1
	v_cvt_pk_f32_fp8_e32 v[228:229], v213
	v_cvt_pk_f32_fp8_sdwa v[230:231], v213 src0_sel:WORD_1
	v_cvt_pk_f32_fp8_e32 v[232:233], v214
	v_cvt_pk_f32_fp8_sdwa v[234:235], v214 src0_sel:WORD_1
	v_cvt_pk_f32_fp8_e32 v[236:237], v215
	v_cvt_pk_f32_fp8_sdwa v[238:239], v215 src0_sel:WORD_1
	v_pk_fma_f32 v[112:113], v[224:225], s[26:27], v[112:113] op_sel_hi:[1,0,1]
	v_pk_fma_f32 v[114:115], v[226:227], s[26:27], v[114:115] op_sel_hi:[1,0,1]
	v_pk_fma_f32 v[116:117], v[228:229], s[26:27], v[116:117] op_sel_hi:[1,0,1]
	v_pk_fma_f32 v[118:119], v[230:231], s[26:27], v[118:119] op_sel_hi:[1,0,1]
	v_pk_fma_f32 v[120:121], v[232:233], s[26:27], v[120:121] op_sel_hi:[1,0,1]
	v_pk_fma_f32 v[122:123], v[234:235], s[26:27], v[122:123] op_sel_hi:[1,0,1]
	v_pk_fma_f32 v[124:125], v[236:237], s[26:27], v[124:125] op_sel_hi:[1,0,1]
	v_pk_fma_f32 v[126:127], v[238:239], s[26:27], v[126:127] op_sel_hi:[1,0,1]
	v_cvt_pk_f32_fp8_e32 v[224:225], v216
	v_cvt_pk_f32_fp8_sdwa v[226:227], v216 src0_sel:WORD_1
	v_cvt_pk_f32_fp8_e32 v[228:229], v217
	v_cvt_pk_f32_fp8_sdwa v[230:231], v217 src0_sel:WORD_1
	v_cvt_pk_f32_fp8_e32 v[232:233], v218
	v_cvt_pk_f32_fp8_sdwa v[234:235], v218 src0_sel:WORD_1
	v_cvt_pk_f32_fp8_e32 v[236:237], v219
	v_cvt_pk_f32_fp8_sdwa v[238:239], v219 src0_sel:WORD_1
	v_pk_fma_f32 v[112:113], v[224:225], s[28:29], v[112:113] op_sel_hi:[1,0,1]
	v_pk_fma_f32 v[114:115], v[226:227], s[28:29], v[114:115] op_sel_hi:[1,0,1]
	v_pk_fma_f32 v[116:117], v[228:229], s[28:29], v[116:117] op_sel_hi:[1,0,1]
	v_pk_fma_f32 v[118:119], v[230:231], s[28:29], v[118:119] op_sel_hi:[1,0,1]
	v_pk_fma_f32 v[120:121], v[232:233], s[28:29], v[120:121] op_sel_hi:[1,0,1]
	v_pk_fma_f32 v[122:123], v[234:235], s[28:29], v[122:123] op_sel_hi:[1,0,1]
	v_pk_fma_f32 v[124:125], v[236:237], s[28:29], v[124:125] op_sel_hi:[1,0,1]
	v_pk_fma_f32 v[126:127], v[238:239], s[28:29], v[126:127] op_sel_hi:[1,0,1]
	v_cvt_pk_f32_fp8_e32 v[224:225], v220
	v_cvt_pk_f32_fp8_sdwa v[226:227], v220 src0_sel:WORD_1
	v_cvt_pk_f32_fp8_e32 v[228:229], v221
	v_cvt_pk_f32_fp8_sdwa v[230:231], v221 src0_sel:WORD_1
	v_cvt_pk_f32_fp8_e32 v[232:233], v222
	v_cvt_pk_f32_fp8_sdwa v[234:235], v222 src0_sel:WORD_1
	v_cvt_pk_f32_fp8_e32 v[236:237], v223
	v_cvt_pk_f32_fp8_sdwa v[238:239], v223 src0_sel:WORD_1
	v_pk_fma_f32 v[112:113], v[224:225], s[30:31], v[112:113] op_sel_hi:[1,0,1]
	v_pk_fma_f32 v[114:115], v[226:227], s[30:31], v[114:115] op_sel_hi:[1,0,1]
	v_pk_fma_f32 v[116:117], v[228:229], s[30:31], v[116:117] op_sel_hi:[1,0,1]
	v_pk_fma_f32 v[118:119], v[230:231], s[30:31], v[118:119] op_sel_hi:[1,0,1]
	v_pk_fma_f32 v[120:121], v[232:233], s[30:31], v[120:121] op_sel_hi:[1,0,1]
	v_pk_fma_f32 v[122:123], v[234:235], s[30:31], v[122:123] op_sel_hi:[1,0,1]
	v_pk_fma_f32 v[124:125], v[236:237], s[30:31], v[124:125] op_sel_hi:[1,0,1]
	v_pk_fma_f32 v[126:127], v[238:239], s[30:31], v[126:127] op_sel_hi:[1,0,1]
	s_add_u32 s12, s12, 1
	s_cmp_lt_u32 s12, 8
	s_cbranch_scc1 .Lvq_kB
	s_waitcnt vmcnt(0)
	s_add_u32 s32, s62, 16384
	s_addc_u32 s33, s63, 0
	s_add_u32 s34, s62, 20480
	s_addc_u32 s35, s63, 0
	s_add_u32 s36, s62, 24576
	s_addc_u32 s37, s63, 0
	s_add_u32 s38, s62, 28672
	s_addc_u32 s39, s63, 0
	v_pk_add_f32 v[0:1], v[0:1], v[64:65]
	v_pk_add_f32 v[2:3], v[2:3], v[66:67]
	v_pk_add_f32 v[4:5], v[4:5], v[68:69]
	v_pk_add_f32 v[6:7], v[6:7], v[70:71]
	v_pk_add_f32 v[8:9], v[8:9], v[72:73]
	v_pk_add_f32 v[10:11], v[10:11], v[74:75]
	v_pk_add_f32 v[12:13], v[12:13], v[76:77]
	v_pk_add_f32 v[14:15], v[14:15], v[78:79]
	v_pk_mul_f32 v[224:225], v[0:1], v[0:1]
	v_pk_mul_f32 v[226:227], v[2:3], v[2:3]
	v_pk_fma_f32 v[224:225], v[4:5], v[4:5], v[224:225]
	v_pk_fma_f32 v[226:227], v[6:7], v[6:7], v[226:227]
	v_pk_fma_f32 v[224:225], v[8:9], v[8:9], v[224:225]
	v_pk_fma_f32 v[226:227], v[10:11], v[10:11], v[226:227]
	v_pk_fma_f32 v[224:225], v[12:13], v[12:13], v[224:225]
	v_pk_fma_f32 v[226:227], v[14:15], v[14:15], v[226:227]
	v_pk_add_f32 v[224:225], v[224:225], v[226:227]
	s_nop 0
	v_add_f32_e32 v224, v224, v225
	ds_bpermute_b32 v225, v242, v224
	s_waitcnt lgkmcnt(0)
	v_add_f32_e32 v224, v224, v225
	ds_bpermute_b32 v225, v243, v224
	s_waitcnt lgkmcnt(0)
	v_add_f32_e32 v224, v224, v225
	ds_bpermute_b32 v225, v244, v224
	s_waitcnt lgkmcnt(0)
	v_add_f32_e32 v224, v224, v225
	ds_bpermute_b32 v225, v245, v224
	s_waitcnt lgkmcnt(0)
	v_add_f32_e32 v224, v224, v225
	ds_bpermute_b32 v225, v246, v224
	s_waitcnt lgkmcnt(0)
	v_add_f32_e32 v224, v224, v225
	ds_bpermute_b32 v225, v247, v224
	s_waitcnt lgkmcnt(0)
; DI void peer_item_v(const Params& p, int item) {
;     ...
;     ss = wave_sum(ss);
;     const float r = rsqrtf(ss * (1.f / 1024.f) + 1e-6f);
; #pragma unroll
;     for (int i = 0; i < 4; ++i) {
;       float4 g = *(const float4*)(p.g_final + 256 * i + lane * 4);
;       y[i].x *= r * g.x; y[i].y *= r * g.y; y[i].z *= r * g.z; y[i].w *= r * g.w;
;       *(float4*)(orow + 256 * i) = y[i];
	v_add_f32_e32 v224, v224, v225
	v_fmamk_f32 v224, v224, 0x3a800000, v248
	v_rsq_f32_e32 v224, v224
	s_nop 1
	v_pk_mul_f32 v[226:227], v[128:129], v[224:225] op_sel_hi:[1,0]
	v_pk_mul_f32 v[0:1], v[0:1], v[226:227]
	v_pk_mul_f32 v[228:229], v[130:131], v[224:225] op_sel_hi:[1,0]
	v_pk_mul_f32 v[2:3], v[2:3], v[228:229]
	v_pk_mul_f32 v[230:231], v[132:133], v[224:225] op_sel_hi:[1,0]
	v_pk_mul_f32 v[4:5], v[4:5], v[230:231]
	v_pk_mul_f32 v[232:233], v[134:135], v[224:225] op_sel_hi:[1,0]
	v_pk_mul_f32 v[6:7], v[6:7], v[232:233]
	v_pk_mul_f32 v[226:227], v[136:137], v[224:225] op_sel_hi:[1,0]
	v_pk_mul_f32 v[8:9], v[8:9], v[226:227]
	v_pk_mul_f32 v[228:229], v[138:139], v[224:225] op_sel_hi:[1,0]
	v_pk_mul_f32 v[10:11], v[10:11], v[228:229]
	v_pk_mul_f32 v[230:231], v[140:141], v[224:225] op_sel_hi:[1,0]
	v_pk_mul_f32 v[12:13], v[12:13], v[230:231]
	v_pk_mul_f32 v[232:233], v[142:143], v[224:225] op_sel_hi:[1,0]
	v_pk_mul_f32 v[14:15], v[14:15], v[232:233]
	v_pk_add_f32 v[16:17], v[16:17], v[80:81]
	v_pk_add_f32 v[18:19], v[18:19], v[82:83]
	v_pk_add_f32 v[20:21], v[20:21], v[84:85]
	v_pk_add_f32 v[22:23], v[22:23], v[86:87]
	v_pk_add_f32 v[24:25], v[24:25], v[88:89]
	v_pk_add_f32 v[26:27], v[26:27], v[90:91]
	v_pk_add_f32 v[28:29], v[28:29], v[92:93]
	v_pk_add_f32 v[30:31], v[30:31], v[94:95]
	v_pk_mul_f32 v[224:225], v[16:17], v[16:17]
	v_pk_mul_f32 v[226:227], v[18:19], v[18:19]
	v_pk_fma_f32 v[224:225], v[20:21], v[20:21], v[224:225]
	v_pk_fma_f32 v[226:227], v[22:23], v[22:23], v[226:227]
	v_pk_fma_f32 v[224:225], v[24:25], v[24:25], v[224:225]
	v_pk_fma_f32 v[226:227], v[26:27], v[26:27], v[226:227]
	v_pk_fma_f32 v[224:225], v[28:29], v[28:29], v[224:225]
	v_pk_fma_f32 v[226:227], v[30:31], v[30:31], v[226:227]
	v_pk_add_f32 v[224:225], v[224:225], v[226:227]
	s_nop 0
	v_add_f32_e32 v224, v224, v225
	ds_bpermute_b32 v225, v242, v224
	s_waitcnt lgkmcnt(0)
	v_add_f32_e32 v224, v224, v225
	ds_bpermute_b32 v225, v243, v224
	s_waitcnt lgkmcnt(0)
	v_add_f32_e32 v224, v224, v225
	ds_bpermute_b32 v225, v244, v224
	s_waitcnt lgkmcnt(0)
	v_add_f32_e32 v224, v224, v225
	ds_bpermute_b32 v225, v245, v224
	s_waitcnt lgkmcnt(0)
	v_add_f32_e32 v224, v224, v225
	ds_bpermute_b32 v225, v246, v224
	s_waitcnt lgkmcnt(0)
	v_add_f32_e32 v224, v224, v225
	ds_bpermute_b32 v225, v247, v224
	s_waitcnt lgkmcnt(0)
	v_add_f32_e32 v224, v224, v225
	v_fmamk_f32 v224, v224, 0x3a800000, v248
	v_rsq_f32_e32 v224, v224
	s_nop 1
	v_pk_mul_f32 v[226:227], v[128:129], v[224:225] op_sel_hi:[1,0]
	v_pk_mul_f32 v[16:17], v[16:17], v[226:227]
	v_pk_mul_f32 v[228:229], v[130:131], v[224:225] op_sel_hi:[1,0]
	v_pk_mul_f32 v[18:19], v[18:19], v[228:229]
	v_pk_mul_f32 v[230:231], v[132:133], v[224:225] op_sel_hi:[1,0]
	v_pk_mul_f32 v[20:21], v[20:21], v[230:231]
	v_pk_mul_f32 v[232:233], v[134:135], v[224:225] op_sel_hi:[1,0]
	v_pk_mul_f32 v[22:23], v[22:23], v[232:233]
	v_pk_mul_f32 v[226:227], v[136:137], v[224:225] op_sel_hi:[1,0]
	v_pk_mul_f32 v[24:25], v[24:25], v[226:227]
	v_pk_mul_f32 v[228:229], v[138:139], v[224:225] op_sel_hi:[1,0]
	v_pk_mul_f32 v[26:27], v[26:27], v[228:229]
	v_pk_mul_f32 v[230:231], v[140:141], v[224:225] op_sel_hi:[1,0]
	v_pk_mul_f32 v[28:29], v[28:29], v[230:231]
	v_pk_mul_f32 v[232:233], v[142:143], v[224:225] op_sel_hi:[1,0]
	v_pk_mul_f32 v[30:31], v[30:31], v[232:233]
	v_pk_add_f32 v[32:33], v[32:33], v[96:97]
	v_pk_add_f32 v[34:35], v[34:35], v[98:99]
	v_pk_add_f32 v[36:37], v[36:37], v[100:101]
	v_pk_add_f32 v[38:39], v[38:39], v[102:103]
	v_pk_add_f32 v[40:41], v[40:41], v[104:105]
	v_pk_add_f32 v[42:43], v[42:43], v[106:107]
	v_pk_add_f32 v[44:45], v[44:45], v[108:109]
	v_pk_add_f32 v[46:47], v[46:47], v[110:111]
	v_pk_mul_f32 v[224:225], v[32:33], v[32:33]
	v_pk_mul_f32 v[226:227], v[34:35], v[34:35]
	v_pk_fma_f32 v[224:225], v[36:37], v[36:37], v[224:225]
	v_pk_fma_f32 v[226:227], v[38:39], v[38:39], v[226:227]
	v_pk_fma_f32 v[224:225], v[40:41], v[40:41], v[224:225]
	v_pk_fma_f32 v[226:227], v[42:43], v[42:43], v[226:227]
	v_pk_fma_f32 v[224:225], v[44:45], v[44:45], v[224:225]
	v_pk_fma_f32 v[226:227], v[46:47], v[46:47], v[226:227]
	v_pk_add_f32 v[224:225], v[224:225], v[226:227]
	s_nop 0
	v_add_f32_e32 v224, v224, v225
	ds_bpermute_b32 v225, v242, v224
	s_waitcnt lgkmcnt(0)
	v_add_f32_e32 v224, v224, v225
	ds_bpermute_b32 v225, v243, v224
	s_waitcnt lgkmcnt(0)
	v_add_f32_e32 v224, v224, v225
	ds_bpermute_b32 v225, v244, v224
	s_waitcnt lgkmcnt(0)
	v_add_f32_e32 v224, v224, v225
	ds_bpermute_b32 v225, v245, v224
	s_waitcnt lgkmcnt(0)
; DI int vb_id() { return (int)blockIdx.x + half_id() * (int)gridDim.x; }
; DI int vb_n() { return (int)gridDim.x * 2; }
; DI void peer_item_v(const Params& p, int item) {
;     ...
;     ss = wave_sum(ss);
;     const float r = rsqrtf(ss * (1.f / 1024.f) + 1e-6f);
; #pragma unroll
;     for (int i = 0; i < 4; ++i) {
;       float4 g = *(const float4*)(p.g_final + 256 * i + lane * 4);
;       y[i].x *= r * g.x; y[i].y *= r * g.y; y[i].z *= r * g.z; y[i].w *= r * g.w;
;       *(float4*)(orow + 256 * i) = y[i];
;     }
; DI void phase_peer_v(const Params& p) {
;   for (int it = vb_id(); it < 512; it += vb_n()) peer_item_v(p, it);
	v_add_f32_e32 v224, v224, v225
	ds_bpermute_b32 v225, v246, v224
	s_waitcnt lgkmcnt(0)
	v_add_f32_e32 v224, v224, v225
	ds_bpermute_b32 v225, v247, v224
	s_waitcnt lgkmcnt(0)
	v_add_f32_e32 v224, v224, v225
	v_fmamk_f32 v224, v224, 0x3a800000, v248
	v_rsq_f32_e32 v224, v224
	s_nop 1
	v_pk_mul_f32 v[226:227], v[128:129], v[224:225] op_sel_hi:[1,0]
	v_pk_mul_f32 v[32:33], v[32:33], v[226:227]
	v_pk_mul_f32 v[228:229], v[130:131], v[224:225] op_sel_hi:[1,0]
	v_pk_mul_f32 v[34:35], v[34:35], v[228:229]
	v_pk_mul_f32 v[230:231], v[132:133], v[224:225] op_sel_hi:[1,0]
	v_pk_mul_f32 v[36:37], v[36:37], v[230:231]
	v_pk_mul_f32 v[232:233], v[134:135], v[224:225] op_sel_hi:[1,0]
	v_pk_mul_f32 v[38:39], v[38:39], v[232:233]
	v_pk_mul_f32 v[226:227], v[136:137], v[224:225] op_sel_hi:[1,0]
	v_pk_mul_f32 v[40:41], v[40:41], v[226:227]
	v_pk_mul_f32 v[228:229], v[138:139], v[224:225] op_sel_hi:[1,0]
	v_pk_mul_f32 v[42:43], v[42:43], v[228:229]
	v_pk_mul_f32 v[230:231], v[140:141], v[224:225] op_sel_hi:[1,0]
	v_pk_mul_f32 v[44:45], v[44:45], v[230:231]
	v_pk_mul_f32 v[232:233], v[142:143], v[224:225] op_sel_hi:[1,0]
	v_pk_mul_f32 v[46:47], v[46:47], v[232:233]
	v_pk_add_f32 v[48:49], v[48:49], v[112:113]
	v_pk_add_f32 v[50:51], v[50:51], v[114:115]
	v_pk_add_f32 v[52:53], v[52:53], v[116:117]
	v_pk_add_f32 v[54:55], v[54:55], v[118:119]
	v_pk_add_f32 v[56:57], v[56:57], v[120:121]
	v_pk_add_f32 v[58:59], v[58:59], v[122:123]
	v_pk_add_f32 v[60:61], v[60:61], v[124:125]
	v_pk_add_f32 v[62:63], v[62:63], v[126:127]
	v_pk_mul_f32 v[224:225], v[48:49], v[48:49]
	v_pk_mul_f32 v[226:227], v[50:51], v[50:51]
	v_pk_fma_f32 v[224:225], v[52:53], v[52:53], v[224:225]
	v_pk_fma_f32 v[226:227], v[54:55], v[54:55], v[226:227]
	v_pk_fma_f32 v[224:225], v[56:57], v[56:57], v[224:225]
	v_pk_fma_f32 v[226:227], v[58:59], v[58:59], v[226:227]
	v_pk_fma_f32 v[224:225], v[60:61], v[60:61], v[224:225]
	v_pk_fma_f32 v[226:227], v[62:63], v[62:63], v[226:227]
	v_pk_add_f32 v[224:225], v[224:225], v[226:227]
	s_nop 0
	v_add_f32_e32 v224, v224, v225
	ds_bpermute_b32 v225, v242, v224
	s_waitcnt lgkmcnt(0)
	v_add_f32_e32 v224, v224, v225
	ds_bpermute_b32 v225, v243, v224
	s_waitcnt lgkmcnt(0)
	v_add_f32_e32 v224, v224, v225
	ds_bpermute_b32 v225, v244, v224
	s_waitcnt lgkmcnt(0)
	v_add_f32_e32 v224, v224, v225
	ds_bpermute_b32 v225, v245, v224
	s_waitcnt lgkmcnt(0)
	v_add_f32_e32 v224, v224, v225
	ds_bpermute_b32 v225, v246, v224
	s_waitcnt lgkmcnt(0)
	v_add_f32_e32 v224, v224, v225
	ds_bpermute_b32 v225, v247, v224
	s_waitcnt lgkmcnt(0)
	v_add_f32_e32 v224, v224, v225
	v_fmamk_f32 v224, v224, 0x3a800000, v248
	v_rsq_f32_e32 v224, v224
	s_nop 1
	v_pk_mul_f32 v[226:227], v[128:129], v[224:225] op_sel_hi:[1,0]
	v_pk_mul_f32 v[48:49], v[48:49], v[226:227]
	v_pk_mul_f32 v[228:229], v[130:131], v[224:225] op_sel_hi:[1,0]
	v_pk_mul_f32 v[50:51], v[50:51], v[228:229]
	v_pk_mul_f32 v[230:231], v[132:133], v[224:225] op_sel_hi:[1,0]
	v_pk_mul_f32 v[52:53], v[52:53], v[230:231]
	v_pk_mul_f32 v[232:233], v[134:135], v[224:225] op_sel_hi:[1,0]
	v_pk_mul_f32 v[54:55], v[54:55], v[232:233]
	v_pk_mul_f32 v[226:227], v[136:137], v[224:225] op_sel_hi:[1,0]
	v_pk_mul_f32 v[56:57], v[56:57], v[226:227]
	v_pk_mul_f32 v[228:229], v[138:139], v[224:225] op_sel_hi:[1,0]
	v_pk_mul_f32 v[58:59], v[58:59], v[228:229]
	v_pk_mul_f32 v[230:231], v[140:141], v[224:225] op_sel_hi:[1,0]
	v_pk_mul_f32 v[60:61], v[60:61], v[230:231]
	v_pk_mul_f32 v[232:233], v[142:143], v[224:225] op_sel_hi:[1,0]
	v_pk_mul_f32 v[62:63], v[62:63], v[232:233]
	global_store_dwordx4 v240, v[0:3], s[32:33] nt
	global_store_dwordx4 v240, v[4:7], s[32:33] offset:1024 nt
	global_store_dwordx4 v240, v[8:11], s[32:33] offset:2048 nt
	global_store_dwordx4 v240, v[12:15], s[32:33] offset:3072 nt
	global_store_dwordx4 v240, v[16:19], s[34:35] nt
	global_store_dwordx4 v240, v[20:23], s[34:35] offset:1024 nt
	global_store_dwordx4 v240, v[24:27], s[34:35] offset:2048 nt
	global_store_dwordx4 v240, v[28:31], s[34:35] offset:3072 nt
	global_store_dwordx4 v240, v[32:35], s[36:37] nt
	global_store_dwordx4 v240, v[36:39], s[36:37] offset:1024 nt
	global_store_dwordx4 v240, v[40:43], s[36:37] offset:2048 nt
	global_store_dwordx4 v240, v[44:47], s[36:37] offset:3072 nt
	global_store_dwordx4 v240, v[48:51], s[38:39] nt
	global_store_dwordx4 v240, v[52:55], s[38:39] offset:1024 nt
	global_store_dwordx4 v240, v[56:59], s[38:39] offset:2048 nt
	global_store_dwordx4 v240, v[60:63], s[38:39] offset:3072 nt
	s_nop 1
	s_add_i32 s10, s10, s11
	s_cmpk_lt_i32 s10, 0x200
	s_cbranch_scc1 .Lvq_item
